# plus: out-GEMM and in_odd epilogue loads hoisted/pipelined, attention K/V prefetch wait moved to loop bottom, bg adaLN row loads issued together
# speedup vs baseline: 1.0272x; 1.0272x over previous
.LBB0_123:
	s_add_u32 s2, s20, 0xfffc0080
	s_addc_u32 s3, s21, -1
	s_add_i32 s53, 0, 0x10000
	v_add_u32_e32 v36, s53, v164
	ds_read_b128 v[24:27], v36
	ds_read_b128 v[28:31], v36 offset:1024
	ds_read_b128 v[32:35], v36 offset:2048
	ds_read_b128 v[36:39], v36 offset:3072
	s_cmp_eq_u32 s52, 12
	s_cselect_b32 s23, s7, s3
	s_cselect_b32 s22, s9, s2
	s_cselect_b32 s3, s13, s51
	s_cselect_b32 s2, s15, s50
	v_lshl_add_u64 v[166:167], s[20:21], 0, v[150:151]
	s_add_i32 m0, s37, 0xc000
	ds_read_b128 v[154:157], v165
	ds_read_b128 v[158:161], v165 offset:1024
	ds_read_b128 v[180:183], v165 offset:2048
	ds_read_b128 v[184:187], v165 offset:3072
	ds_read_b128 v[188:191], v165 offset:4096
	ds_read_b128 v[192:195], v165 offset:5120
	ds_read_b128 v[196:199], v165 offset:6144
	ds_read_b128 v[200:203], v165 offset:7168
	global_load_lds_dwordx4 v[166:167], off
	v_lshl_add_u64 v[166:167], s[20:21], 0, v[152:153]
	s_add_i32 m0, s37, 0xe000
	s_nop 0
	global_load_lds_dwordx4 v[166:167], off
	s_waitcnt lgkmcnt(8)
	s_barrier
	s_waitcnt lgkmcnt(0)
	s_setprio 1
	s_waitcnt lgkmcnt(0)
	v_mfma_f32_16x16x32_bf16 v[140:143], v[24:27], v[154:157], v[140:143]
	v_mfma_f32_16x16x32_bf16 v[136:139], v[32:35], v[154:157], v[136:139]
	v_mfma_f32_16x16x32_bf16 v[124:127], v[24:27], v[180:183], v[124:127]
	v_mfma_f32_16x16x32_bf16 v[120:123], v[32:35], v[180:183], v[120:123]
	v_mfma_f32_16x16x32_bf16 v[108:111], v[24:27], v[188:191], v[108:111]
	v_mfma_f32_16x16x32_bf16 v[104:107], v[32:35], v[188:191], v[104:107]
	v_mfma_f32_16x16x32_bf16 v[92:95], v[24:27], v[196:199], v[92:95]
	v_mfma_f32_16x16x32_bf16 v[88:91], v[32:35], v[196:199], v[88:91]
	v_mfma_f32_16x16x32_bf16 v[140:143], v[28:31], v[158:161], v[140:143]
	v_mfma_f32_16x16x32_bf16 v[136:139], v[36:39], v[158:161], v[136:139]
	v_mfma_f32_16x16x32_bf16 v[124:127], v[28:31], v[184:187], v[124:127]
	v_mfma_f32_16x16x32_bf16 v[120:123], v[36:39], v[184:187], v[120:123]
	v_mfma_f32_16x16x32_bf16 v[108:111], v[28:31], v[192:195], v[108:111]
	v_mfma_f32_16x16x32_bf16 v[104:107], v[36:39], v[192:195], v[104:107]
	v_mfma_f32_16x16x32_bf16 v[92:95], v[28:31], v[200:203], v[92:95]
	v_mfma_f32_16x16x32_bf16 v[88:91], v[36:39], v[200:203], v[88:91]
	s_setprio 0
	s_barrier
	s_add_i32 s56, 0, 0x14000
	v_add_u32_e32 v166, s56, v164
	s_add_i32 s53, s53, s36
	ds_read_b128 v[204:207], v166
	ds_read_b128 v[208:211], v166 offset:1024
	ds_read_b128 v[212:215], v166 offset:2048
	ds_read_b128 v[216:219], v166 offset:3072
	v_lshl_add_u64 v[166:167], s[2:3], 0, v[168:169]
	s_mov_b32 m0, s53
	v_lshl_add_u64 v[220:221], s[2:3], 0, v[148:149]
	global_load_lds_dwordx4 v[166:167], off
	s_add_i32 m0, s53, 0x2000
	s_nop 0
	global_load_lds_dwordx4 v[220:221], off
	s_barrier
	s_waitcnt lgkmcnt(0)
	s_setprio 1
	s_waitcnt lgkmcnt(0)
	v_mfma_f32_16x16x32_bf16 v[132:135], v[204:207], v[154:157], v[132:135]
	v_mfma_f32_16x16x32_bf16 v[128:131], v[212:215], v[154:157], v[128:131]
	v_mfma_f32_16x16x32_bf16 v[116:119], v[204:207], v[180:183], v[116:119]
	v_mfma_f32_16x16x32_bf16 v[112:115], v[212:215], v[180:183], v[112:115]
	v_mfma_f32_16x16x32_bf16 v[100:103], v[204:207], v[188:191], v[100:103]
	v_mfma_f32_16x16x32_bf16 v[96:99], v[212:215], v[188:191], v[96:99]
	v_mfma_f32_16x16x32_bf16 v[84:87], v[204:207], v[196:199], v[84:87]
	v_mfma_f32_16x16x32_bf16 v[80:83], v[212:215], v[196:199], v[80:83]
	v_mfma_f32_16x16x32_bf16 v[132:135], v[208:211], v[158:161], v[132:135]
	v_mfma_f32_16x16x32_bf16 v[128:131], v[216:219], v[158:161], v[128:131]
	v_mfma_f32_16x16x32_bf16 v[116:119], v[208:211], v[184:187], v[116:119]
	v_mfma_f32_16x16x32_bf16 v[112:115], v[216:219], v[184:187], v[112:115]
	v_mfma_f32_16x16x32_bf16 v[100:103], v[208:211], v[192:195], v[100:103]
	v_mfma_f32_16x16x32_bf16 v[96:99], v[216:219], v[192:195], v[96:99]
	v_mfma_f32_16x16x32_bf16 v[84:87], v[208:211], v[200:203], v[84:87]
	v_mfma_f32_16x16x32_bf16 v[80:83], v[216:219], v[200:203], v[80:83]
	s_setprio 0
	s_mov_b32 m0, s37
	v_lshl_add_u64 v[222:223], s[22:23], 0, v[144:145]
	s_barrier
	ds_read_b128 v[154:157], v165 offset:16384
	ds_read_b128 v[158:161], v165 offset:17408
	ds_read_b128 v[180:183], v165 offset:18432
	ds_read_b128 v[184:187], v165 offset:19456
	ds_read_b128 v[188:191], v165 offset:20480
	ds_read_b128 v[192:195], v165 offset:21504
	ds_read_b128 v[196:199], v165 offset:22528
	ds_read_b128 v[200:203], v165 offset:23552
	global_load_lds_dwordx4 v[222:223], off
	v_lshl_add_u64 v[236:237], s[22:23], 0, v[146:147]
	s_mov_b32 m0, s38
	s_nop 0
	global_load_lds_dwordx4 v[236:237], off
	s_barrier
	s_waitcnt lgkmcnt(0)
	s_setprio 1
	s_waitcnt lgkmcnt(0)
	v_mfma_f32_16x16x32_bf16 v[76:79], v[24:27], v[154:157], v[76:79]
	v_mfma_f32_16x16x32_bf16 v[72:75], v[32:35], v[154:157], v[72:75]
	v_mfma_f32_16x16x32_bf16 v[60:63], v[24:27], v[180:183], v[60:63]
	v_mfma_f32_16x16x32_bf16 v[56:59], v[32:35], v[180:183], v[56:59]
	v_mfma_f32_16x16x32_bf16 v[44:47], v[24:27], v[188:191], v[44:47]
	v_mfma_f32_16x16x32_bf16 v[40:43], v[32:35], v[188:191], v[40:43]
	v_mfma_f32_16x16x32_bf16 v[12:15], v[24:27], v[196:199], v[12:15]
	v_mfma_f32_16x16x32_bf16 v[8:11], v[32:35], v[196:199], v[8:11]
	v_mfma_f32_16x16x32_bf16 v[76:79], v[28:31], v[158:161], v[76:79]
	v_mfma_f32_16x16x32_bf16 v[72:75], v[36:39], v[158:161], v[72:75]
	v_mfma_f32_16x16x32_bf16 v[60:63], v[28:31], v[184:187], v[60:63]
	v_mfma_f32_16x16x32_bf16 v[56:59], v[36:39], v[184:187], v[56:59]
	v_mfma_f32_16x16x32_bf16 v[44:47], v[28:31], v[192:195], v[44:47]
	v_mfma_f32_16x16x32_bf16 v[40:43], v[36:39], v[192:195], v[40:43]
	v_mfma_f32_16x16x32_bf16 v[12:15], v[28:31], v[200:203], v[12:15]
	v_mfma_f32_16x16x32_bf16 v[8:11], v[36:39], v[200:203], v[8:11]
	s_setprio 0
	s_barrier
	s_add_u32 s54, s2, 0x40000
	s_addc_u32 s55, s3, 0
	s_add_i32 s53, s56, s36
	v_lshl_add_u64 v[24:25], s[54:55], 0, v[168:169]
	s_mov_b32 m0, s53
	s_nop 0
	global_load_lds_dwordx4 v[24:25], off
	v_lshl_add_u64 v[24:25], s[54:55], 0, v[148:149]
	s_add_i32 m0, s53, 0x2000
	s_nop 0
	global_load_lds_dwordx4 v[24:25], off
	s_waitcnt vmcnt(6)
	s_barrier
	s_setprio 1
	v_mfma_f32_16x16x32_bf16 v[20:23], v[204:207], v[188:191], v[20:23]
	v_mfma_f32_16x16x32_bf16 v[16:19], v[212:215], v[188:191], v[16:19]
	v_mfma_f32_16x16x32_bf16 v[4:7], v[204:207], v[196:199], v[4:7]
	v_mfma_f32_16x16x32_bf16 v[0:3], v[212:215], v[196:199], v[0:3]
	v_mfma_f32_16x16x32_bf16 v[24:27], v[204:207], v[154:157], v[68:71]
	v_mfma_f32_16x16x32_bf16 v[28:31], v[212:215], v[154:157], v[64:67]
	v_mfma_f32_16x16x32_bf16 v[32:35], v[204:207], v[180:183], v[52:55]
	v_mfma_f32_16x16x32_bf16 v[36:39], v[212:215], v[180:183], v[48:51]
	v_mfma_f32_16x16x32_bf16 v[20:23], v[208:211], v[192:195], v[20:23]
	v_mfma_f32_16x16x32_bf16 v[16:19], v[216:219], v[192:195], v[16:19]
	v_mfma_f32_16x16x32_bf16 v[4:7], v[208:211], v[200:203], v[4:7]
	v_mfma_f32_16x16x32_bf16 v[0:3], v[216:219], v[200:203], v[0:3]
	v_mfma_f32_16x16x32_bf16 v[24:27], v[208:211], v[158:161], v[24:27]
	v_mfma_f32_16x16x32_bf16 v[28:31], v[216:219], v[158:161], v[28:31]
	v_mfma_f32_16x16x32_bf16 v[32:35], v[208:211], v[184:187], v[32:35]
	v_mfma_f32_16x16x32_bf16 v[36:39], v[216:219], v[184:187], v[36:39]
	s_setprio 0
	s_add_i32 s53, 0, 0x18000
	v_add_u32_e32 v68, s53, v164
	s_barrier
	ds_read_b128 v[48:51], v68
	ds_read_b128 v[52:55], v68 offset:1024
	ds_read_b128 v[64:67], v68 offset:2048
	ds_read_b128 v[68:71], v68 offset:3072
	s_add_u32 s22, s22, 0x40000
	s_addc_u32 s23, s23, 0
	s_mov_b32 m0, s39
	v_lshl_add_u64 v[204:205], s[22:23], 0, v[144:145]
	ds_read_b128 v[154:157], v165 offset:32768
	ds_read_b128 v[158:161], v165 offset:33792
	ds_read_b128 v[180:183], v165 offset:34816
	ds_read_b128 v[184:187], v165 offset:35840
	ds_read_b128 v[188:191], v165 offset:36864
	ds_read_b128 v[192:195], v165 offset:37888
	ds_read_b128 v[196:199], v165 offset:38912
	ds_read_b128 v[200:203], v165 offset:39936
	global_load_lds_dwordx4 v[204:205], off
	v_lshl_add_u64 v[204:205], s[22:23], 0, v[146:147]
	s_mov_b32 m0, s40
	s_nop 0
	global_load_lds_dwordx4 v[204:205], off
	s_waitcnt lgkmcnt(8)
	s_barrier
	s_waitcnt lgkmcnt(0)
	s_setprio 1
	s_waitcnt lgkmcnt(0)
	v_mfma_f32_16x16x32_bf16 v[140:143], v[48:51], v[154:157], v[140:143]
	v_mfma_f32_16x16x32_bf16 v[136:139], v[64:67], v[154:157], v[136:139]
	v_mfma_f32_16x16x32_bf16 v[124:127], v[48:51], v[180:183], v[124:127]
	v_mfma_f32_16x16x32_bf16 v[120:123], v[64:67], v[180:183], v[120:123]
	v_mfma_f32_16x16x32_bf16 v[108:111], v[48:51], v[188:191], v[108:111]
	v_mfma_f32_16x16x32_bf16 v[104:107], v[64:67], v[188:191], v[104:107]
	v_mfma_f32_16x16x32_bf16 v[92:95], v[48:51], v[196:199], v[92:95]
	v_mfma_f32_16x16x32_bf16 v[88:91], v[64:67], v[196:199], v[88:91]
	v_mfma_f32_16x16x32_bf16 v[140:143], v[52:55], v[158:161], v[140:143]
	v_mfma_f32_16x16x32_bf16 v[136:139], v[68:71], v[158:161], v[136:139]
	v_mfma_f32_16x16x32_bf16 v[124:127], v[52:55], v[184:187], v[124:127]
	v_mfma_f32_16x16x32_bf16 v[120:123], v[68:71], v[184:187], v[120:123]
	v_mfma_f32_16x16x32_bf16 v[108:111], v[52:55], v[192:195], v[108:111]
	v_mfma_f32_16x16x32_bf16 v[104:107], v[68:71], v[192:195], v[104:107]
	v_mfma_f32_16x16x32_bf16 v[92:95], v[52:55], v[200:203], v[92:95]
	v_mfma_f32_16x16x32_bf16 v[88:91], v[68:71], v[200:203], v[88:91]
	s_setprio 0
	s_barrier
	s_add_i32 s22, 0, 0x1c000
	s_add_i32 s23, s53, s36
	v_add_u32_e32 v216, s22, v164
	v_lshl_add_u64 v[166:167], v[166:167], 0, s[78:79]
	s_mov_b32 m0, s23
	ds_read_b128 v[204:207], v216
	ds_read_b128 v[208:211], v216 offset:1024
	ds_read_b128 v[212:215], v216 offset:2048
	ds_read_b128 v[216:219], v216 offset:3072
	global_load_lds_dwordx4 v[166:167], off
	v_lshl_add_u64 v[166:167], v[220:221], 0, s[78:79]
	s_add_i32 m0, s23, 0x2000
	s_nop 0
	global_load_lds_dwordx4 v[166:167], off
	s_barrier
	s_waitcnt lgkmcnt(0)
	s_setprio 1
	s_waitcnt lgkmcnt(0)
	v_mfma_f32_16x16x32_bf16 v[132:135], v[204:207], v[154:157], v[132:135]
	v_mfma_f32_16x16x32_bf16 v[128:131], v[212:215], v[154:157], v[128:131]
	v_mfma_f32_16x16x32_bf16 v[116:119], v[204:207], v[180:183], v[116:119]
	v_mfma_f32_16x16x32_bf16 v[112:115], v[212:215], v[180:183], v[112:115]
	v_mfma_f32_16x16x32_bf16 v[100:103], v[204:207], v[188:191], v[100:103]
	v_mfma_f32_16x16x32_bf16 v[96:99], v[212:215], v[188:191], v[96:99]
	v_mfma_f32_16x16x32_bf16 v[84:87], v[204:207], v[196:199], v[84:87]
	v_mfma_f32_16x16x32_bf16 v[80:83], v[212:215], v[196:199], v[80:83]
	v_mfma_f32_16x16x32_bf16 v[132:135], v[208:211], v[158:161], v[132:135]
	v_mfma_f32_16x16x32_bf16 v[128:131], v[216:219], v[158:161], v[128:131]
	v_mfma_f32_16x16x32_bf16 v[116:119], v[208:211], v[184:187], v[116:119]
	v_mfma_f32_16x16x32_bf16 v[112:115], v[216:219], v[184:187], v[112:115]
	v_mfma_f32_16x16x32_bf16 v[100:103], v[208:211], v[192:195], v[100:103]
	v_mfma_f32_16x16x32_bf16 v[96:99], v[216:219], v[192:195], v[96:99]
	v_mfma_f32_16x16x32_bf16 v[84:87], v[208:211], v[200:203], v[84:87]
	v_mfma_f32_16x16x32_bf16 v[80:83], v[216:219], v[200:203], v[80:83]
	s_setprio 0
	s_mov_b32 m0, s45
	v_lshl_add_u64 v[166:167], v[222:223], 0, s[78:79]
	s_barrier
	ds_read_b128 v[154:157], v165 offset:49152
	ds_read_b128 v[158:161], v165 offset:50176
	ds_read_b128 v[180:183], v165 offset:51200
	ds_read_b128 v[184:187], v165 offset:52224
	ds_read_b128 v[188:191], v165 offset:53248
	ds_read_b128 v[192:195], v165 offset:54272
	ds_read_b128 v[196:199], v165 offset:55296
	ds_read_b128 v[200:203], v165 offset:56320
	global_load_lds_dwordx4 v[166:167], off
	v_lshl_add_u64 v[166:167], v[236:237], 0, s[78:79]
	s_mov_b32 m0, s46
	s_nop 0
	global_load_lds_dwordx4 v[166:167], off
	s_barrier
	s_waitcnt lgkmcnt(0)
	s_setprio 1
	s_waitcnt lgkmcnt(0)
	v_mfma_f32_16x16x32_bf16 v[76:79], v[48:51], v[154:157], v[76:79]
	v_mfma_f32_16x16x32_bf16 v[72:75], v[64:67], v[154:157], v[72:75]
	v_mfma_f32_16x16x32_bf16 v[60:63], v[48:51], v[180:183], v[60:63]
	v_mfma_f32_16x16x32_bf16 v[56:59], v[64:67], v[180:183], v[56:59]
	v_mfma_f32_16x16x32_bf16 v[44:47], v[48:51], v[188:191], v[44:47]
	v_mfma_f32_16x16x32_bf16 v[40:43], v[64:67], v[188:191], v[40:43]
	v_mfma_f32_16x16x32_bf16 v[12:15], v[48:51], v[196:199], v[12:15]
	v_mfma_f32_16x16x32_bf16 v[8:11], v[64:67], v[196:199], v[8:11]
	v_mfma_f32_16x16x32_bf16 v[76:79], v[52:55], v[158:161], v[76:79]
	v_mfma_f32_16x16x32_bf16 v[72:75], v[68:71], v[158:161], v[72:75]
	v_mfma_f32_16x16x32_bf16 v[60:63], v[52:55], v[184:187], v[60:63]
	v_mfma_f32_16x16x32_bf16 v[56:59], v[68:71], v[184:187], v[56:59]
	v_mfma_f32_16x16x32_bf16 v[44:47], v[52:55], v[192:195], v[44:47]
	v_mfma_f32_16x16x32_bf16 v[40:43], v[68:71], v[192:195], v[40:43]
	v_mfma_f32_16x16x32_bf16 v[12:15], v[52:55], v[200:203], v[12:15]
	v_mfma_f32_16x16x32_bf16 v[8:11], v[68:71], v[200:203], v[8:11]
	s_setprio 0
	s_barrier
	s_add_u32 s2, s2, 0x40080
	s_addc_u32 s3, s3, 0
	s_add_i32 s22, s22, s36
	v_lshl_add_u64 v[48:49], s[2:3], 0, v[168:169]
	s_mov_b32 m0, s22
	s_nop 0
	global_load_lds_dwordx4 v[48:49], off
	v_lshl_add_u64 v[48:49], s[2:3], 0, v[148:149]
	s_add_i32 m0, s22, 0x2000
	s_nop 0
	global_load_lds_dwordx4 v[48:49], off
	s_waitcnt vmcnt(6)
	s_barrier
	s_setprio 1
	v_mfma_f32_16x16x32_bf16 v[24:27], v[204:207], v[154:157], v[24:27]
	v_mfma_f32_16x16x32_bf16 v[68:71], v[208:211], v[158:161], v[24:27]
	v_mfma_f32_16x16x32_bf16 v[24:27], v[212:215], v[154:157], v[28:31]
	v_mfma_f32_16x16x32_bf16 v[64:67], v[216:219], v[158:161], v[24:27]
	v_mfma_f32_16x16x32_bf16 v[24:27], v[204:207], v[180:183], v[32:35]
	v_mfma_f32_16x16x32_bf16 v[52:55], v[208:211], v[184:187], v[24:27]
	v_mfma_f32_16x16x32_bf16 v[24:27], v[212:215], v[180:183], v[36:39]
	v_mfma_f32_16x16x32_bf16 v[20:23], v[204:207], v[188:191], v[20:23]
	v_mfma_f32_16x16x32_bf16 v[16:19], v[212:215], v[188:191], v[16:19]
	v_mfma_f32_16x16x32_bf16 v[4:7], v[204:207], v[196:199], v[4:7]
	v_mfma_f32_16x16x32_bf16 v[0:3], v[212:215], v[196:199], v[0:3]
	v_mfma_f32_16x16x32_bf16 v[48:51], v[216:219], v[184:187], v[24:27]
	v_mfma_f32_16x16x32_bf16 v[20:23], v[208:211], v[192:195], v[20:23]
	v_mfma_f32_16x16x32_bf16 v[16:19], v[216:219], v[192:195], v[16:19]
	v_mfma_f32_16x16x32_bf16 v[4:7], v[208:211], v[200:203], v[4:7]
	v_mfma_f32_16x16x32_bf16 v[0:3], v[216:219], v[200:203], v[0:3]
	s_setprio 0
	s_add_i32 s52, s52, 2
	s_add_u32 s20, s20, 0x100
	s_addc_u32 s21, s21, 0
	s_add_u32 s50, s50, 0x100
	s_addc_u32 s51, s51, 0
	s_cmp_gt_u32 s52, 13
	s_barrier
	s_cbranch_scc0 .LBB0_123
	s_lshl_b32 s2, s6, 8
	s_add_i32 s3, s2, s43
	s_lshl_b32 s2, s8, 8
	s_cmp_gt_i32 s8, 3
	s_cselect_b64 s[20:21], -1, 0
	s_and_b64 s[22:23], s[20:21], exec
	s_mov_b32 s7, 0x8982000
	s_cselect_b32 s7, s7, 0x7182000
	s_add_u32 s22, s26, s7
	s_addc_u32 s23, s25, 0
	s_add_i32 s7, s6, -16
	v_mov_b32_e32 v160, v163
	v_mov_b32_e32 v24, v162
	s_lshr_b32 s7, s7, 3
	s_add_i32 s96, s7, 1
	v_add_u32_e32 v154, s3, v24
	s_lshl_b64 s[50:51], s[96:97], 11
	v_ashrrev_i32_e32 v155, 31, v154
	s_cmp_gt_i32 s6, 15
	v_lshl_add_u64 v[156:157], v[154:155], 2, s[10:11]
	s_cselect_b32 s7, s51, 0
	s_cselect_b32 s6, s50, 0
	global_load_dword v166, v[156:157], off
	global_load_dword v191, v[156:157], off offset:64
	global_load_dword v192, v[156:157], off offset:128
	global_load_dword v193, v[156:157], off offset:192
	global_load_dword v194, v[156:157], off offset:512
	global_load_dword v195, v[156:157], off offset:576
	global_load_dword v196, v[156:157], off offset:640
	global_load_dword v197, v[156:157], off offset:704
	s_lshl_b64 s[6:7], s[6:7], 2
	s_add_u32 s9, s41, s6
	s_addc_u32 s13, s42, s7
	s_ashr_i32 s3, s2, 31
	s_lshl_b64 s[6:7], s[2:3], 2
	s_add_u32 s3, s9, s6
	s_addc_u32 s7, s13, s7
	v_lshlrev_b32_e32 v158, 3, v160
	s_add_u32 s6, s3, s49
	s_addc_u32 s7, s7, 0
	v_ashrrev_i32_e32 v159, 31, v158
	v_lshl_add_u64 v[24:25], v[158:159], 2, s[6:7]
	global_load_dwordx4 v[36:39], v[24:25], off
	global_load_dwordx4 v[32:35], v[24:25], off offset:16
	global_load_dwordx4 v[28:31], v[24:25], off offset:512
	s_nop 0
	global_load_dwordx4 v[24:27], v[24:25], off offset:528
	s_and_b32 s2, s2, 0x300
	s_or_b32 s2, s2, s44
	v_add_u32_e32 v158, s2, v158
	v_cmp_eq_u32_e64 s[6:7], 0, v160
	v_lshlrev_b64 v[160:161], 11, v[154:155]
	s_cmp_lt_i32 s8, 4
	s_waitcnt vmcnt(0)
	v_fmamk_f32 v159, v166, 0x3a800000, v225
	v_mul_f32_e32 v166, 0x4b800000, v159
	v_cmp_gt_f32_e32 vcc, s93, v159
	s_nop 1
	v_cndmask_b32_e32 v159, v159, v166, vcc
	v_rsq_f32_e32 v166, v159
	v_ashrrev_i32_e32 v159, 31, v158
	v_lshl_add_u64 v[158:159], v[158:159], 1, s[22:23]
	v_lshl_add_u64 v[160:161], v[158:159], 0, v[160:161]
	v_mul_f32_e32 v167, 0x45800000, v166
	v_cndmask_b32_e32 v166, v166, v167, vcc
	v_pk_fma_f32 v[142:143], v[142:143], v[166:167], v[38:39] op_sel_hi:[1,0,1]
	v_pk_fma_f32 v[140:141], v[140:141], v[166:167], v[36:37] op_sel_hi:[1,0,1]
	v_pk_fma_f32 v[138:139], v[138:139], v[166:167], v[34:35] op_sel_hi:[1,0,1]
	v_pk_fma_f32 v[136:137], v[136:137], v[166:167], v[32:33] op_sel_hi:[1,0,1]
	v_pk_fma_f32 v[180:181], v[134:135], v[166:167], v[30:31] op_sel_hi:[1,0,1]
	v_pk_fma_f32 v[182:183], v[132:133], v[166:167], v[28:29] op_sel_hi:[1,0,1]
	v_pk_fma_f32 v[184:185], v[128:129], v[166:167], v[24:25] op_sel_hi:[1,0,1]
	v_mul_f32_e32 v128, 0x3d372713, v140
	v_mul_f32_e32 v129, 0x3d372713, v136
	v_mul_f32_e32 v132, 0x3d372713, v141
	v_mul_f32_e32 v133, 0x3d372713, v137
	v_mul_f32_e32 v134, 0x3d372713, v142
	v_mul_f32_e32 v135, 0x3d372713, v138
	v_mul_f32_e32 v167, 0x3d372713, v143
	v_mul_f32_e32 v186, 0x3d372713, v139
	v_mul_f32_e32 v128, v140, v128
	v_mul_f32_e32 v129, v136, v129
	v_mul_f32_e32 v132, v141, v132
	v_mul_f32_e32 v133, v137, v133
	v_mul_f32_e32 v134, v142, v134
	v_mul_f32_e32 v135, v138, v135
	v_mul_f32_e32 v167, v143, v167
	v_mul_f32_e32 v186, v139, v186
	v_fma_f32 v128, v140, v128, v140
	v_fma_f32 v129, v136, v129, v136
	v_fma_f32 v132, v141, v132, v141
	v_fma_f32 v133, v137, v133, v137
	v_fma_f32 v134, v142, v134, v142
	v_fma_f32 v135, v138, v135, v138
	v_fma_f32 v167, v143, v167, v143
	v_fma_f32 v186, v139, v186, v139
	v_mul_f32_e32 v128, 0xc0135761, v128
	v_mul_f32_e32 v129, 0xc0135761, v129
	v_mul_f32_e32 v132, 0xc0135761, v132
	v_mul_f32_e32 v133, 0xc0135761, v133
	v_mul_f32_e32 v134, 0xc0135761, v134
	v_mul_f32_e32 v135, 0xc0135761, v135
	v_mul_f32_e32 v167, 0xc0135761, v167
	v_mul_f32_e32 v186, 0xc0135761, v186
	v_exp_f32_e32 v128, v128
	v_exp_f32_e32 v129, v129
	v_exp_f32_e32 v132, v132
	v_exp_f32_e32 v133, v133
	v_exp_f32_e32 v134, v134
	v_exp_f32_e32 v135, v135
	v_exp_f32_e32 v167, v167
	v_exp_f32_e32 v186, v186
	v_add_f32_e32 v128, 1.0, v128
	v_add_f32_e32 v129, 1.0, v129
	v_add_f32_e32 v132, 1.0, v132
	v_add_f32_e32 v133, 1.0, v133
	v_add_f32_e32 v187, 1.0, v134
	v_add_f32_e32 v188, 1.0, v135
	v_add_f32_e32 v167, 1.0, v167
	v_add_f32_e32 v189, 1.0, v186
	v_rcp_f32_e32 v128, v128
	v_rcp_f32_e32 v134, v129
	v_rcp_f32_e32 v129, v132
	v_rcp_f32_e32 v135, v133
	v_rcp_f32_e32 v186, v187
	v_rcp_f32_e32 v188, v188
	v_rcp_f32_e32 v187, v167
	v_rcp_f32_e32 v189, v189
	v_pk_mul_f32 v[132:133], v[140:141], v[128:129]
	v_pk_mul_f32 v[136:137], v[136:137], v[134:135]
	v_pk_mul_f32 v[128:129], v[142:143], v[186:187]
	v_pk_mul_f32 v[134:135], v[138:139], v[188:189]
	v_cvt_pk_bf16_f32 v138, v132, v133
	v_cvt_pk_bf16_f32 v139, v128, v129
	v_cvt_pk_bf16_f32 v140, v136, v137
	v_cvt_pk_bf16_f32 v141, v134, v135
	v_mul_f32_e32 v190, 0x3d372713, v182
	global_store_dwordx4 v[160:161], v[138:141], off
	v_pk_fma_f32 v[142:143], v[130:131], v[166:167], v[26:27] op_sel_hi:[1,0,1]
	s_nop 0
	v_mul_f32_e32 v139, 0x3d372713, v184
	v_mul_f32_e32 v138, v182, v190
	v_mul_f32_e32 v139, v184, v139
	v_fma_f32 v138, v182, v138, v182
	v_fma_f32 v139, v184, v139, v184
	v_mul_f32_e32 v138, 0xc0135761, v138
	v_mul_f32_e32 v139, 0xc0135761, v139
	v_exp_f32_e32 v138, v138
	v_exp_f32_e32 v139, v139
	v_mul_f32_e32 v141, 0x3d372713, v142
	v_mul_f32_e32 v141, v142, v141
	v_add_f32_e32 v130, 1.0, v138
	v_add_f32_e32 v131, 1.0, v139
	v_mul_f32_e32 v138, 0x3d372713, v183
	v_mul_f32_e32 v139, 0x3d372713, v185
	v_mul_f32_e32 v138, v183, v138
	v_mul_f32_e32 v139, v185, v139
	v_fma_f32 v138, v183, v138, v183
	v_fma_f32 v139, v185, v139, v185
	v_mul_f32_e32 v138, 0xc0135761, v138
	v_mul_f32_e32 v139, 0xc0135761, v139
	v_exp_f32_e32 v138, v138
	v_exp_f32_e32 v139, v139
	v_rcp_f32_e32 v140, v131
	v_fma_f32 v141, v142, v141, v142
	v_add_f32_e32 v131, 1.0, v138
	v_add_f32_e32 v138, 1.0, v139
	v_mul_f32_e32 v139, 0x3d372713, v180
	v_mul_f32_e32 v139, v180, v139
	v_fma_f32 v139, v180, v139, v180
	v_mul_f32_e32 v139, 0xc0135761, v139
	v_exp_f32_e32 v139, v139
	v_mul_f32_e32 v141, 0xc0135761, v141
	v_exp_f32_e32 v167, v141
	v_rcp_f32_e32 v141, v138
	v_add_f32_e32 v138, 1.0, v139
	v_mul_f32_e32 v139, 0x3d372713, v181
	v_rcp_f32_e32 v166, v138
	v_add_f32_e32 v138, 1.0, v167
	v_mul_f32_e32 v139, v181, v139
	v_mul_f32_e32 v167, 0x3d372713, v143
	v_fma_f32 v139, v181, v139, v181
	v_mul_f32_e32 v167, v143, v167
	v_mul_f32_e32 v139, 0xc0135761, v139
	v_fma_f32 v167, v143, v167, v143
	v_exp_f32_e32 v139, v139
	v_mul_f32_e32 v167, 0xc0135761, v167
	v_exp_f32_e32 v187, v167
	v_rcp_f32_e32 v186, v138
	v_add_f32_e32 v138, 1.0, v139
	v_rcp_f32_e32 v167, v138
	v_add_f32_e32 v138, 1.0, v187
	v_rcp_f32_e32 v130, v130
	v_rcp_f32_e32 v131, v131
	v_rcp_f32_e32 v187, v138
	v_pk_mul_f32 v[140:141], v[184:185], v[140:141]
	v_pk_mul_f32 v[138:139], v[182:183], v[130:131]
	v_pk_mul_f32 v[130:131], v[180:181], v[166:167]
	v_pk_mul_f32 v[142:143], v[142:143], v[186:187]
	v_cvt_pk_bf16_f32 v180, v138, v139
	v_cvt_pk_bf16_f32 v181, v130, v131
	v_cvt_pk_bf16_f32 v182, v140, v141
	v_cvt_pk_bf16_f32 v183, v142, v143
	global_store_dwordx4 v[160:161], v[180:183], off offset:256
	s_cbranch_scc1 .LBB0_128
	v_pk_mul_f32 v[136:137], v[136:137], v[136:137]
	v_pk_mul_f32 v[134:135], v[134:135], v[134:135]
	v_pk_fma_f32 v[132:133], v[132:133], v[132:133], v[136:137]
	v_pk_fma_f32 v[128:129], v[128:129], v[128:129], v[134:135]
	v_pk_add_f32 v[132:133], v[132:133], v[132:133] op_sel:[0,1] op_sel_hi:[1,0]
	s_nop 0
	v_pk_add_f32 v[132:133], v[128:129], v[132:133]
	s_nop 0
	v_pk_add_f32 v[128:129], v[128:129], v[132:133] op_sel:[1,0] op_sel_hi:[0,1]
	v_pk_mul_f32 v[132:133], v[140:141], v[140:141]
	s_nop 0
	v_pk_fma_f32 v[132:133], v[138:139], v[138:139], v[132:133]
	s_nop 0
	v_pk_add_f32 v[128:129], v[132:133], v[128:129]
	s_nop 0
	v_pk_add_f32 v[128:129], v[132:133], v[128:129] op_sel:[1,0] op_sel_hi:[0,1]
	v_pk_mul_f32 v[132:133], v[142:143], v[142:143]
	s_nop 0
	v_pk_fma_f32 v[130:131], v[130:131], v[130:131], v[132:133]
	s_nop 0
	v_pk_add_f32 v[128:129], v[130:131], v[128:129]
	s_nop 0
	v_pk_add_f32 v[128:129], v[130:131], v[128:129] op_sel:[1,0] op_sel_hi:[0,1]
	v_mov_b32_e32 v129, v128
	s_nop 1
	v_permlane16_swap_b32_e32 v128, v129
	v_add_f32_e32 v128, v128, v129
	v_mov_b32_e32 v129, v128
	s_nop 1
	v_permlane32_swap_b32_e32 v128, v129
	s_and_saveexec_b64 s[2:3], s[6:7]
	s_cbranch_execz .LBB0_127
	v_lshl_add_u64 v[130:131], v[154:155], 2, s[0:1]
	v_add_f32_e32 v128, v128, v129
	global_atomic_add_f32 v[130:131], v128, off

.LBB0_128:
	v_mov_b32_e32 v132, v191
	v_add_u32_e32 v128, 16, v154
	v_ashrrev_i32_e32 v129, 31, v128
	v_lshlrev_b64 v[130:131], 11, v[128:129]
	v_lshl_add_u64 v[130:131], v[158:159], 0, v[130:131]
	s_nop 0
	v_fmamk_f32 v132, v132, 0x3a800000, v225
	v_cmp_gt_f32_e32 vcc, s93, v132
	v_mul_f32_e32 v133, 0x4b800000, v132
	s_nop 0
	v_cndmask_b32_e32 v132, v132, v133, vcc
	v_rsq_f32_e32 v132, v132
	s_nop 0
	v_mul_f32_e32 v133, 0x45800000, v132
	v_cndmask_b32_e32 v132, v132, v133, vcc
	v_pk_fma_f32 v[134:135], v[122:123], v[132:133], v[34:35] op_sel_hi:[1,0,1]
	v_pk_fma_f32 v[122:123], v[120:121], v[132:133], v[32:33] op_sel_hi:[1,0,1]
	v_pk_fma_f32 v[124:125], v[124:125], v[132:133], v[36:37] op_sel_hi:[1,0,1]
	v_mul_f32_e32 v121, 0x3d372713, v122
	v_mul_f32_e32 v121, v122, v121
	v_fma_f32 v121, v122, v121, v122
	v_mul_f32_e32 v121, 0xc0135761, v121
	v_exp_f32_e32 v121, v121
	v_mul_f32_e32 v120, 0x3d372713, v124
	v_mul_f32_e32 v120, v124, v120
	v_fma_f32 v120, v124, v120, v124
	v_add_f32_e32 v121, 1.0, v121
	v_rcp_f32_e32 v136, v121
	v_mul_f32_e32 v121, 0x3d372713, v125
	v_mul_f32_e32 v121, v125, v121
	v_fma_f32 v121, v125, v121, v125
	v_mul_f32_e32 v120, 0xc0135761, v120
	v_mul_f32_e32 v121, 0xc0135761, v121
	v_exp_f32_e32 v120, v120
	v_exp_f32_e32 v121, v121
	v_pk_fma_f32 v[126:127], v[126:127], v[132:133], v[38:39] op_sel_hi:[1,0,1]
	v_pk_fma_f32 v[118:119], v[118:119], v[132:133], v[30:31] op_sel_hi:[1,0,1]
	v_add_f32_e32 v120, 1.0, v120
	v_add_f32_e32 v121, 1.0, v121
	v_rcp_f32_e32 v120, v120
	v_rcp_f32_e32 v121, v121
	v_pk_fma_f32 v[114:115], v[114:115], v[132:133], v[26:27] op_sel_hi:[1,0,1]
	s_andn2_b64 vcc, exec, s[20:21]
	v_pk_mul_f32 v[120:121], v[124:125], v[120:121]
	v_mul_f32_e32 v124, 0x3d372713, v123
	v_mul_f32_e32 v124, v123, v124
	v_fma_f32 v124, v123, v124, v123
	v_mul_f32_e32 v124, 0xc0135761, v124
	v_exp_f32_e32 v124, v124
	v_mul_f32_e32 v125, 0x3d372713, v134
	v_mul_f32_e32 v125, v134, v125
	v_fma_f32 v125, v134, v125, v134
	v_mul_f32_e32 v125, 0xc0135761, v125
	v_add_f32_e32 v124, 1.0, v124
	v_exp_f32_e32 v125, v125
	v_rcp_f32_e32 v137, v124
	v_mul_f32_e32 v124, 0x3d372713, v126
	v_mul_f32_e32 v124, v126, v124
	v_add_f32_e32 v125, 1.0, v125
	v_pk_mul_f32 v[122:123], v[122:123], v[136:137]
	v_rcp_f32_e32 v136, v125
	v_mul_f32_e32 v125, 0x3d372713, v127
	v_mul_f32_e32 v125, v127, v125
	v_fma_f32 v124, v126, v124, v126
	v_fma_f32 v125, v127, v125, v127
	v_mul_f32_e32 v124, 0xc0135761, v124
	v_mul_f32_e32 v125, 0xc0135761, v125
	v_exp_f32_e32 v124, v124
	v_exp_f32_e32 v125, v125
	v_add_f32_e32 v124, 1.0, v124
	v_add_f32_e32 v125, 1.0, v125
	v_rcp_f32_e32 v124, v124
	v_rcp_f32_e32 v125, v125
	s_nop 0
	v_pk_mul_f32 v[124:125], v[126:127], v[124:125]
	v_mul_f32_e32 v126, 0x3d372713, v135
	v_mul_f32_e32 v126, v135, v126
	v_fma_f32 v126, v135, v126, v135
	v_mul_f32_e32 v126, 0xc0135761, v126
	v_exp_f32_e32 v126, v126
	s_nop 0
	v_add_f32_e32 v126, 1.0, v126
	v_rcp_f32_e32 v137, v126
	s_nop 0
	v_pk_mul_f32 v[126:127], v[134:135], v[136:137]
	v_cvt_pk_bf16_f32 v134, v120, v121
	v_cvt_pk_bf16_f32 v135, v124, v125
	v_cvt_pk_bf16_f32 v136, v122, v123
	v_cvt_pk_bf16_f32 v137, v126, v127
	global_store_dwordx4 v[130:131], v[134:137], off
	s_nop 1
	v_pk_fma_f32 v[134:135], v[116:117], v[132:133], v[28:29] op_sel_hi:[1,0,1]
	v_pk_fma_f32 v[116:117], v[112:113], v[132:133], v[24:25] op_sel_hi:[1,0,1]
	v_mul_f32_e32 v112, 0x3d372713, v134
	v_mul_f32_e32 v113, 0x3d372713, v116
	v_mul_f32_e32 v133, 0x3d372713, v117
	v_mul_f32_e32 v113, v116, v113
	v_mul_f32_e32 v133, v117, v133
	v_fma_f32 v113, v116, v113, v116
	v_fma_f32 v133, v117, v133, v117
	v_mul_f32_e32 v113, 0xc0135761, v113
	v_mul_f32_e32 v133, 0xc0135761, v133
	v_exp_f32_e32 v113, v113
	v_exp_f32_e32 v133, v133
	v_mul_f32_e32 v112, v134, v112
	v_fma_f32 v112, v134, v112, v134
	v_add_f32_e32 v113, 1.0, v113
	v_add_f32_e32 v133, 1.0, v133
	v_rcp_f32_e32 v132, v113
	v_mul_f32_e32 v113, 0x3d372713, v135
	v_rcp_f32_e32 v133, v133
	v_mul_f32_e32 v113, v135, v113
	v_fma_f32 v113, v135, v113, v135
	v_mul_f32_e32 v112, 0xc0135761, v112
	v_mul_f32_e32 v113, 0xc0135761, v113
	v_exp_f32_e32 v112, v112
	v_exp_f32_e32 v113, v113
	v_pk_mul_f32 v[116:117], v[116:117], v[132:133]
	v_mul_f32_e32 v133, 0x3d372713, v114
	v_mul_f32_e32 v133, v114, v133
	v_fma_f32 v133, v114, v133, v114
	v_mul_f32_e32 v133, 0xc0135761, v133
	v_add_f32_e32 v112, 1.0, v112
	v_add_f32_e32 v113, 1.0, v113
	v_exp_f32_e32 v133, v133
	v_rcp_f32_e32 v112, v112
	v_rcp_f32_e32 v113, v113
	v_mul_f32_e32 v132, 0x3d372713, v118
	v_add_f32_e32 v133, 1.0, v133
	v_mul_f32_e32 v132, v118, v132
	v_pk_mul_f32 v[112:113], v[134:135], v[112:113]
	v_rcp_f32_e32 v134, v133
	v_mul_f32_e32 v133, 0x3d372713, v119
	v_mul_f32_e32 v133, v119, v133
	v_fma_f32 v132, v118, v132, v118
	v_fma_f32 v133, v119, v133, v119
	v_mul_f32_e32 v132, 0xc0135761, v132
	v_mul_f32_e32 v133, 0xc0135761, v133
	v_exp_f32_e32 v132, v132
	v_exp_f32_e32 v133, v133
	v_add_f32_e32 v132, 1.0, v132
	v_add_f32_e32 v133, 1.0, v133
	v_rcp_f32_e32 v132, v132
	v_rcp_f32_e32 v133, v133
	s_nop 0
	v_pk_mul_f32 v[118:119], v[118:119], v[132:133]
	v_mul_f32_e32 v132, 0x3d372713, v115
	v_mul_f32_e32 v132, v115, v132
	v_fma_f32 v132, v115, v132, v115
	v_mul_f32_e32 v132, 0xc0135761, v132
	v_exp_f32_e32 v132, v132
	v_cvt_pk_bf16_f32 v133, v118, v119
	v_add_f32_e32 v132, 1.0, v132
	v_rcp_f32_e32 v135, v132
	v_cvt_pk_bf16_f32 v132, v112, v113
	v_pk_mul_f32 v[114:115], v[114:115], v[134:135]
	v_cvt_pk_bf16_f32 v134, v116, v117
	v_cvt_pk_bf16_f32 v135, v114, v115
	global_store_dwordx4 v[130:131], v[132:135], off offset:256
	v_cndmask_b32_e64 v130, 0, 1, s[20:21]
	v_cmp_ne_u32_e64 s[8:9], 1, v130
	s_cbranch_vccnz .LBB0_132
	v_pk_mul_f32 v[122:123], v[122:123], v[122:123]
	v_pk_mul_f32 v[116:117], v[116:117], v[116:117]
	v_pk_fma_f32 v[120:121], v[120:121], v[120:121], v[122:123]
	v_pk_mul_f32 v[122:123], v[126:127], v[126:127]
	v_pk_add_f32 v[120:121], v[120:121], v[120:121] op_sel:[0,1] op_sel_hi:[1,0]
	v_pk_fma_f32 v[122:123], v[124:125], v[124:125], v[122:123]
	v_pk_fma_f32 v[112:113], v[112:113], v[112:113], v[116:117]
	v_pk_add_f32 v[120:121], v[122:123], v[120:121]
	v_pk_mul_f32 v[114:115], v[114:115], v[114:115]
	v_pk_add_f32 v[120:121], v[122:123], v[120:121] op_sel:[1,0] op_sel_hi:[0,1]
	v_pk_add_f32 v[116:117], v[112:113], v[120:121]
	v_pk_fma_f32 v[114:115], v[118:119], v[118:119], v[114:115]
	v_pk_add_f32 v[112:113], v[112:113], v[116:117] op_sel:[1,0] op_sel_hi:[0,1]
	v_pk_add_f32 v[112:113], v[114:115], v[112:113]
	s_nop 0
	v_pk_add_f32 v[112:113], v[114:115], v[112:113] op_sel:[1,0] op_sel_hi:[0,1]
	v_mov_b32_e32 v113, v112
	s_nop 1
	v_permlane16_swap_b32_e32 v112, v113
	v_add_f32_e32 v112, v112, v113
	v_mov_b32_e32 v113, v112
	s_nop 1
	v_permlane32_swap_b32_e32 v112, v113
	s_and_saveexec_b64 s[2:3], s[6:7]
	s_cbranch_execz .LBB0_131
	v_lshl_add_u64 v[114:115], v[128:129], 2, s[0:1]
	v_add_f32_e32 v112, v112, v113
	global_atomic_add_f32 v[114:115], v112, off

.LBB0_132:
	v_mov_b32_e32 v116, v192
	v_add_u32_e32 v112, 32, v154
	v_ashrrev_i32_e32 v113, 31, v112
	v_lshlrev_b64 v[114:115], 11, v[112:113]
	v_lshl_add_u64 v[114:115], v[158:159], 0, v[114:115]
	s_nop 0
	v_fmamk_f32 v116, v116, 0x3a800000, v225
	v_cmp_gt_f32_e32 vcc, s93, v116
	v_mul_f32_e32 v117, 0x4b800000, v116
	s_nop 0
	v_cndmask_b32_e32 v116, v116, v117, vcc
	v_rsq_f32_e32 v116, v116
	s_nop 0
	v_mul_f32_e32 v117, 0x45800000, v116
	v_cndmask_b32_e32 v116, v116, v117, vcc
	v_pk_fma_f32 v[118:119], v[106:107], v[116:117], v[34:35] op_sel_hi:[1,0,1]
	v_pk_fma_f32 v[106:107], v[104:105], v[116:117], v[32:33] op_sel_hi:[1,0,1]
	v_pk_fma_f32 v[108:109], v[108:109], v[116:117], v[36:37] op_sel_hi:[1,0,1]
	v_mul_f32_e32 v105, 0x3d372713, v106
	v_mul_f32_e32 v105, v106, v105
	v_fma_f32 v105, v106, v105, v106
	v_mul_f32_e32 v105, 0xc0135761, v105
	v_exp_f32_e32 v105, v105
	v_mul_f32_e32 v104, 0x3d372713, v108
	v_mul_f32_e32 v104, v108, v104
	v_fma_f32 v104, v108, v104, v108
	v_add_f32_e32 v105, 1.0, v105
	v_rcp_f32_e32 v120, v105
	v_mul_f32_e32 v105, 0x3d372713, v109
	v_mul_f32_e32 v105, v109, v105
	v_fma_f32 v105, v109, v105, v109
	v_mul_f32_e32 v104, 0xc0135761, v104
	v_mul_f32_e32 v105, 0xc0135761, v105
	v_exp_f32_e32 v104, v104
	v_exp_f32_e32 v105, v105
	v_pk_fma_f32 v[110:111], v[110:111], v[116:117], v[38:39] op_sel_hi:[1,0,1]
	v_pk_fma_f32 v[102:103], v[102:103], v[116:117], v[30:31] op_sel_hi:[1,0,1]
	v_add_f32_e32 v104, 1.0, v104
	v_add_f32_e32 v105, 1.0, v105
	v_rcp_f32_e32 v104, v104
	v_rcp_f32_e32 v105, v105
	v_pk_fma_f32 v[98:99], v[98:99], v[116:117], v[26:27] op_sel_hi:[1,0,1]
	s_and_b64 vcc, exec, s[8:9]
	v_pk_mul_f32 v[104:105], v[108:109], v[104:105]
	v_mul_f32_e32 v108, 0x3d372713, v107
	v_mul_f32_e32 v108, v107, v108
	v_fma_f32 v108, v107, v108, v107
	v_mul_f32_e32 v108, 0xc0135761, v108
	v_exp_f32_e32 v108, v108
	v_mul_f32_e32 v109, 0x3d372713, v118
	v_mul_f32_e32 v109, v118, v109
	v_fma_f32 v109, v118, v109, v118
	v_mul_f32_e32 v109, 0xc0135761, v109
	v_add_f32_e32 v108, 1.0, v108
	v_exp_f32_e32 v109, v109
	v_rcp_f32_e32 v121, v108
	v_mul_f32_e32 v108, 0x3d372713, v110
	v_mul_f32_e32 v108, v110, v108
	v_add_f32_e32 v109, 1.0, v109
	v_pk_mul_f32 v[106:107], v[106:107], v[120:121]
	v_rcp_f32_e32 v120, v109
	v_mul_f32_e32 v109, 0x3d372713, v111
	v_mul_f32_e32 v109, v111, v109
	v_fma_f32 v108, v110, v108, v110
	v_fma_f32 v109, v111, v109, v111
	v_mul_f32_e32 v108, 0xc0135761, v108
	v_mul_f32_e32 v109, 0xc0135761, v109
	v_exp_f32_e32 v108, v108
	v_exp_f32_e32 v109, v109
	v_add_f32_e32 v108, 1.0, v108
	v_add_f32_e32 v109, 1.0, v109
	v_rcp_f32_e32 v108, v108
	v_rcp_f32_e32 v109, v109
	s_nop 0
	v_pk_mul_f32 v[108:109], v[110:111], v[108:109]
	v_mul_f32_e32 v110, 0x3d372713, v119
	v_mul_f32_e32 v110, v119, v110
	v_fma_f32 v110, v119, v110, v119
	v_mul_f32_e32 v110, 0xc0135761, v110
	v_exp_f32_e32 v110, v110
	s_nop 0
	v_add_f32_e32 v110, 1.0, v110
	v_rcp_f32_e32 v121, v110
	s_nop 0
	v_pk_mul_f32 v[110:111], v[118:119], v[120:121]
	v_cvt_pk_bf16_f32 v118, v104, v105
	v_cvt_pk_bf16_f32 v119, v108, v109
	v_cvt_pk_bf16_f32 v120, v106, v107
	v_cvt_pk_bf16_f32 v121, v110, v111
	global_store_dwordx4 v[114:115], v[118:121], off
	s_nop 1
	v_pk_fma_f32 v[118:119], v[100:101], v[116:117], v[28:29] op_sel_hi:[1,0,1]
	v_pk_fma_f32 v[100:101], v[96:97], v[116:117], v[24:25] op_sel_hi:[1,0,1]
	v_mul_f32_e32 v96, 0x3d372713, v118
	v_mul_f32_e32 v97, 0x3d372713, v100
	v_mul_f32_e32 v117, 0x3d372713, v101
	v_mul_f32_e32 v97, v100, v97
	v_mul_f32_e32 v117, v101, v117
	v_fma_f32 v97, v100, v97, v100
	v_fma_f32 v117, v101, v117, v101
	v_mul_f32_e32 v97, 0xc0135761, v97
	v_mul_f32_e32 v117, 0xc0135761, v117
	v_exp_f32_e32 v97, v97
	v_exp_f32_e32 v117, v117
	v_mul_f32_e32 v96, v118, v96
	v_fma_f32 v96, v118, v96, v118
	v_add_f32_e32 v97, 1.0, v97
	v_add_f32_e32 v117, 1.0, v117
	v_rcp_f32_e32 v116, v97
	v_mul_f32_e32 v97, 0x3d372713, v119
	v_rcp_f32_e32 v117, v117
	v_mul_f32_e32 v97, v119, v97
	v_fma_f32 v97, v119, v97, v119
	v_mul_f32_e32 v96, 0xc0135761, v96
	v_mul_f32_e32 v97, 0xc0135761, v97
	v_exp_f32_e32 v96, v96
	v_exp_f32_e32 v97, v97
	v_pk_mul_f32 v[100:101], v[100:101], v[116:117]
	v_mul_f32_e32 v117, 0x3d372713, v98
	v_mul_f32_e32 v117, v98, v117
	v_fma_f32 v117, v98, v117, v98
	v_mul_f32_e32 v117, 0xc0135761, v117
	v_add_f32_e32 v96, 1.0, v96
	v_add_f32_e32 v97, 1.0, v97
	v_exp_f32_e32 v117, v117
	v_rcp_f32_e32 v96, v96
	v_rcp_f32_e32 v97, v97
	v_mul_f32_e32 v116, 0x3d372713, v102
	v_add_f32_e32 v117, 1.0, v117
	v_mul_f32_e32 v116, v102, v116
	v_pk_mul_f32 v[96:97], v[118:119], v[96:97]
	v_rcp_f32_e32 v118, v117
	v_mul_f32_e32 v117, 0x3d372713, v103
	v_mul_f32_e32 v117, v103, v117
	v_fma_f32 v116, v102, v116, v102
	v_fma_f32 v117, v103, v117, v103
	v_mul_f32_e32 v116, 0xc0135761, v116
	v_mul_f32_e32 v117, 0xc0135761, v117
	v_exp_f32_e32 v116, v116
	v_exp_f32_e32 v117, v117
	v_add_f32_e32 v116, 1.0, v116
	v_add_f32_e32 v117, 1.0, v117
	v_rcp_f32_e32 v116, v116
	v_rcp_f32_e32 v117, v117
	s_nop 0
	v_pk_mul_f32 v[102:103], v[102:103], v[116:117]
	v_mul_f32_e32 v116, 0x3d372713, v99
	v_mul_f32_e32 v116, v99, v116
	v_fma_f32 v116, v99, v116, v99
	v_mul_f32_e32 v116, 0xc0135761, v116
	v_exp_f32_e32 v116, v116
	v_cvt_pk_bf16_f32 v117, v102, v103
	v_add_f32_e32 v116, 1.0, v116
	v_rcp_f32_e32 v119, v116
	v_cvt_pk_bf16_f32 v116, v96, v97
	v_pk_mul_f32 v[98:99], v[98:99], v[118:119]
	v_cvt_pk_bf16_f32 v118, v100, v101
	v_cvt_pk_bf16_f32 v119, v98, v99
	global_store_dwordx4 v[114:115], v[116:119], off offset:256
	s_cbranch_vccnz .LBB0_136
	v_pk_mul_f32 v[106:107], v[106:107], v[106:107]
	v_pk_mul_f32 v[100:101], v[100:101], v[100:101]
	v_pk_fma_f32 v[104:105], v[104:105], v[104:105], v[106:107]
	v_pk_mul_f32 v[106:107], v[110:111], v[110:111]
	v_pk_add_f32 v[104:105], v[104:105], v[104:105] op_sel:[0,1] op_sel_hi:[1,0]
	v_pk_fma_f32 v[106:107], v[108:109], v[108:109], v[106:107]
	v_pk_fma_f32 v[96:97], v[96:97], v[96:97], v[100:101]
	v_pk_add_f32 v[104:105], v[106:107], v[104:105]
	v_pk_mul_f32 v[98:99], v[98:99], v[98:99]
	v_pk_add_f32 v[104:105], v[106:107], v[104:105] op_sel:[1,0] op_sel_hi:[0,1]
	v_pk_add_f32 v[100:101], v[96:97], v[104:105]
	v_pk_fma_f32 v[98:99], v[102:103], v[102:103], v[98:99]
	v_pk_add_f32 v[96:97], v[96:97], v[100:101] op_sel:[1,0] op_sel_hi:[0,1]
	v_pk_add_f32 v[96:97], v[98:99], v[96:97]
	s_nop 0
	v_pk_add_f32 v[96:97], v[98:99], v[96:97] op_sel:[1,0] op_sel_hi:[0,1]
	v_mov_b32_e32 v97, v96
	s_nop 1
	v_permlane16_swap_b32_e32 v96, v97
	v_add_f32_e32 v96, v96, v97
	v_mov_b32_e32 v97, v96
	s_nop 1
	v_permlane32_swap_b32_e32 v96, v97
	s_and_saveexec_b64 s[2:3], s[6:7]
	s_cbranch_execz .LBB0_135
	v_lshl_add_u64 v[98:99], v[112:113], 2, s[0:1]
	v_add_f32_e32 v96, v96, v97
	global_atomic_add_f32 v[98:99], v96, off

.LBB0_136:
	v_mov_b32_e32 v100, v193
	v_add_u32_e32 v96, 48, v154
	v_ashrrev_i32_e32 v97, 31, v96
	v_lshlrev_b64 v[98:99], 11, v[96:97]
	v_lshl_add_u64 v[98:99], v[158:159], 0, v[98:99]
	s_nop 0
	v_fmamk_f32 v100, v100, 0x3a800000, v225
	v_cmp_gt_f32_e32 vcc, s93, v100
	v_mul_f32_e32 v101, 0x4b800000, v100
	s_nop 0
	v_cndmask_b32_e32 v100, v100, v101, vcc
	v_rsq_f32_e32 v100, v100
	s_nop 0
	v_mul_f32_e32 v101, 0x45800000, v100
	v_cndmask_b32_e32 v100, v100, v101, vcc
	v_pk_fma_f32 v[102:103], v[90:91], v[100:101], v[34:35] op_sel_hi:[1,0,1]
	v_pk_fma_f32 v[90:91], v[88:89], v[100:101], v[32:33] op_sel_hi:[1,0,1]
	v_pk_fma_f32 v[92:93], v[92:93], v[100:101], v[36:37] op_sel_hi:[1,0,1]
	v_mul_f32_e32 v89, 0x3d372713, v90
	v_mul_f32_e32 v89, v90, v89
	v_fma_f32 v89, v90, v89, v90
	v_mul_f32_e32 v89, 0xc0135761, v89
	v_exp_f32_e32 v89, v89
	v_mul_f32_e32 v88, 0x3d372713, v92
	v_mul_f32_e32 v88, v92, v88
	v_fma_f32 v88, v92, v88, v92
	v_add_f32_e32 v89, 1.0, v89
	v_rcp_f32_e32 v104, v89
	v_mul_f32_e32 v89, 0x3d372713, v93
	v_mul_f32_e32 v89, v93, v89
	v_fma_f32 v89, v93, v89, v93
	v_mul_f32_e32 v88, 0xc0135761, v88
	v_mul_f32_e32 v89, 0xc0135761, v89
	v_exp_f32_e32 v88, v88
	v_exp_f32_e32 v89, v89
	v_pk_fma_f32 v[94:95], v[94:95], v[100:101], v[38:39] op_sel_hi:[1,0,1]
	v_pk_fma_f32 v[86:87], v[86:87], v[100:101], v[30:31] op_sel_hi:[1,0,1]
	v_add_f32_e32 v88, 1.0, v88
	v_add_f32_e32 v89, 1.0, v89
	v_rcp_f32_e32 v88, v88
	v_rcp_f32_e32 v89, v89
	v_pk_fma_f32 v[82:83], v[82:83], v[100:101], v[26:27] op_sel_hi:[1,0,1]
	s_and_b64 vcc, exec, s[8:9]
	v_pk_mul_f32 v[88:89], v[92:93], v[88:89]
	v_mul_f32_e32 v92, 0x3d372713, v91
	v_mul_f32_e32 v92, v91, v92
	v_fma_f32 v92, v91, v92, v91
	v_mul_f32_e32 v92, 0xc0135761, v92
	v_exp_f32_e32 v92, v92
	v_mul_f32_e32 v93, 0x3d372713, v102
	v_mul_f32_e32 v93, v102, v93
	v_fma_f32 v93, v102, v93, v102
	v_mul_f32_e32 v93, 0xc0135761, v93
	v_add_f32_e32 v92, 1.0, v92
	v_exp_f32_e32 v93, v93
	v_rcp_f32_e32 v105, v92
	v_mul_f32_e32 v92, 0x3d372713, v94
	v_mul_f32_e32 v92, v94, v92
	v_add_f32_e32 v93, 1.0, v93
	v_pk_mul_f32 v[90:91], v[90:91], v[104:105]
	v_rcp_f32_e32 v104, v93
	v_mul_f32_e32 v93, 0x3d372713, v95
	v_mul_f32_e32 v93, v95, v93
	v_fma_f32 v92, v94, v92, v94
	v_fma_f32 v93, v95, v93, v95
	v_mul_f32_e32 v92, 0xc0135761, v92
	v_mul_f32_e32 v93, 0xc0135761, v93
	v_exp_f32_e32 v92, v92
	v_exp_f32_e32 v93, v93
	v_add_f32_e32 v92, 1.0, v92
	v_add_f32_e32 v93, 1.0, v93
	v_rcp_f32_e32 v92, v92
	v_rcp_f32_e32 v93, v93
	s_nop 0
	v_pk_mul_f32 v[92:93], v[94:95], v[92:93]
	v_mul_f32_e32 v94, 0x3d372713, v103
	v_mul_f32_e32 v94, v103, v94
	v_fma_f32 v94, v103, v94, v103
	v_mul_f32_e32 v94, 0xc0135761, v94
	v_exp_f32_e32 v94, v94
	s_nop 0
	v_add_f32_e32 v94, 1.0, v94
	v_rcp_f32_e32 v105, v94
	s_nop 0
	v_pk_mul_f32 v[94:95], v[102:103], v[104:105]
	v_cvt_pk_bf16_f32 v102, v88, v89
	v_cvt_pk_bf16_f32 v103, v92, v93
	v_cvt_pk_bf16_f32 v104, v90, v91
	v_cvt_pk_bf16_f32 v105, v94, v95
	global_store_dwordx4 v[98:99], v[102:105], off
	s_nop 1
	v_pk_fma_f32 v[102:103], v[84:85], v[100:101], v[28:29] op_sel_hi:[1,0,1]
	v_pk_fma_f32 v[84:85], v[80:81], v[100:101], v[24:25] op_sel_hi:[1,0,1]
	v_mul_f32_e32 v80, 0x3d372713, v102
	v_mul_f32_e32 v81, 0x3d372713, v84
	v_mul_f32_e32 v101, 0x3d372713, v85
	v_mul_f32_e32 v81, v84, v81
	v_mul_f32_e32 v101, v85, v101
	v_fma_f32 v81, v84, v81, v84
	v_fma_f32 v101, v85, v101, v85
	v_mul_f32_e32 v81, 0xc0135761, v81
	v_mul_f32_e32 v101, 0xc0135761, v101
	v_exp_f32_e32 v81, v81
	v_exp_f32_e32 v101, v101
	v_mul_f32_e32 v80, v102, v80
	v_fma_f32 v80, v102, v80, v102
	v_add_f32_e32 v81, 1.0, v81
	v_add_f32_e32 v101, 1.0, v101
	v_rcp_f32_e32 v100, v81
	v_mul_f32_e32 v81, 0x3d372713, v103
	v_rcp_f32_e32 v101, v101
	v_mul_f32_e32 v81, v103, v81
	v_fma_f32 v81, v103, v81, v103
	v_mul_f32_e32 v80, 0xc0135761, v80
	v_mul_f32_e32 v81, 0xc0135761, v81
	v_exp_f32_e32 v80, v80
	v_exp_f32_e32 v81, v81
	v_pk_mul_f32 v[84:85], v[84:85], v[100:101]
	v_mul_f32_e32 v101, 0x3d372713, v82
	v_mul_f32_e32 v101, v82, v101
	v_fma_f32 v101, v82, v101, v82
	v_mul_f32_e32 v101, 0xc0135761, v101
	v_add_f32_e32 v80, 1.0, v80
	v_add_f32_e32 v81, 1.0, v81
	v_exp_f32_e32 v101, v101
	v_rcp_f32_e32 v80, v80
	v_rcp_f32_e32 v81, v81
	v_mul_f32_e32 v100, 0x3d372713, v86
	v_add_f32_e32 v101, 1.0, v101
	v_mul_f32_e32 v100, v86, v100
	v_pk_mul_f32 v[80:81], v[102:103], v[80:81]
	v_rcp_f32_e32 v102, v101
	v_mul_f32_e32 v101, 0x3d372713, v87
	v_mul_f32_e32 v101, v87, v101
	v_fma_f32 v100, v86, v100, v86
	v_fma_f32 v101, v87, v101, v87
	v_mul_f32_e32 v100, 0xc0135761, v100
	v_mul_f32_e32 v101, 0xc0135761, v101
	v_exp_f32_e32 v100, v100
	v_exp_f32_e32 v101, v101
	v_add_f32_e32 v100, 1.0, v100
	v_add_f32_e32 v101, 1.0, v101
	v_rcp_f32_e32 v100, v100
	v_rcp_f32_e32 v101, v101
	s_nop 0
	v_pk_mul_f32 v[86:87], v[86:87], v[100:101]
	v_mul_f32_e32 v100, 0x3d372713, v83
	v_mul_f32_e32 v100, v83, v100
	v_fma_f32 v100, v83, v100, v83
	v_mul_f32_e32 v100, 0xc0135761, v100
	v_exp_f32_e32 v100, v100
	v_cvt_pk_bf16_f32 v101, v86, v87
	v_add_f32_e32 v100, 1.0, v100
	v_rcp_f32_e32 v103, v100
	v_cvt_pk_bf16_f32 v100, v80, v81
	v_pk_mul_f32 v[82:83], v[82:83], v[102:103]
	v_cvt_pk_bf16_f32 v102, v84, v85
	v_cvt_pk_bf16_f32 v103, v82, v83
	global_store_dwordx4 v[98:99], v[100:103], off offset:256
	s_cbranch_vccnz .LBB0_140
	v_pk_mul_f32 v[90:91], v[90:91], v[90:91]
	v_pk_mul_f32 v[84:85], v[84:85], v[84:85]
	v_pk_fma_f32 v[88:89], v[88:89], v[88:89], v[90:91]
	v_pk_mul_f32 v[90:91], v[94:95], v[94:95]
	v_pk_add_f32 v[88:89], v[88:89], v[88:89] op_sel:[0,1] op_sel_hi:[1,0]
	v_pk_fma_f32 v[90:91], v[92:93], v[92:93], v[90:91]
	v_pk_fma_f32 v[80:81], v[80:81], v[80:81], v[84:85]
	v_pk_add_f32 v[88:89], v[90:91], v[88:89]
	v_pk_mul_f32 v[82:83], v[82:83], v[82:83]
	v_pk_add_f32 v[88:89], v[90:91], v[88:89] op_sel:[1,0] op_sel_hi:[0,1]
	v_pk_add_f32 v[84:85], v[80:81], v[88:89]
	v_pk_fma_f32 v[82:83], v[86:87], v[86:87], v[82:83]
	v_pk_add_f32 v[80:81], v[80:81], v[84:85] op_sel:[1,0] op_sel_hi:[0,1]
	v_pk_add_f32 v[80:81], v[82:83], v[80:81]
	s_nop 0
	v_pk_add_f32 v[80:81], v[82:83], v[80:81] op_sel:[1,0] op_sel_hi:[0,1]
	v_mov_b32_e32 v81, v80
	s_nop 1
	v_permlane16_swap_b32_e32 v80, v81
	v_add_f32_e32 v80, v80, v81
	v_mov_b32_e32 v81, v80
	s_nop 1
	v_permlane32_swap_b32_e32 v80, v81
	s_and_saveexec_b64 s[2:3], s[6:7]
	s_cbranch_execz .LBB0_139
	v_lshl_add_u64 v[82:83], v[96:97], 2, s[0:1]
	v_add_f32_e32 v80, v80, v81
	global_atomic_add_f32 v[82:83], v80, off

.LBB0_140:
	v_mov_b32_e32 v84, v194
	v_add_u32_e32 v80, 0x80, v154
	v_ashrrev_i32_e32 v81, 31, v80
	v_lshlrev_b64 v[82:83], 11, v[80:81]
	v_lshl_add_u64 v[82:83], v[158:159], 0, v[82:83]
	s_nop 0
	v_fmamk_f32 v84, v84, 0x3a800000, v225
	v_cmp_gt_f32_e32 vcc, s93, v84
	v_mul_f32_e32 v85, 0x4b800000, v84
	s_nop 0
	v_cndmask_b32_e32 v84, v84, v85, vcc
	v_rsq_f32_e32 v84, v84
	s_nop 0
	v_mul_f32_e32 v85, 0x45800000, v84
	v_cndmask_b32_e32 v84, v84, v85, vcc
	v_pk_fma_f32 v[86:87], v[74:75], v[84:85], v[34:35] op_sel_hi:[1,0,1]
	v_pk_fma_f32 v[74:75], v[72:73], v[84:85], v[32:33] op_sel_hi:[1,0,1]
	v_pk_fma_f32 v[76:77], v[76:77], v[84:85], v[36:37] op_sel_hi:[1,0,1]
	v_mul_f32_e32 v73, 0x3d372713, v74
	v_mul_f32_e32 v73, v74, v73
	v_fma_f32 v73, v74, v73, v74
	v_mul_f32_e32 v73, 0xc0135761, v73
	v_exp_f32_e32 v73, v73
	v_mul_f32_e32 v72, 0x3d372713, v76
	v_mul_f32_e32 v72, v76, v72
	v_fma_f32 v72, v76, v72, v76
	v_add_f32_e32 v73, 1.0, v73
	v_rcp_f32_e32 v88, v73
	v_mul_f32_e32 v73, 0x3d372713, v77
	v_mul_f32_e32 v73, v77, v73
	v_fma_f32 v73, v77, v73, v77
	v_mul_f32_e32 v72, 0xc0135761, v72
	v_mul_f32_e32 v73, 0xc0135761, v73
	v_exp_f32_e32 v72, v72
	v_exp_f32_e32 v73, v73
	v_pk_fma_f32 v[78:79], v[78:79], v[84:85], v[38:39] op_sel_hi:[1,0,1]
	v_pk_fma_f32 v[70:71], v[70:71], v[84:85], v[30:31] op_sel_hi:[1,0,1]
	v_add_f32_e32 v72, 1.0, v72
	v_add_f32_e32 v73, 1.0, v73
	v_rcp_f32_e32 v72, v72
	v_rcp_f32_e32 v73, v73
	v_pk_fma_f32 v[66:67], v[66:67], v[84:85], v[26:27] op_sel_hi:[1,0,1]
	s_and_b64 vcc, exec, s[8:9]
	v_pk_mul_f32 v[72:73], v[76:77], v[72:73]
	v_mul_f32_e32 v76, 0x3d372713, v75
	v_mul_f32_e32 v76, v75, v76
	v_fma_f32 v76, v75, v76, v75
	v_mul_f32_e32 v76, 0xc0135761, v76
	v_exp_f32_e32 v76, v76
	v_mul_f32_e32 v77, 0x3d372713, v86
	v_mul_f32_e32 v77, v86, v77
	v_fma_f32 v77, v86, v77, v86
	v_mul_f32_e32 v77, 0xc0135761, v77
	v_add_f32_e32 v76, 1.0, v76
	v_exp_f32_e32 v77, v77
	v_rcp_f32_e32 v89, v76
	v_mul_f32_e32 v76, 0x3d372713, v78
	v_mul_f32_e32 v76, v78, v76
	v_add_f32_e32 v77, 1.0, v77
	v_pk_mul_f32 v[74:75], v[74:75], v[88:89]
	v_rcp_f32_e32 v88, v77
	v_mul_f32_e32 v77, 0x3d372713, v79
	v_mul_f32_e32 v77, v79, v77
	v_fma_f32 v76, v78, v76, v78
	v_fma_f32 v77, v79, v77, v79
	v_mul_f32_e32 v76, 0xc0135761, v76
	v_mul_f32_e32 v77, 0xc0135761, v77
	v_exp_f32_e32 v76, v76
	v_exp_f32_e32 v77, v77
	v_add_f32_e32 v76, 1.0, v76
	v_add_f32_e32 v77, 1.0, v77
	v_rcp_f32_e32 v76, v76
	v_rcp_f32_e32 v77, v77
	s_nop 0
	v_pk_mul_f32 v[76:77], v[78:79], v[76:77]
	v_mul_f32_e32 v78, 0x3d372713, v87
	v_mul_f32_e32 v78, v87, v78
	v_fma_f32 v78, v87, v78, v87
	v_mul_f32_e32 v78, 0xc0135761, v78
	v_exp_f32_e32 v78, v78
	s_nop 0
	v_add_f32_e32 v78, 1.0, v78
	v_rcp_f32_e32 v89, v78
	s_nop 0
	v_pk_mul_f32 v[78:79], v[86:87], v[88:89]
	v_cvt_pk_bf16_f32 v86, v72, v73
	v_cvt_pk_bf16_f32 v87, v76, v77
	v_cvt_pk_bf16_f32 v88, v74, v75
	v_cvt_pk_bf16_f32 v89, v78, v79
	global_store_dwordx4 v[82:83], v[86:89], off
	s_nop 1
	v_pk_fma_f32 v[86:87], v[68:69], v[84:85], v[28:29] op_sel_hi:[1,0,1]
	v_pk_fma_f32 v[68:69], v[64:65], v[84:85], v[24:25] op_sel_hi:[1,0,1]
	v_mul_f32_e32 v64, 0x3d372713, v86
	v_mul_f32_e32 v65, 0x3d372713, v68
	v_mul_f32_e32 v85, 0x3d372713, v69
	v_mul_f32_e32 v65, v68, v65
	v_mul_f32_e32 v85, v69, v85
	v_fma_f32 v65, v68, v65, v68
	v_fma_f32 v85, v69, v85, v69
	v_mul_f32_e32 v65, 0xc0135761, v65
	v_mul_f32_e32 v85, 0xc0135761, v85
	v_exp_f32_e32 v65, v65
	v_exp_f32_e32 v85, v85
	v_mul_f32_e32 v64, v86, v64
	v_fma_f32 v64, v86, v64, v86
	v_add_f32_e32 v65, 1.0, v65
	v_add_f32_e32 v85, 1.0, v85
	v_rcp_f32_e32 v84, v65
	v_mul_f32_e32 v65, 0x3d372713, v87
	v_rcp_f32_e32 v85, v85
	v_mul_f32_e32 v65, v87, v65
	v_fma_f32 v65, v87, v65, v87
	v_mul_f32_e32 v64, 0xc0135761, v64
	v_mul_f32_e32 v65, 0xc0135761, v65
	v_exp_f32_e32 v64, v64
	v_exp_f32_e32 v65, v65
	v_pk_mul_f32 v[68:69], v[68:69], v[84:85]
	v_mul_f32_e32 v85, 0x3d372713, v66
	v_mul_f32_e32 v85, v66, v85
	v_fma_f32 v85, v66, v85, v66
	v_mul_f32_e32 v85, 0xc0135761, v85
	v_add_f32_e32 v64, 1.0, v64
	v_add_f32_e32 v65, 1.0, v65
	v_exp_f32_e32 v85, v85
	v_rcp_f32_e32 v64, v64
	v_rcp_f32_e32 v65, v65
	v_mul_f32_e32 v84, 0x3d372713, v70
	v_add_f32_e32 v85, 1.0, v85
	v_mul_f32_e32 v84, v70, v84
	v_pk_mul_f32 v[64:65], v[86:87], v[64:65]
	v_rcp_f32_e32 v86, v85
	v_mul_f32_e32 v85, 0x3d372713, v71
	v_mul_f32_e32 v85, v71, v85
	v_fma_f32 v84, v70, v84, v70
	v_fma_f32 v85, v71, v85, v71
	v_mul_f32_e32 v84, 0xc0135761, v84
	v_mul_f32_e32 v85, 0xc0135761, v85
	v_exp_f32_e32 v84, v84
	v_exp_f32_e32 v85, v85
	v_add_f32_e32 v84, 1.0, v84
	v_add_f32_e32 v85, 1.0, v85
	v_rcp_f32_e32 v84, v84
	v_rcp_f32_e32 v85, v85
	s_nop 0
	v_pk_mul_f32 v[70:71], v[70:71], v[84:85]
	v_mul_f32_e32 v84, 0x3d372713, v67
	v_mul_f32_e32 v84, v67, v84
	v_fma_f32 v84, v67, v84, v67
	v_mul_f32_e32 v84, 0xc0135761, v84
	v_exp_f32_e32 v84, v84
	v_cvt_pk_bf16_f32 v85, v70, v71
	v_add_f32_e32 v84, 1.0, v84
	v_rcp_f32_e32 v87, v84
	v_cvt_pk_bf16_f32 v84, v64, v65
	v_pk_mul_f32 v[66:67], v[66:67], v[86:87]
	v_cvt_pk_bf16_f32 v86, v68, v69
	v_cvt_pk_bf16_f32 v87, v66, v67
	global_store_dwordx4 v[82:83], v[84:87], off offset:256
	s_cbranch_vccnz .LBB0_144
	v_pk_mul_f32 v[74:75], v[74:75], v[74:75]
	v_pk_mul_f32 v[68:69], v[68:69], v[68:69]
	v_pk_fma_f32 v[72:73], v[72:73], v[72:73], v[74:75]
	v_pk_mul_f32 v[74:75], v[78:79], v[78:79]
	v_pk_add_f32 v[72:73], v[72:73], v[72:73] op_sel:[0,1] op_sel_hi:[1,0]
	v_pk_fma_f32 v[74:75], v[76:77], v[76:77], v[74:75]
	v_pk_fma_f32 v[64:65], v[64:65], v[64:65], v[68:69]
	v_pk_add_f32 v[72:73], v[74:75], v[72:73]
	v_pk_mul_f32 v[66:67], v[66:67], v[66:67]
	v_pk_add_f32 v[72:73], v[74:75], v[72:73] op_sel:[1,0] op_sel_hi:[0,1]
	v_pk_add_f32 v[68:69], v[64:65], v[72:73]
	v_pk_fma_f32 v[66:67], v[70:71], v[70:71], v[66:67]
	v_pk_add_f32 v[64:65], v[64:65], v[68:69] op_sel:[1,0] op_sel_hi:[0,1]
	v_pk_add_f32 v[64:65], v[66:67], v[64:65]
	s_nop 0
	v_pk_add_f32 v[64:65], v[66:67], v[64:65] op_sel:[1,0] op_sel_hi:[0,1]
	v_mov_b32_e32 v65, v64
	s_nop 1
	v_permlane16_swap_b32_e32 v64, v65
	v_add_f32_e32 v64, v64, v65
	v_mov_b32_e32 v65, v64
	s_nop 1
	v_permlane32_swap_b32_e32 v64, v65
	s_and_saveexec_b64 s[2:3], s[6:7]
	s_cbranch_execz .LBB0_143
	v_lshl_add_u64 v[66:67], v[80:81], 2, s[0:1]
	v_add_f32_e32 v64, v64, v65
	global_atomic_add_f32 v[66:67], v64, off

.LBB0_144:
	v_mov_b32_e32 v68, v195
	v_add_u32_e32 v64, 0x90, v154
	v_ashrrev_i32_e32 v65, 31, v64
	v_lshlrev_b64 v[66:67], 11, v[64:65]
	v_lshl_add_u64 v[66:67], v[158:159], 0, v[66:67]
	s_nop 0
	v_fmamk_f32 v68, v68, 0x3a800000, v225
	v_cmp_gt_f32_e32 vcc, s93, v68
	v_mul_f32_e32 v69, 0x4b800000, v68
	s_nop 0
	v_cndmask_b32_e32 v68, v68, v69, vcc
	v_rsq_f32_e32 v68, v68
	s_nop 0
	v_mul_f32_e32 v69, 0x45800000, v68
	v_cndmask_b32_e32 v68, v68, v69, vcc
	v_pk_fma_f32 v[70:71], v[58:59], v[68:69], v[34:35] op_sel_hi:[1,0,1]
	v_pk_fma_f32 v[58:59], v[56:57], v[68:69], v[32:33] op_sel_hi:[1,0,1]
	v_pk_fma_f32 v[60:61], v[60:61], v[68:69], v[36:37] op_sel_hi:[1,0,1]
	v_mul_f32_e32 v57, 0x3d372713, v58
	v_mul_f32_e32 v57, v58, v57
	v_fma_f32 v57, v58, v57, v58
	v_mul_f32_e32 v57, 0xc0135761, v57
	v_exp_f32_e32 v57, v57
	v_mul_f32_e32 v56, 0x3d372713, v60
	v_mul_f32_e32 v56, v60, v56
	v_fma_f32 v56, v60, v56, v60
	v_add_f32_e32 v57, 1.0, v57
	v_rcp_f32_e32 v72, v57
	v_mul_f32_e32 v57, 0x3d372713, v61
	v_mul_f32_e32 v57, v61, v57
	v_fma_f32 v57, v61, v57, v61
	v_mul_f32_e32 v56, 0xc0135761, v56
	v_mul_f32_e32 v57, 0xc0135761, v57
	v_exp_f32_e32 v56, v56
	v_exp_f32_e32 v57, v57
	v_pk_fma_f32 v[62:63], v[62:63], v[68:69], v[38:39] op_sel_hi:[1,0,1]
	v_pk_fma_f32 v[54:55], v[54:55], v[68:69], v[30:31] op_sel_hi:[1,0,1]
	v_add_f32_e32 v56, 1.0, v56
	v_add_f32_e32 v57, 1.0, v57
	v_rcp_f32_e32 v56, v56
	v_rcp_f32_e32 v57, v57
	v_pk_fma_f32 v[50:51], v[50:51], v[68:69], v[26:27] op_sel_hi:[1,0,1]
	s_and_b64 vcc, exec, s[8:9]
	v_pk_mul_f32 v[56:57], v[60:61], v[56:57]
	v_mul_f32_e32 v60, 0x3d372713, v59
	v_mul_f32_e32 v60, v59, v60
	v_fma_f32 v60, v59, v60, v59
	v_mul_f32_e32 v60, 0xc0135761, v60
	v_exp_f32_e32 v60, v60
	v_mul_f32_e32 v61, 0x3d372713, v70
	v_mul_f32_e32 v61, v70, v61
	v_fma_f32 v61, v70, v61, v70
	v_mul_f32_e32 v61, 0xc0135761, v61
	v_add_f32_e32 v60, 1.0, v60
	v_exp_f32_e32 v61, v61
	v_rcp_f32_e32 v73, v60
	v_mul_f32_e32 v60, 0x3d372713, v62
	v_mul_f32_e32 v60, v62, v60
	v_add_f32_e32 v61, 1.0, v61
	v_pk_mul_f32 v[58:59], v[58:59], v[72:73]
	v_rcp_f32_e32 v72, v61
	v_mul_f32_e32 v61, 0x3d372713, v63
	v_mul_f32_e32 v61, v63, v61
	v_fma_f32 v60, v62, v60, v62
	v_fma_f32 v61, v63, v61, v63
	v_mul_f32_e32 v60, 0xc0135761, v60
	v_mul_f32_e32 v61, 0xc0135761, v61
	v_exp_f32_e32 v60, v60
	v_exp_f32_e32 v61, v61
	v_add_f32_e32 v60, 1.0, v60
	v_add_f32_e32 v61, 1.0, v61
	v_rcp_f32_e32 v60, v60
	v_rcp_f32_e32 v61, v61
	s_nop 0
	v_pk_mul_f32 v[60:61], v[62:63], v[60:61]
	v_mul_f32_e32 v62, 0x3d372713, v71
	v_mul_f32_e32 v62, v71, v62
	v_fma_f32 v62, v71, v62, v71
	v_mul_f32_e32 v62, 0xc0135761, v62
	v_exp_f32_e32 v62, v62
	s_nop 0
	v_add_f32_e32 v62, 1.0, v62
	v_rcp_f32_e32 v73, v62
	s_nop 0
	v_pk_mul_f32 v[62:63], v[70:71], v[72:73]
	v_cvt_pk_bf16_f32 v70, v56, v57
	v_cvt_pk_bf16_f32 v71, v60, v61
	v_cvt_pk_bf16_f32 v72, v58, v59
	v_cvt_pk_bf16_f32 v73, v62, v63
	global_store_dwordx4 v[66:67], v[70:73], off
	s_nop 1
	v_pk_fma_f32 v[70:71], v[52:53], v[68:69], v[28:29] op_sel_hi:[1,0,1]
	v_pk_fma_f32 v[52:53], v[48:49], v[68:69], v[24:25] op_sel_hi:[1,0,1]
	v_mul_f32_e32 v48, 0x3d372713, v70
	v_mul_f32_e32 v49, 0x3d372713, v52
	v_mul_f32_e32 v69, 0x3d372713, v53
	v_mul_f32_e32 v49, v52, v49
	v_mul_f32_e32 v69, v53, v69
	v_fma_f32 v49, v52, v49, v52
	v_fma_f32 v69, v53, v69, v53
	v_mul_f32_e32 v49, 0xc0135761, v49
	v_mul_f32_e32 v69, 0xc0135761, v69
	v_exp_f32_e32 v49, v49
	v_exp_f32_e32 v69, v69
	v_mul_f32_e32 v48, v70, v48
	v_fma_f32 v48, v70, v48, v70
	v_add_f32_e32 v49, 1.0, v49
	v_add_f32_e32 v69, 1.0, v69
	v_rcp_f32_e32 v68, v49
	v_mul_f32_e32 v49, 0x3d372713, v71
	v_rcp_f32_e32 v69, v69
	v_mul_f32_e32 v49, v71, v49
	v_fma_f32 v49, v71, v49, v71
	v_mul_f32_e32 v48, 0xc0135761, v48
	v_mul_f32_e32 v49, 0xc0135761, v49
	v_exp_f32_e32 v48, v48
	v_exp_f32_e32 v49, v49
	v_pk_mul_f32 v[52:53], v[52:53], v[68:69]
	v_mul_f32_e32 v69, 0x3d372713, v50
	v_mul_f32_e32 v69, v50, v69
	v_fma_f32 v69, v50, v69, v50
	v_mul_f32_e32 v69, 0xc0135761, v69
	v_add_f32_e32 v48, 1.0, v48
	v_add_f32_e32 v49, 1.0, v49
	v_exp_f32_e32 v69, v69
	v_rcp_f32_e32 v48, v48
	v_rcp_f32_e32 v49, v49
	v_mul_f32_e32 v68, 0x3d372713, v54
	v_add_f32_e32 v69, 1.0, v69
	v_mul_f32_e32 v68, v54, v68
	v_pk_mul_f32 v[48:49], v[70:71], v[48:49]
	v_rcp_f32_e32 v70, v69
	v_mul_f32_e32 v69, 0x3d372713, v55
	v_mul_f32_e32 v69, v55, v69
	v_fma_f32 v68, v54, v68, v54
	v_fma_f32 v69, v55, v69, v55
	v_mul_f32_e32 v68, 0xc0135761, v68
	v_mul_f32_e32 v69, 0xc0135761, v69
	v_exp_f32_e32 v68, v68
	v_exp_f32_e32 v69, v69
	v_add_f32_e32 v68, 1.0, v68
	v_add_f32_e32 v69, 1.0, v69
	v_rcp_f32_e32 v68, v68
	v_rcp_f32_e32 v69, v69
	s_nop 0
	v_pk_mul_f32 v[54:55], v[54:55], v[68:69]
	v_mul_f32_e32 v68, 0x3d372713, v51
	v_mul_f32_e32 v68, v51, v68
	v_fma_f32 v68, v51, v68, v51
	v_mul_f32_e32 v68, 0xc0135761, v68
	v_exp_f32_e32 v68, v68
	v_cvt_pk_bf16_f32 v69, v54, v55
	v_add_f32_e32 v68, 1.0, v68
	v_rcp_f32_e32 v71, v68
	v_cvt_pk_bf16_f32 v68, v48, v49
	v_pk_mul_f32 v[50:51], v[50:51], v[70:71]
	v_cvt_pk_bf16_f32 v70, v52, v53
	v_cvt_pk_bf16_f32 v71, v50, v51
	global_store_dwordx4 v[66:67], v[68:71], off offset:256
	s_cbranch_vccnz .LBB0_148
	v_pk_mul_f32 v[58:59], v[58:59], v[58:59]
	v_pk_mul_f32 v[52:53], v[52:53], v[52:53]
	v_pk_fma_f32 v[56:57], v[56:57], v[56:57], v[58:59]
	v_pk_mul_f32 v[58:59], v[62:63], v[62:63]
	v_pk_add_f32 v[56:57], v[56:57], v[56:57] op_sel:[0,1] op_sel_hi:[1,0]
	v_pk_fma_f32 v[58:59], v[60:61], v[60:61], v[58:59]
	v_pk_fma_f32 v[48:49], v[48:49], v[48:49], v[52:53]
	v_pk_add_f32 v[56:57], v[58:59], v[56:57]
	v_pk_mul_f32 v[50:51], v[50:51], v[50:51]
	v_pk_add_f32 v[56:57], v[58:59], v[56:57] op_sel:[1,0] op_sel_hi:[0,1]
	v_pk_add_f32 v[52:53], v[48:49], v[56:57]
	v_pk_fma_f32 v[50:51], v[54:55], v[54:55], v[50:51]
	v_pk_add_f32 v[48:49], v[48:49], v[52:53] op_sel:[1,0] op_sel_hi:[0,1]
	v_pk_add_f32 v[48:49], v[50:51], v[48:49]
	s_nop 0
	v_pk_add_f32 v[48:49], v[50:51], v[48:49] op_sel:[1,0] op_sel_hi:[0,1]
	v_mov_b32_e32 v49, v48
	s_nop 1
	v_permlane16_swap_b32_e32 v48, v49
	v_add_f32_e32 v48, v48, v49
	v_mov_b32_e32 v49, v48
	s_nop 1
	v_permlane32_swap_b32_e32 v48, v49
	s_and_saveexec_b64 s[2:3], s[6:7]
	s_cbranch_execz .LBB0_147
	v_lshl_add_u64 v[50:51], v[64:65], 2, s[0:1]
	v_add_f32_e32 v48, v48, v49
	global_atomic_add_f32 v[50:51], v48, off

.LBB0_148:
	v_mov_b32_e32 v52, v196
	v_add_u32_e32 v48, 0xa0, v154
	v_ashrrev_i32_e32 v49, 31, v48
	v_lshlrev_b64 v[50:51], 11, v[48:49]
	v_lshl_add_u64 v[50:51], v[158:159], 0, v[50:51]
	s_nop 0
	v_fmamk_f32 v52, v52, 0x3a800000, v225
	v_cmp_gt_f32_e32 vcc, s93, v52
	v_mul_f32_e32 v53, 0x4b800000, v52
	s_nop 0
	v_cndmask_b32_e32 v52, v52, v53, vcc
	v_rsq_f32_e32 v52, v52
	s_nop 0
	v_mul_f32_e32 v53, 0x45800000, v52
	v_cndmask_b32_e32 v52, v52, v53, vcc
	v_pk_fma_f32 v[54:55], v[42:43], v[52:53], v[34:35] op_sel_hi:[1,0,1]
	v_pk_fma_f32 v[42:43], v[40:41], v[52:53], v[32:33] op_sel_hi:[1,0,1]
	v_pk_fma_f32 v[44:45], v[44:45], v[52:53], v[36:37] op_sel_hi:[1,0,1]
	v_mul_f32_e32 v41, 0x3d372713, v42
	v_mul_f32_e32 v41, v42, v41
	v_fma_f32 v41, v42, v41, v42
	v_mul_f32_e32 v41, 0xc0135761, v41
	v_exp_f32_e32 v41, v41
	v_mul_f32_e32 v40, 0x3d372713, v44
	v_mul_f32_e32 v40, v44, v40
	v_fma_f32 v40, v44, v40, v44
	v_add_f32_e32 v41, 1.0, v41
	v_rcp_f32_e32 v56, v41
	v_mul_f32_e32 v41, 0x3d372713, v45
	v_mul_f32_e32 v41, v45, v41
	v_fma_f32 v41, v45, v41, v45
	v_mul_f32_e32 v40, 0xc0135761, v40
	v_mul_f32_e32 v41, 0xc0135761, v41
	v_exp_f32_e32 v40, v40
	v_exp_f32_e32 v41, v41
	v_pk_fma_f32 v[46:47], v[46:47], v[52:53], v[38:39] op_sel_hi:[1,0,1]
	v_pk_fma_f32 v[22:23], v[22:23], v[52:53], v[30:31] op_sel_hi:[1,0,1]
	v_add_f32_e32 v40, 1.0, v40
	v_add_f32_e32 v41, 1.0, v41
	v_rcp_f32_e32 v40, v40
	v_rcp_f32_e32 v41, v41
	v_pk_fma_f32 v[18:19], v[18:19], v[52:53], v[26:27] op_sel_hi:[1,0,1]
	s_and_b64 vcc, exec, s[8:9]
	v_pk_mul_f32 v[40:41], v[44:45], v[40:41]
	v_mul_f32_e32 v44, 0x3d372713, v43
	v_mul_f32_e32 v44, v43, v44
	v_fma_f32 v44, v43, v44, v43
	v_mul_f32_e32 v44, 0xc0135761, v44
	v_exp_f32_e32 v44, v44
	v_mul_f32_e32 v45, 0x3d372713, v54
	v_mul_f32_e32 v45, v54, v45
	v_fma_f32 v45, v54, v45, v54
	v_mul_f32_e32 v45, 0xc0135761, v45
	v_add_f32_e32 v44, 1.0, v44
	v_exp_f32_e32 v45, v45
	v_rcp_f32_e32 v57, v44
	v_mul_f32_e32 v44, 0x3d372713, v46
	v_mul_f32_e32 v44, v46, v44
	v_add_f32_e32 v45, 1.0, v45
	v_pk_mul_f32 v[42:43], v[42:43], v[56:57]
	v_rcp_f32_e32 v56, v45
	v_mul_f32_e32 v45, 0x3d372713, v47
	v_mul_f32_e32 v45, v47, v45
	v_fma_f32 v44, v46, v44, v46
	v_fma_f32 v45, v47, v45, v47
	v_mul_f32_e32 v44, 0xc0135761, v44
	v_mul_f32_e32 v45, 0xc0135761, v45
	v_exp_f32_e32 v44, v44
	v_exp_f32_e32 v45, v45
	v_add_f32_e32 v44, 1.0, v44
	v_add_f32_e32 v45, 1.0, v45
	v_rcp_f32_e32 v44, v44
	v_rcp_f32_e32 v45, v45
	s_nop 0
	v_pk_mul_f32 v[44:45], v[46:47], v[44:45]
	v_mul_f32_e32 v46, 0x3d372713, v55
	v_mul_f32_e32 v46, v55, v46
	v_fma_f32 v46, v55, v46, v55
	v_mul_f32_e32 v46, 0xc0135761, v46
	v_exp_f32_e32 v46, v46
	s_nop 0
	v_add_f32_e32 v46, 1.0, v46
	v_rcp_f32_e32 v57, v46
	s_nop 0
	v_pk_mul_f32 v[46:47], v[54:55], v[56:57]
	v_cvt_pk_bf16_f32 v54, v40, v41
	v_cvt_pk_bf16_f32 v55, v44, v45
	v_cvt_pk_bf16_f32 v56, v42, v43
	v_cvt_pk_bf16_f32 v57, v46, v47
	global_store_dwordx4 v[50:51], v[54:57], off
	s_nop 1
	v_pk_fma_f32 v[54:55], v[20:21], v[52:53], v[28:29] op_sel_hi:[1,0,1]
	v_pk_fma_f32 v[20:21], v[16:17], v[52:53], v[24:25] op_sel_hi:[1,0,1]
	v_mul_f32_e32 v16, 0x3d372713, v54
	v_mul_f32_e32 v17, 0x3d372713, v20
	v_mul_f32_e32 v53, 0x3d372713, v21
	v_mul_f32_e32 v17, v20, v17
	v_mul_f32_e32 v53, v21, v53
	v_fma_f32 v17, v20, v17, v20
	v_fma_f32 v53, v21, v53, v21
	v_mul_f32_e32 v17, 0xc0135761, v17
	v_mul_f32_e32 v53, 0xc0135761, v53
	v_exp_f32_e32 v17, v17
	v_exp_f32_e32 v53, v53
	v_mul_f32_e32 v16, v54, v16
	v_fma_f32 v16, v54, v16, v54
	v_add_f32_e32 v17, 1.0, v17
	v_add_f32_e32 v53, 1.0, v53
	v_rcp_f32_e32 v52, v17
	v_mul_f32_e32 v17, 0x3d372713, v55
	v_rcp_f32_e32 v53, v53
	v_mul_f32_e32 v17, v55, v17
	v_fma_f32 v17, v55, v17, v55
	v_mul_f32_e32 v16, 0xc0135761, v16
	v_mul_f32_e32 v17, 0xc0135761, v17
	v_exp_f32_e32 v16, v16
	v_exp_f32_e32 v17, v17
	v_pk_mul_f32 v[20:21], v[20:21], v[52:53]
	v_mul_f32_e32 v53, 0x3d372713, v18
	v_mul_f32_e32 v53, v18, v53
	v_fma_f32 v53, v18, v53, v18
	v_mul_f32_e32 v53, 0xc0135761, v53
	v_add_f32_e32 v16, 1.0, v16
	v_add_f32_e32 v17, 1.0, v17
	v_exp_f32_e32 v53, v53
	v_rcp_f32_e32 v16, v16
	v_rcp_f32_e32 v17, v17
	v_mul_f32_e32 v52, 0x3d372713, v22
	v_add_f32_e32 v53, 1.0, v53
	v_mul_f32_e32 v52, v22, v52
	v_pk_mul_f32 v[16:17], v[54:55], v[16:17]
	v_rcp_f32_e32 v54, v53
	v_mul_f32_e32 v53, 0x3d372713, v23
	v_mul_f32_e32 v53, v23, v53
	v_fma_f32 v52, v22, v52, v22
	v_fma_f32 v53, v23, v53, v23
	v_mul_f32_e32 v52, 0xc0135761, v52
	v_mul_f32_e32 v53, 0xc0135761, v53
	v_exp_f32_e32 v52, v52
	v_exp_f32_e32 v53, v53
	v_add_f32_e32 v52, 1.0, v52
	v_add_f32_e32 v53, 1.0, v53
	v_rcp_f32_e32 v52, v52
	v_rcp_f32_e32 v53, v53
	s_nop 0
	v_pk_mul_f32 v[22:23], v[22:23], v[52:53]
	v_mul_f32_e32 v52, 0x3d372713, v19
	v_mul_f32_e32 v52, v19, v52
	v_fma_f32 v52, v19, v52, v19
	v_mul_f32_e32 v52, 0xc0135761, v52
	v_exp_f32_e32 v52, v52
	v_cvt_pk_bf16_f32 v53, v22, v23
	v_add_f32_e32 v52, 1.0, v52
	v_rcp_f32_e32 v55, v52
	v_cvt_pk_bf16_f32 v52, v16, v17
	v_pk_mul_f32 v[18:19], v[18:19], v[54:55]
	v_cvt_pk_bf16_f32 v54, v20, v21
	v_cvt_pk_bf16_f32 v55, v18, v19
	global_store_dwordx4 v[50:51], v[52:55], off offset:256
	s_cbranch_vccnz .LBB0_152
	v_pk_mul_f32 v[42:43], v[42:43], v[42:43]
	v_pk_mul_f32 v[20:21], v[20:21], v[20:21]
	v_pk_fma_f32 v[40:41], v[40:41], v[40:41], v[42:43]
	v_pk_mul_f32 v[42:43], v[46:47], v[46:47]
	v_pk_add_f32 v[40:41], v[40:41], v[40:41] op_sel:[0,1] op_sel_hi:[1,0]
	v_pk_fma_f32 v[42:43], v[44:45], v[44:45], v[42:43]
	v_pk_fma_f32 v[16:17], v[16:17], v[16:17], v[20:21]
	v_pk_add_f32 v[40:41], v[42:43], v[40:41]
	v_pk_mul_f32 v[18:19], v[18:19], v[18:19]
	v_pk_add_f32 v[40:41], v[42:43], v[40:41] op_sel:[1,0] op_sel_hi:[0,1]
	v_pk_add_f32 v[20:21], v[16:17], v[40:41]
	v_pk_fma_f32 v[18:19], v[22:23], v[22:23], v[18:19]
	v_pk_add_f32 v[16:17], v[16:17], v[20:21] op_sel:[1,0] op_sel_hi:[0,1]
	v_pk_add_f32 v[16:17], v[18:19], v[16:17]
	s_nop 0
	v_pk_add_f32 v[16:17], v[18:19], v[16:17] op_sel:[1,0] op_sel_hi:[0,1]
	v_mov_b32_e32 v17, v16
	s_nop 1
	v_permlane16_swap_b32_e32 v16, v17
	v_add_f32_e32 v16, v16, v17
	v_mov_b32_e32 v17, v16
	s_nop 1
	v_permlane32_swap_b32_e32 v16, v17
	s_and_saveexec_b64 s[2:3], s[6:7]
	s_cbranch_execz .LBB0_151
	v_lshl_add_u64 v[18:19], v[48:49], 2, s[0:1]
	v_add_f32_e32 v16, v16, v17
	global_atomic_add_f32 v[18:19], v16, off

.LBB0_152:
	v_mov_b32_e32 v17, v197
	v_add_u32_e32 v16, 0xb0, v154
	s_nop 0
	v_fmamk_f32 v17, v17, 0x3a800000, v225
	v_mul_f32_e32 v18, 0x4b800000, v17
	v_cmp_gt_f32_e32 vcc, s93, v17
	s_nop 1
	v_cndmask_b32_e32 v17, v17, v18, vcc
	v_rsq_f32_e32 v20, v17
	v_ashrrev_i32_e32 v17, 31, v16
	v_lshlrev_b64 v[18:19], 11, v[16:17]
	v_lshl_add_u64 v[18:19], v[158:159], 0, v[18:19]
	v_mul_f32_e32 v21, 0x45800000, v20
	v_cndmask_b32_e32 v20, v20, v21, vcc
	v_pk_fma_f32 v[14:15], v[14:15], v[20:21], v[38:39] op_sel_hi:[1,0,1]
	v_pk_fma_f32 v[12:13], v[12:13], v[20:21], v[36:37] op_sel_hi:[1,0,1]
	v_pk_fma_f32 v[10:11], v[10:11], v[20:21], v[34:35] op_sel_hi:[1,0,1]
	v_pk_fma_f32 v[8:9], v[8:9], v[20:21], v[32:33] op_sel_hi:[1,0,1]
	v_pk_fma_f32 v[22:23], v[6:7], v[20:21], v[30:31] op_sel_hi:[1,0,1]
	v_pk_fma_f32 v[28:29], v[4:5], v[20:21], v[28:29] op_sel_hi:[1,0,1]
	v_pk_fma_f32 v[26:27], v[2:3], v[20:21], v[26:27] op_sel_hi:[1,0,1]
	v_pk_fma_f32 v[20:21], v[0:1], v[20:21], v[24:25] op_sel_hi:[1,0,1]
	v_mul_f32_e32 v0, 0x3d372713, v12
	v_mul_f32_e32 v1, 0x3d372713, v8
	v_mul_f32_e32 v2, 0x3d372713, v13
	v_mul_f32_e32 v3, 0x3d372713, v9
	v_mul_f32_e32 v4, 0x3d372713, v14
	v_mul_f32_e32 v5, 0x3d372713, v10
	v_mul_f32_e32 v6, 0x3d372713, v15
	v_mul_f32_e32 v7, 0x3d372713, v11
	v_mul_f32_e32 v24, 0x3d372713, v28
	v_mul_f32_e32 v25, 0x3d372713, v20
	v_mul_f32_e32 v0, v12, v0
	v_mul_f32_e32 v1, v8, v1
	v_mul_f32_e32 v2, v13, v2
	v_mul_f32_e32 v3, v9, v3
	v_mul_f32_e32 v4, v14, v4
	v_mul_f32_e32 v5, v10, v5
	v_mul_f32_e32 v6, v15, v6
	v_mul_f32_e32 v7, v11, v7
	v_mul_f32_e32 v24, v28, v24
	v_mul_f32_e32 v25, v20, v25
	v_fma_f32 v0, v12, v0, v12
	v_fma_f32 v1, v8, v1, v8
	v_fma_f32 v2, v13, v2, v13
	v_fma_f32 v3, v9, v3, v9
	v_fma_f32 v4, v14, v4, v14
	v_fma_f32 v5, v10, v5, v10
	v_fma_f32 v6, v15, v6, v15
	v_fma_f32 v7, v11, v7, v11
	v_fma_f32 v24, v28, v24, v28
	v_fma_f32 v25, v20, v25, v20
	v_mul_f32_e32 v0, 0xc0135761, v0
	v_mul_f32_e32 v1, 0xc0135761, v1
	v_mul_f32_e32 v2, 0xc0135761, v2
	v_mul_f32_e32 v3, 0xc0135761, v3
	v_mul_f32_e32 v4, 0xc0135761, v4
	v_mul_f32_e32 v5, 0xc0135761, v5
	v_mul_f32_e32 v6, 0xc0135761, v6
	v_mul_f32_e32 v7, 0xc0135761, v7
	v_mul_f32_e32 v30, 0x3d372713, v29
	v_mul_f32_e32 v24, 0xc0135761, v24
	v_mul_f32_e32 v25, 0xc0135761, v25
	v_exp_f32_e32 v0, v0
	v_exp_f32_e32 v1, v1
	v_exp_f32_e32 v2, v2
	v_exp_f32_e32 v3, v3
	v_exp_f32_e32 v4, v4
	v_exp_f32_e32 v5, v5
	v_exp_f32_e32 v6, v6
	v_exp_f32_e32 v7, v7
	v_mul_f32_e32 v30, v29, v30
	v_exp_f32_e32 v24, v24
	v_exp_f32_e32 v25, v25
	v_mul_f32_e32 v31, 0x3d372713, v21
	v_fma_f32 v30, v29, v30, v29
	v_mul_f32_e32 v31, v21, v31
	v_mul_f32_e32 v30, 0xc0135761, v30
	v_fma_f32 v33, v21, v31, v21
	v_exp_f32_e32 v34, v30
	v_add_f32_e32 v0, 1.0, v0
	v_add_f32_e32 v1, 1.0, v1
	v_add_f32_e32 v2, 1.0, v2
	v_add_f32_e32 v3, 1.0, v3
	v_add_f32_e32 v30, 1.0, v4
	v_add_f32_e32 v31, 1.0, v5
	v_add_f32_e32 v6, 1.0, v6
	v_add_f32_e32 v7, 1.0, v7
	v_add_f32_e32 v32, 1.0, v24
	v_add_f32_e32 v35, 1.0, v25
	v_rcp_f32_e32 v0, v0
	v_rcp_f32_e32 v4, v1
	v_rcp_f32_e32 v1, v2
	v_rcp_f32_e32 v5, v3
	v_rcp_f32_e32 v24, v30
	v_rcp_f32_e32 v30, v31
	v_rcp_f32_e32 v25, v6
	v_rcp_f32_e32 v31, v7
	v_pk_mul_f32 v[2:3], v[12:13], v[0:1]
	v_pk_mul_f32 v[6:7], v[8:9], v[4:5]
	v_pk_mul_f32 v[0:1], v[14:15], v[24:25]
	v_pk_mul_f32 v[4:5], v[10:11], v[30:31]
	v_cvt_pk_bf16_f32 v8, v2, v3
	v_cvt_pk_bf16_f32 v9, v0, v1
	v_cvt_pk_bf16_f32 v10, v6, v7
	v_cvt_pk_bf16_f32 v11, v4, v5
	global_store_dwordx4 v[18:19], v[8:11], off
	v_mul_f32_e32 v12, 0x3d372713, v27
	v_mul_f32_e32 v12, v27, v12
	v_add_f32_e32 v10, 1.0, v34
	v_mul_f32_e32 v8, 0xc0135761, v33
	v_rcp_f32_e32 v33, v10
	v_mul_f32_e32 v10, 0x3d372713, v22
	v_mul_f32_e32 v10, v22, v10
	v_mul_f32_e32 v11, 0x3d372713, v26
	v_fma_f32 v10, v22, v10, v22
	v_mul_f32_e32 v11, v26, v11
	v_mul_f32_e32 v10, 0xc0135761, v10
	v_fma_f32 v11, v26, v11, v26
	v_exp_f32_e32 v10, v10
	v_mul_f32_e32 v11, 0xc0135761, v11
	v_exp_f32_e32 v11, v11
	v_fma_f32 v12, v27, v12, v27
	v_add_f32_e32 v10, 1.0, v10
	v_rcp_f32_e32 v14, v10
	v_add_f32_e32 v10, 1.0, v11
	v_mul_f32_e32 v11, 0x3d372713, v23
	v_mul_f32_e32 v11, v23, v11
	v_fma_f32 v11, v23, v11, v23
	v_mul_f32_e32 v11, 0xc0135761, v11
	v_exp_f32_e32 v11, v11
	v_mul_f32_e32 v12, 0xc0135761, v12
	v_exp_f32_e32 v9, v8
	v_exp_f32_e32 v12, v12
	v_rcp_f32_e32 v24, v10
	v_add_f32_e32 v10, 1.0, v11
	v_add_f32_e32 v9, 1.0, v9
	v_rcp_f32_e32 v15, v10
	v_add_f32_e32 v10, 1.0, v12
	v_rcp_f32_e32 v32, v32
	v_rcp_f32_e32 v8, v35
	v_rcp_f32_e32 v9, v9
	v_rcp_f32_e32 v25, v10
	v_pk_mul_f32 v[10:11], v[28:29], v[32:33]
	s_and_b64 vcc, exec, s[8:9]
	v_pk_mul_f32 v[12:13], v[20:21], v[8:9]
	v_pk_mul_f32 v[8:9], v[22:23], v[14:15]
	v_pk_mul_f32 v[14:15], v[26:27], v[24:25]
	v_cvt_pk_bf16_f32 v20, v10, v11
	v_cvt_pk_bf16_f32 v21, v8, v9
	v_cvt_pk_bf16_f32 v22, v12, v13
	v_cvt_pk_bf16_f32 v23, v14, v15
	global_store_dwordx4 v[18:19], v[20:23], off offset:256
	s_cbranch_vccnz .LBB0_119
	v_pk_mul_f32 v[6:7], v[6:7], v[6:7]
	v_pk_mul_f32 v[4:5], v[4:5], v[4:5]
	v_pk_fma_f32 v[2:3], v[2:3], v[2:3], v[6:7]
	v_pk_fma_f32 v[0:1], v[0:1], v[0:1], v[4:5]
	v_pk_add_f32 v[2:3], v[2:3], v[2:3] op_sel:[0,1] op_sel_hi:[1,0]
	s_nop 0
	v_pk_add_f32 v[2:3], v[0:1], v[2:3]
	s_nop 0
	v_pk_add_f32 v[0:1], v[0:1], v[2:3] op_sel:[1,0] op_sel_hi:[0,1]
	v_pk_mul_f32 v[2:3], v[12:13], v[12:13]
	s_nop 0
	v_pk_fma_f32 v[2:3], v[10:11], v[10:11], v[2:3]
	s_nop 0
	v_pk_add_f32 v[0:1], v[2:3], v[0:1]
	s_nop 0
	v_pk_add_f32 v[0:1], v[2:3], v[0:1] op_sel:[1,0] op_sel_hi:[0,1]
	v_pk_mul_f32 v[2:3], v[14:15], v[14:15]
	s_nop 0
	v_pk_fma_f32 v[2:3], v[8:9], v[8:9], v[2:3]
	s_nop 0
	v_pk_add_f32 v[0:1], v[2:3], v[0:1]
	s_nop 0
	v_pk_add_f32 v[0:1], v[2:3], v[0:1] op_sel:[1,0] op_sel_hi:[0,1]
	v_mov_b32_e32 v1, v0
	s_nop 1
	v_permlane16_swap_b32_e32 v0, v1
	v_add_f32_e32 v0, v0, v1
	v_mov_b32_e32 v1, v0
	s_nop 1
	v_permlane32_swap_b32_e32 v0, v1
	s_and_saveexec_b64 s[2:3], s[6:7]
	s_cbranch_execz .LBB0_118
	v_lshl_add_u64 v[2:3], v[16:17], 2, s[0:1]
	v_add_f32_e32 v0, v0, v1
	global_atomic_add_f32 v[2:3], v0, off
	s_branch .LBB0_118

.LBB0_599:
	s_or_b64 exec, exec, s[0:1]
	v_readlane_b32 s0, v254, 44
	v_add_u32_e32 v1, 0xffffff80, v1
	v_add_u32_e32 v134, v2, v139
	v_mov_b32_e32 v4, s0
	ds_read_b64 v[4:5], v4
	v_ashrrev_i32_e32 v1, 5, v1
	v_ashrrev_i32_e32 v135, 31, v134
	v_cndmask_b32_e64 v1, v1, 0, s[70:71]
	v_and_b32_e32 v16, 7, v0
	v_lshlrev_b64 v[2:3], 10, v[134:135]
	v_add_u32_e32 v136, v1, v144
	v_lshl_add_u64 v[2:3], s[88:89], 0, v[2:3]
	v_lshlrev_b32_e32 v168, 7, v16
	v_ashrrev_i32_e32 v137, 31, v136
	v_lshl_add_u64 v[2:3], v[2:3], 0, v[168:169]
	v_mov_b32_e32 v129, v169
	s_waitcnt lgkmcnt(0)
	v_readfirstlane_b32 s1, v5
	v_readfirstlane_b32 s0, v4
	v_lshlrev_b64 v[4:5], 12, v[136:137]
	v_lshl_add_u64 v[2:3], v[2:3], 0, v[128:129]
	v_lshlrev_b32_e32 v1, 2, v16
	v_lshl_add_u64 v[6:7], v[132:133], 0, v[4:5]
	v_lshlrev_b32_e32 v168, 1, v124
	v_lshl_add_u64 v[4:5], v[130:131], 0, v[4:5]
	global_load_dwordx4 v[48:51], v[2:3], off
	global_load_dwordx4 v[52:55], v[2:3], off offset:32
	global_load_dword v38, v1, s[0:1]
	v_lshl_add_u64 v[4:5], v[4:5], 0, v[168:169]
	v_lshl_add_u64 v[6:7], v[6:7], 0, v[168:169]
	global_load_dwordx4 v[112:115], v[4:5], off offset:3072
	global_load_dwordx4 v[116:119], v[4:5], off offset:2048
	global_load_dwordx4 v[120:123], v[4:5], off offset:1024
	global_load_dwordx4 v[32:35], v[4:5], off
	global_load_dwordx4 v[64:67], v[6:7], off offset:3072
	global_load_dwordx4 v[72:75], v[6:7], off offset:2048
	global_load_dwordx4 v[68:71], v[6:7], off offset:1024
	global_load_dwordx4 v[76:79], v[6:7], off
	global_load_dwordx4 v[56:59], v[2:3], off offset:64
	global_load_dwordx4 v[60:63], v[2:3], off offset:96
	v_lshlrev_b32_e32 v17, 2, v0
	v_and_b32_e32 v37, 16, v17
	v_lshl_or_b32 v36, v36, 5, v37
	v_add_u32_e32 v18, 16, v127
	v_mov_b32_e32 v14, v169
	v_mov_b32_e32 v15, v169
	v_ashrrev_i32_e32 v37, 31, v36
	v_mov_b32_e32 v0, v169
	v_mov_b32_e32 v1, v169
	v_mov_b32_e32 v2, v169
	v_mov_b32_e32 v3, v169
	v_mov_b32_e32 v4, v169
	v_mov_b32_e32 v5, v169
	v_mov_b32_e32 v6, v169
	v_mov_b32_e32 v7, v169
	v_mov_b32_e32 v8, v169
	v_mov_b32_e32 v9, v169
	v_mov_b32_e32 v10, v169
	v_mov_b32_e32 v11, v169
	v_mov_b32_e32 v12, v169
	v_mov_b32_e32 v13, v169
	v_lshlrev_b32_e32 v138, 6, v16
	v_cndmask_b32_e64 v145, v18, v127, s[70:71]
	v_mov_b64_e32 v[30:31], v[14:15]
	v_lshlrev_b64 v[36:37], 12, v[36:37]
	s_mov_b32 s92, 1
	v_sub_u32_e32 v129, 0, v127
	v_mov_b32_e32 v137, 1.0
	s_mov_b64 s[2:3], 0
	v_mov_b64_e32 v[28:29], v[12:13]
	v_mov_b64_e32 v[26:27], v[10:11]
	v_mov_b64_e32 v[24:25], v[8:9]
	v_mov_b64_e32 v[22:23], v[6:7]
	v_mov_b64_e32 v[20:21], v[4:5]
	v_mov_b64_e32 v[18:19], v[2:3]
	v_mov_b64_e32 v[16:17], v[0:1]
	v_sub_u32_e32 v146, 0, v145
	v_lshl_add_u64 v[140:141], s[82:83], 0, v[36:37]
	v_lshl_add_u64 v[142:143], s[80:81], 0, v[36:37]
	s_waitcnt vmcnt(9)
	v_mov_b64_e32 v[92:93], v[112:113]
	s_waitcnt vmcnt(8)
	v_mov_b64_e32 v[88:89], v[116:117]
	s_waitcnt vmcnt(7)
	v_mov_b64_e32 v[84:85], v[120:121]
	s_waitcnt vmcnt(6)
	v_mov_b64_e32 v[82:83], v[34:35]
	s_waitcnt vmcnt(5)
	v_mov_b64_e32 v[106:107], v[66:67]
	s_waitcnt vmcnt(4)
	v_mov_b64_e32 v[110:111], v[74:75]
	s_waitcnt vmcnt(3)
	v_mov_b64_e32 v[98:99], v[70:71]
	s_waitcnt vmcnt(0)
	v_mov_b64_e32 v[102:103], v[78:79]
	v_mul_f32_e32 v147, 0x3fb8aa3b, v38
	v_mov_b64_e32 v[94:95], v[114:115]
	v_mov_b64_e32 v[90:91], v[118:119]
	v_mov_b64_e32 v[86:87], v[122:123]
	v_mov_b64_e32 v[80:81], v[32:33]
	v_mov_b64_e32 v[104:105], v[64:65]
	v_mov_b64_e32 v[108:109], v[72:73]
	v_mov_b64_e32 v[96:97], v[68:69]
	v_mov_b64_e32 v[100:101], v[76:77]
	s_branch .LBB0_601
.LBB0_600:
	v_fma_f32 v32, v32, s33, -v147
	v_exp_f32_e32 v32, v32
	v_fma_f32 v33, v33, s33, -v147
	v_exp_f32_e32 v33, v33
	v_fma_f32 v34, v34, s33, -v147
	v_exp_f32_e32 v34, v34
	v_fma_f32 v35, v35, s33, -v147
	v_exp_f32_e32 v35, v35
	v_fma_f32 v36, v36, s33, -v147
	v_add_f32_e32 v112, 0, v32
	v_exp_f32_e32 v36, v36
	v_fma_f32 v37, v37, s33, -v147
	v_add_f32_e32 v112, v33, v112
	v_exp_f32_e32 v37, v37
	v_fma_f32 v38, v38, s33, -v147
	v_add_f32_e32 v112, v34, v112
	v_exp_f32_e32 v38, v38
	v_fma_f32 v39, v39, s33, -v147
	v_add_f32_e32 v112, v35, v112
	v_exp_f32_e32 v39, v39
	v_fma_f32 v40, v40, s33, -v147
	v_add_f32_e32 v112, v36, v112
	v_exp_f32_e32 v40, v40
	v_fma_f32 v41, v41, s33, -v147
	v_add_f32_e32 v112, v37, v112
	v_exp_f32_e32 v41, v41
	v_fma_f32 v42, v42, s33, -v147
	v_add_f32_e32 v112, v38, v112
	v_exp_f32_e32 v42, v42
	v_fma_f32 v43, v43, s33, -v147
	v_add_f32_e32 v112, v39, v112
	v_exp_f32_e32 v43, v43
	v_fma_f32 v44, v44, s33, -v147
	v_add_f32_e32 v112, v40, v112
	v_exp_f32_e32 v44, v44
	v_fma_f32 v45, v45, s33, -v147
	v_add_f32_e32 v112, v41, v112
	v_exp_f32_e32 v45, v45
	v_fma_f32 v46, v46, s33, -v147
	v_add_f32_e32 v112, v42, v112
	v_exp_f32_e32 v46, v46
	v_fma_f32 v47, v47, s33, -v147
	v_add_f32_e32 v112, v43, v112
	v_exp_f32_e32 v47, v47
	v_add_f32_e32 v112, v44, v112
	v_add_f32_e32 v112, v45, v112
	v_add_f32_e32 v112, v46, v112
	v_add_f32_e32 v112, v47, v112
	v_mov_b32_e32 v113, v112
	s_nop 1
	v_permlane32_swap_b32_e32 v112, v113
	v_add_f32_e32 v112, v112, v113
	v_cvt_pk_bf16_f32 v32, v32, v33
	v_cvt_pk_bf16_f32 v33, v34, v35
	v_cvt_pk_bf16_f32 v34, v36, v37
	v_cvt_pk_bf16_f32 v35, v38, v39
	s_setprio 1
	s_nop 0
	v_mfma_f32_32x32x16_bf16 v[16:31], v[76:79], v[32:35], v[16:31]
	v_mfma_f32_32x32x16_bf16 v[0:15], v[72:75], v[32:35], v[0:15]
	s_setprio 0
	v_cvt_pk_bf16_f32 v32, v40, v41
	v_cvt_pk_bf16_f32 v33, v42, v43
	v_cvt_pk_bf16_f32 v34, v44, v45
	v_cvt_pk_bf16_f32 v35, v46, v47
	s_setprio 1
	s_nop 0
	v_mfma_f32_32x32x16_bf16 v[16:31], v[68:71], v[32:35], v[16:31]
	v_mfma_f32_32x32x16_bf16 v[0:15], v[64:67], v[32:35], v[0:15]
	s_setprio 0
	s_add_i32 s92, s92, 1
	v_add_u32_e32 v32, s92, v146
	v_add_f32_e32 v137, v137, v112
	v_cmp_eq_u32_e32 vcc, 1, v32
	s_waitcnt vmcnt(0)
	v_mov_b64_e32 v[114:115], v[94:95]
	v_mov_b64_e32 v[118:119], v[90:91]
	v_mov_b64_e32 v[122:123], v[86:87]
	v_mov_b64_e32 v[32:33], v[80:81]
	v_mov_b64_e32 v[64:65], v[104:105]
	v_mov_b64_e32 v[72:73], v[108:109]
	v_mov_b64_e32 v[68:69], v[96:97]
	v_mov_b64_e32 v[76:77], v[100:101]
	s_or_b64 s[2:3], vcc, s[2:3]
	v_mov_b64_e32 v[112:113], v[92:93]
	v_mov_b64_e32 v[116:117], v[88:89]
	v_mov_b64_e32 v[120:121], v[84:85]
	v_mov_b64_e32 v[34:35], v[82:83]
	v_mov_b64_e32 v[66:67], v[106:107]
	v_mov_b64_e32 v[74:75], v[110:111]
	v_mov_b64_e32 v[70:71], v[98:99]
	v_mov_b64_e32 v[78:79], v[102:103]
	s_andn2_b64 exec, exec, s[2:3]
	s_cbranch_execz .LBB0_594

.LBB0_603:
	s_or_b64 exec, exec, s[0:1]
	s_add_i32 s0, s92, -1
	v_cmp_ge_i32_e32 vcc, s0, v127
	v_add_u32_e32 v36, s92, v144
	s_or_b64 s[94:95], s[70:71], vcc
	v_cmp_ne_u32_e32 vcc, 1, v36
	v_cmp_ne_u32_e64 s[0:1], 9, v36
	s_setprio 1
	v_mfma_f32_32x32x16_bf16 v[32:47], v[32:35], v[48:51], 0
	v_mfma_f32_32x32x16_bf16 v[32:47], v[120:123], v[52:55], v[32:47]
	v_mfma_f32_32x32x16_bf16 v[32:47], v[116:119], v[56:59], v[32:47]
	v_mfma_f32_32x32x16_bf16 v[32:47], v[112:115], v[60:63], v[32:47]
	s_setprio 0
	s_and_b64 s[0:1], vcc, s[0:1]
	s_nor_b64 s[0:1], s[94:95], s[0:1]
	s_and_saveexec_b64 s[94:95], s[0:1]
	s_cbranch_execz .LBB0_605
	v_cndmask_b32_e64 v112, 0, 1, s[6:7]
	v_cndmask_b32_e64 v113, 0, 1, s[4:5]
	v_cndmask_b32_e32 v112, v113, v112, vcc
	v_and_b32_e32 v112, 1, v112
	v_cmp_eq_u32_e64 s[0:1], 1, v112
	v_cndmask_b32_e64 v112, 0, 1, s[10:11]
	v_cndmask_b32_e64 v113, 0, 1, s[8:9]
	v_cndmask_b32_e32 v112, v113, v112, vcc
	v_and_b32_e32 v112, 1, v112
	v_cndmask_b32_e64 v32, v233, v32, s[0:1]
	v_cmp_eq_u32_e64 s[0:1], 1, v112
	v_cndmask_b32_e64 v112, 0, 1, s[14:15]
	v_cndmask_b32_e64 v113, 0, 1, s[12:13]
	v_cndmask_b32_e32 v112, v113, v112, vcc
	v_and_b32_e32 v112, 1, v112
	v_cndmask_b32_e64 v33, v233, v33, s[0:1]
	v_cmp_eq_u32_e64 s[0:1], 1, v112
	v_cndmask_b32_e64 v112, 0, 1, s[18:19]
	v_cndmask_b32_e64 v113, 0, 1, s[16:17]
	v_cndmask_b32_e32 v112, v113, v112, vcc
	v_and_b32_e32 v112, 1, v112
	v_cndmask_b32_e64 v34, v233, v34, s[0:1]
	v_cmp_eq_u32_e64 s[0:1], 1, v112
	v_cndmask_b32_e64 v112, 0, 1, s[22:23]
	v_cndmask_b32_e64 v113, 0, 1, s[20:21]
	v_cndmask_b32_e32 v112, v113, v112, vcc
	v_and_b32_e32 v112, 1, v112
	v_cndmask_b32_e64 v35, v233, v35, s[0:1]
	v_cmp_eq_u32_e64 s[0:1], 1, v112
	v_cndmask_b32_e64 v112, 0, 1, s[26:27]
	v_cndmask_b32_e64 v113, 0, 1, s[24:25]
	v_cndmask_b32_e32 v112, v113, v112, vcc
	v_and_b32_e32 v112, 1, v112
	v_cndmask_b32_e64 v36, v233, v36, s[0:1]
	v_cmp_eq_u32_e64 s[0:1], 1, v112
	v_cndmask_b32_e64 v112, 0, 1, s[30:31]
	v_cndmask_b32_e64 v113, 0, 1, s[28:29]
	v_cndmask_b32_e32 v112, v113, v112, vcc
	v_and_b32_e32 v112, 1, v112
	v_cndmask_b32_e64 v37, v233, v37, s[0:1]
	v_cmp_eq_u32_e64 s[0:1], 1, v112
	v_cndmask_b32_e64 v112, 0, 1, s[36:37]
	v_cndmask_b32_e64 v113, 0, 1, s[34:35]
	v_cndmask_b32_e32 v112, v113, v112, vcc
	v_and_b32_e32 v112, 1, v112
	v_cndmask_b32_e64 v38, v233, v38, s[0:1]
	v_cmp_eq_u32_e64 s[0:1], 1, v112
	v_cndmask_b32_e64 v112, 0, 1, s[40:41]
	v_cndmask_b32_e64 v113, 0, 1, s[38:39]
	v_cndmask_b32_e32 v112, v113, v112, vcc
	v_and_b32_e32 v112, 1, v112
	v_cndmask_b32_e64 v39, v233, v39, s[0:1]
	v_cmp_eq_u32_e64 s[0:1], 1, v112
	v_cndmask_b32_e64 v112, 0, 1, s[44:45]
	v_cndmask_b32_e64 v113, 0, 1, s[42:43]
	v_cndmask_b32_e32 v112, v113, v112, vcc
	v_and_b32_e32 v112, 1, v112
	v_cndmask_b32_e64 v40, v233, v40, s[0:1]
	v_cmp_eq_u32_e64 s[0:1], 1, v112
	v_cndmask_b32_e64 v112, 0, 1, s[48:49]
	v_cndmask_b32_e64 v113, 0, 1, s[46:47]
	v_cndmask_b32_e32 v112, v113, v112, vcc
	v_and_b32_e32 v112, 1, v112
	v_cndmask_b32_e64 v41, v233, v41, s[0:1]
	v_cmp_eq_u32_e64 s[0:1], 1, v112
	v_cndmask_b32_e64 v112, 0, 1, s[52:53]
	v_cndmask_b32_e64 v113, 0, 1, s[50:51]
	v_cndmask_b32_e32 v112, v113, v112, vcc
	v_and_b32_e32 v112, 1, v112
	v_cndmask_b32_e64 v42, v233, v42, s[0:1]
	v_cmp_eq_u32_e64 s[0:1], 1, v112
	v_cndmask_b32_e64 v112, 0, 1, s[56:57]
	v_cndmask_b32_e64 v113, 0, 1, s[54:55]
	v_cndmask_b32_e32 v112, v113, v112, vcc
	v_and_b32_e32 v112, 1, v112
	v_cndmask_b32_e64 v43, v233, v43, s[0:1]
	v_cmp_eq_u32_e64 s[0:1], 1, v112
	v_cndmask_b32_e64 v112, 0, 1, s[60:61]
	v_cndmask_b32_e64 v113, 0, 1, s[58:59]
	v_cndmask_b32_e32 v112, v113, v112, vcc
	v_and_b32_e32 v112, 1, v112
	v_cndmask_b32_e64 v44, v233, v44, s[0:1]
	v_cmp_eq_u32_e64 s[0:1], 1, v112
	v_cndmask_b32_e64 v112, 0, 1, s[64:65]
	v_cndmask_b32_e64 v113, 0, 1, s[62:63]
	v_cndmask_b32_e32 v112, v113, v112, vcc
	v_and_b32_e32 v112, 1, v112
	v_cndmask_b32_e64 v45, v233, v45, s[0:1]
	v_cmp_eq_u32_e64 s[0:1], 1, v112
	v_cndmask_b32_e64 v112, 0, 1, s[68:69]
	v_cndmask_b32_e64 v113, 0, 1, s[66:67]
	v_cndmask_b32_e32 v112, v113, v112, vcc
	v_and_b32_e32 v112, 1, v112
	v_cmp_eq_u32_e32 vcc, 1, v112
	v_cndmask_b32_e64 v46, v233, v46, s[0:1]
	s_nop 0
	v_cndmask_b32_e32 v47, v233, v47, vcc

.LBB0_678:
	s_add_u32 s2, s8, 0xfffc0080
	s_addc_u32 s3, s9, -1
	s_add_i32 s59, 0, 0x10000
	v_add_u32_e32 v68, s59, v206
	ds_read_b128 v[48:51], v68
	ds_read_b128 v[52:55], v68 offset:1024
	ds_read_b128 v[60:63], v68 offset:2048
	ds_read_b128 v[68:71], v68 offset:3072
	s_cmp_eq_u32 s58, 12
	s_cselect_b32 s29, s1, s3
	s_cselect_b32 s28, s7, s2
	s_cselect_b32 s3, s21, s57
	s_cselect_b32 s2, s23, s56
	v_lshl_add_u64 v[200:201], s[8:9], 0, v[188:189]
	s_add_i32 m0, s41, 0xc000
	ds_read_b128 v[72:75], v207
	ds_read_b128 v[76:79], v207 offset:1024
	ds_read_b128 v[80:83], v207 offset:2048
	ds_read_b128 v[84:87], v207 offset:3072
	ds_read_b128 v[160:163], v207 offset:4096
	ds_read_b128 v[164:167], v207 offset:5120
	ds_read_b128 v[192:195], v207 offset:6144
	ds_read_b128 v[196:199], v207 offset:7168
	global_load_lds_dwordx4 v[200:201], off
	v_lshl_add_u64 v[200:201], s[8:9], 0, v[190:191]
	s_add_i32 m0, s41, 0xe000
	s_nop 0
	global_load_lds_dwordx4 v[200:201], off
	s_waitcnt lgkmcnt(8)
	s_barrier
	s_waitcnt lgkmcnt(0)
	s_setprio 1
	s_waitcnt lgkmcnt(0)
	v_mfma_f32_16x16x32_bf16 v[156:159], v[48:51], v[72:75], v[156:159]
	v_mfma_f32_16x16x32_bf16 v[152:155], v[60:63], v[72:75], v[152:155]
	v_mfma_f32_16x16x32_bf16 v[140:143], v[48:51], v[80:83], v[140:143]
	v_mfma_f32_16x16x32_bf16 v[136:139], v[60:63], v[80:83], v[136:139]
	v_mfma_f32_16x16x32_bf16 v[124:127], v[48:51], v[160:163], v[124:127]
	v_mfma_f32_16x16x32_bf16 v[120:123], v[60:63], v[160:163], v[120:123]
	v_mfma_f32_16x16x32_bf16 v[108:111], v[48:51], v[192:195], v[108:111]
	v_mfma_f32_16x16x32_bf16 v[104:107], v[60:63], v[192:195], v[104:107]
	v_mfma_f32_16x16x32_bf16 v[156:159], v[52:55], v[76:79], v[156:159]
	v_mfma_f32_16x16x32_bf16 v[152:155], v[68:71], v[76:79], v[152:155]
	v_mfma_f32_16x16x32_bf16 v[140:143], v[52:55], v[84:87], v[140:143]
	v_mfma_f32_16x16x32_bf16 v[136:139], v[68:71], v[84:87], v[136:139]
	v_mfma_f32_16x16x32_bf16 v[124:127], v[52:55], v[164:167], v[124:127]
	v_mfma_f32_16x16x32_bf16 v[120:123], v[68:71], v[164:167], v[120:123]
	v_mfma_f32_16x16x32_bf16 v[108:111], v[52:55], v[196:199], v[108:111]
	v_mfma_f32_16x16x32_bf16 v[104:107], v[68:71], v[196:199], v[104:107]
	s_setprio 0
	s_barrier
	s_add_i32 s62, 0, 0x14000
	s_add_i32 s59, s59, s40
	v_add_u32_e32 v168, s62, v206
	v_lshl_add_u64 v[240:241], s[2:3], 0, v[182:183]
	s_mov_b32 m0, s59
	ds_read_b128 v[200:203], v168
	ds_read_b128 v[208:211], v168 offset:1024
	ds_read_b128 v[212:215], v168 offset:2048
	ds_read_b128 v[216:219], v168 offset:3072
	global_load_lds_dwordx4 v[240:241], off
	v_lshl_add_u64 v[242:243], s[2:3], 0, v[186:187]
	s_add_i32 m0, s59, 0x2000
	s_nop 0
	global_load_lds_dwordx4 v[242:243], off
	s_barrier
	s_waitcnt lgkmcnt(0)
	s_setprio 1
	s_waitcnt lgkmcnt(0)
	v_mfma_f32_16x16x32_bf16 v[148:151], v[200:203], v[72:75], v[148:151]
	v_mfma_f32_16x16x32_bf16 v[72:75], v[212:215], v[72:75], v[144:147]
	v_mfma_f32_16x16x32_bf16 v[148:151], v[208:211], v[76:79], v[148:151]
	v_mfma_f32_16x16x32_bf16 v[72:75], v[216:219], v[76:79], v[72:75]
	v_mfma_f32_16x16x32_bf16 v[76:79], v[200:203], v[80:83], v[132:135]
	v_mfma_f32_16x16x32_bf16 v[80:83], v[212:215], v[80:83], v[128:131]
	v_mfma_f32_16x16x32_bf16 v[112:115], v[212:215], v[160:163], v[112:115]
	v_mfma_f32_16x16x32_bf16 v[100:103], v[200:203], v[192:195], v[100:103]
	v_mfma_f32_16x16x32_bf16 v[96:99], v[212:215], v[192:195], v[96:99]
	v_mfma_f32_16x16x32_bf16 v[76:79], v[208:211], v[84:87], v[76:79]
	v_mfma_f32_16x16x32_bf16 v[80:83], v[216:219], v[84:87], v[80:83]
	v_mfma_f32_16x16x32_bf16 v[84:87], v[200:203], v[160:163], v[116:119]
	v_mfma_f32_16x16x32_bf16 v[112:115], v[216:219], v[164:167], v[112:115]
	v_mfma_f32_16x16x32_bf16 v[100:103], v[208:211], v[196:199], v[100:103]
	v_mfma_f32_16x16x32_bf16 v[96:99], v[216:219], v[196:199], v[96:99]
	v_mfma_f32_16x16x32_bf16 v[84:87], v[208:211], v[164:167], v[84:87]
	s_setprio 0
	s_mov_b32 m0, s41
	v_lshl_add_u64 v[244:245], s[28:29], 0, v[180:181]
	s_barrier
	ds_read_b128 v[116:119], v207 offset:16384
	ds_read_b128 v[128:131], v207 offset:17408
	ds_read_b128 v[132:135], v207 offset:18432
	ds_read_b128 v[144:147], v207 offset:19456
	ds_read_b128 v[160:163], v207 offset:20480
	ds_read_b128 v[164:167], v207 offset:21504
	ds_read_b128 v[192:195], v207 offset:22528
	ds_read_b128 v[196:199], v207 offset:23552
	global_load_lds_dwordx4 v[244:245], off
	v_lshl_add_u64 v[246:247], s[28:29], 0, v[184:185]
	s_mov_b32 m0, s42
	s_nop 0
	global_load_lds_dwordx4 v[246:247], off
	s_barrier
	s_waitcnt lgkmcnt(0)
	s_setprio 1
	s_waitcnt lgkmcnt(0)
	v_mfma_f32_16x16x32_bf16 v[92:95], v[48:51], v[116:119], v[92:95]
	v_mfma_f32_16x16x32_bf16 v[88:91], v[60:63], v[116:119], v[88:91]
	v_mfma_f32_16x16x32_bf16 v[44:47], v[48:51], v[132:135], v[44:47]
	v_mfma_f32_16x16x32_bf16 v[40:43], v[60:63], v[132:135], v[40:43]
	v_mfma_f32_16x16x32_bf16 v[28:31], v[48:51], v[160:163], v[28:31]
	v_mfma_f32_16x16x32_bf16 v[24:27], v[60:63], v[160:163], v[24:27]
	v_mfma_f32_16x16x32_bf16 v[12:15], v[48:51], v[192:195], v[12:15]
	v_mfma_f32_16x16x32_bf16 v[8:11], v[60:63], v[192:195], v[8:11]
	v_mfma_f32_16x16x32_bf16 v[92:95], v[52:55], v[128:131], v[92:95]
	v_mfma_f32_16x16x32_bf16 v[88:91], v[68:71], v[128:131], v[88:91]
	v_mfma_f32_16x16x32_bf16 v[44:47], v[52:55], v[144:147], v[44:47]
	v_mfma_f32_16x16x32_bf16 v[40:43], v[68:71], v[144:147], v[40:43]
	v_mfma_f32_16x16x32_bf16 v[28:31], v[52:55], v[164:167], v[28:31]
	v_mfma_f32_16x16x32_bf16 v[24:27], v[68:71], v[164:167], v[24:27]
	v_mfma_f32_16x16x32_bf16 v[12:15], v[52:55], v[196:199], v[12:15]
	v_mfma_f32_16x16x32_bf16 v[8:11], v[68:71], v[196:199], v[8:11]
	s_setprio 0
	s_barrier
	s_add_u32 s60, s2, 0x40000
	s_addc_u32 s61, s3, 0
	s_add_i32 s59, s62, s40
	v_lshl_add_u64 v[48:49], s[60:61], 0, v[182:183]
	s_mov_b32 m0, s59
	s_nop 0
	global_load_lds_dwordx4 v[48:49], off
	v_lshl_add_u64 v[48:49], s[60:61], 0, v[186:187]
	s_add_i32 m0, s59, 0x2000
	s_nop 0
	global_load_lds_dwordx4 v[48:49], off
	s_waitcnt vmcnt(6)
	s_barrier
	s_setprio 1
	v_mfma_f32_16x16x32_bf16 v[36:39], v[200:203], v[132:135], v[36:39]
	v_mfma_f32_16x16x32_bf16 v[32:35], v[212:215], v[132:135], v[32:35]
	v_mfma_f32_16x16x32_bf16 v[20:23], v[200:203], v[160:163], v[20:23]
	v_mfma_f32_16x16x32_bf16 v[16:19], v[212:215], v[160:163], v[16:19]
	v_mfma_f32_16x16x32_bf16 v[4:7], v[200:203], v[192:195], v[4:7]
	v_mfma_f32_16x16x32_bf16 v[0:3], v[212:215], v[192:195], v[0:3]
	v_mfma_f32_16x16x32_bf16 v[48:51], v[200:203], v[116:119], v[64:67]
	v_mfma_f32_16x16x32_bf16 v[52:55], v[212:215], v[116:119], v[56:59]
	v_mfma_f32_16x16x32_bf16 v[36:39], v[208:211], v[144:147], v[36:39]
	v_mfma_f32_16x16x32_bf16 v[32:35], v[216:219], v[144:147], v[32:35]
	v_mfma_f32_16x16x32_bf16 v[20:23], v[208:211], v[164:167], v[20:23]
	v_mfma_f32_16x16x32_bf16 v[16:19], v[216:219], v[164:167], v[16:19]
	v_mfma_f32_16x16x32_bf16 v[4:7], v[208:211], v[196:199], v[4:7]
	v_mfma_f32_16x16x32_bf16 v[0:3], v[216:219], v[196:199], v[0:3]
	v_mfma_f32_16x16x32_bf16 v[48:51], v[208:211], v[128:131], v[48:51]
	v_mfma_f32_16x16x32_bf16 v[52:55], v[216:219], v[128:131], v[52:55]
	s_setprio 0
	s_add_i32 s59, 0, 0x18000
	v_add_u32_e32 v68, s59, v206
	s_barrier
	ds_read_b128 v[56:59], v68
	ds_read_b128 v[60:63], v68 offset:1024
	ds_read_b128 v[64:67], v68 offset:2048
	ds_read_b128 v[68:71], v68 offset:3072
	s_add_u32 s28, s28, 0x40000
	s_addc_u32 s29, s29, 0
	s_mov_b32 m0, s43
	v_lshl_add_u64 v[132:133], s[28:29], 0, v[180:181]
	ds_read_b128 v[116:119], v207 offset:32768
	ds_read_b128 v[128:131], v207 offset:33792
	ds_read_b128 v[160:163], v207 offset:34816
	ds_read_b128 v[164:167], v207 offset:35840
	ds_read_b128 v[192:195], v207 offset:36864
	ds_read_b128 v[196:199], v207 offset:37888
	ds_read_b128 v[200:203], v207 offset:38912
	ds_read_b128 v[208:211], v207 offset:39936
	global_load_lds_dwordx4 v[132:133], off
	v_lshl_add_u64 v[132:133], s[28:29], 0, v[184:185]
	s_mov_b32 m0, s44
	s_nop 0
	global_load_lds_dwordx4 v[132:133], off
	s_waitcnt lgkmcnt(8)
	s_barrier
	s_waitcnt lgkmcnt(0)
	s_setprio 1
	s_waitcnt lgkmcnt(0)
	v_mfma_f32_16x16x32_bf16 v[132:135], v[56:59], v[116:119], v[156:159]
	v_mfma_f32_16x16x32_bf16 v[156:159], v[60:63], v[128:131], v[132:135]
	v_mfma_f32_16x16x32_bf16 v[132:135], v[64:67], v[116:119], v[152:155]
	v_mfma_f32_16x16x32_bf16 v[152:155], v[68:71], v[128:131], v[132:135]
	v_mfma_f32_16x16x32_bf16 v[132:135], v[56:59], v[160:163], v[140:143]
	v_mfma_f32_16x16x32_bf16 v[140:143], v[60:63], v[164:167], v[132:135]
	v_mfma_f32_16x16x32_bf16 v[132:135], v[64:67], v[160:163], v[136:139]
	v_mfma_f32_16x16x32_bf16 v[124:127], v[56:59], v[192:195], v[124:127]
	v_mfma_f32_16x16x32_bf16 v[120:123], v[64:67], v[192:195], v[120:123]
	v_mfma_f32_16x16x32_bf16 v[108:111], v[56:59], v[200:203], v[108:111]
	v_mfma_f32_16x16x32_bf16 v[104:107], v[64:67], v[200:203], v[104:107]
	v_mfma_f32_16x16x32_bf16 v[136:139], v[68:71], v[164:167], v[132:135]
	v_mfma_f32_16x16x32_bf16 v[124:127], v[60:63], v[196:199], v[124:127]
	v_mfma_f32_16x16x32_bf16 v[120:123], v[68:71], v[196:199], v[120:123]
	v_mfma_f32_16x16x32_bf16 v[108:111], v[60:63], v[208:211], v[108:111]
	v_mfma_f32_16x16x32_bf16 v[104:107], v[68:71], v[208:211], v[104:107]
	s_setprio 0
	s_barrier
	s_add_i32 s28, 0, 0x1c000
	v_add_u32_e32 v132, s28, v206
	s_add_i32 s29, s59, s40
	ds_read_b128 v[212:215], v132
	ds_read_b128 v[216:219], v132 offset:1024
	ds_read_b128 v[220:223], v132 offset:2048
	ds_read_b128 v[236:239], v132 offset:3072
	v_lshl_add_u64 v[132:133], v[240:241], 0, s[78:79]
	s_mov_b32 m0, s29
	s_nop 0
	global_load_lds_dwordx4 v[132:133], off
	v_lshl_add_u64 v[132:133], v[242:243], 0, s[78:79]
	s_add_i32 m0, s29, 0x2000
	s_nop 0
	global_load_lds_dwordx4 v[132:133], off
	s_barrier
	s_waitcnt lgkmcnt(0)
	s_setprio 1
	s_waitcnt lgkmcnt(0)
	v_mfma_f32_16x16x32_bf16 v[72:75], v[220:223], v[116:119], v[72:75]
	v_mfma_f32_16x16x32_bf16 v[132:135], v[212:215], v[116:119], v[148:151]
	v_mfma_f32_16x16x32_bf16 v[144:147], v[236:239], v[128:131], v[72:75]
	v_mfma_f32_16x16x32_bf16 v[72:75], v[212:215], v[160:163], v[76:79]
	v_mfma_f32_16x16x32_bf16 v[148:151], v[216:219], v[128:131], v[132:135]
	v_mfma_f32_16x16x32_bf16 v[132:135], v[216:219], v[164:167], v[72:75]
	v_mfma_f32_16x16x32_bf16 v[72:75], v[220:223], v[160:163], v[80:83]
	v_mfma_f32_16x16x32_bf16 v[128:131], v[236:239], v[164:167], v[72:75]
	v_mfma_f32_16x16x32_bf16 v[72:75], v[212:215], v[192:195], v[84:87]
	v_mfma_f32_16x16x32_bf16 v[116:119], v[216:219], v[196:199], v[72:75]
	v_mfma_f32_16x16x32_bf16 v[72:75], v[220:223], v[192:195], v[112:115]
	v_mfma_f32_16x16x32_bf16 v[112:115], v[236:239], v[196:199], v[72:75]
	v_mfma_f32_16x16x32_bf16 v[72:75], v[212:215], v[200:203], v[100:103]
	v_mfma_f32_16x16x32_bf16 v[100:103], v[216:219], v[208:211], v[72:75]
	v_mfma_f32_16x16x32_bf16 v[72:75], v[220:223], v[200:203], v[96:99]
	v_mfma_f32_16x16x32_bf16 v[96:99], v[236:239], v[208:211], v[72:75]
	s_setprio 0
	s_mov_b32 m0, s53
	v_lshl_add_u64 v[200:201], v[244:245], 0, s[78:79]
	s_barrier
	s_nop 2
	ds_read_b128 v[72:75], v207 offset:49152
	ds_read_b128 v[76:79], v207 offset:50176
	ds_read_b128 v[80:83], v207 offset:51200
	ds_read_b128 v[84:87], v207 offset:52224
	ds_read_b128 v[160:163], v207 offset:53248
	ds_read_b128 v[164:167], v207 offset:54272
	ds_read_b128 v[192:195], v207 offset:55296
	ds_read_b128 v[196:199], v207 offset:56320
	global_load_lds_dwordx4 v[200:201], off
	v_lshl_add_u64 v[200:201], v[246:247], 0, s[78:79]
	s_mov_b32 m0, s54
	s_nop 0
	global_load_lds_dwordx4 v[200:201], off
	s_barrier
	s_waitcnt lgkmcnt(0)
	s_setprio 1
	s_waitcnt lgkmcnt(0)
	v_mfma_f32_16x16x32_bf16 v[92:95], v[56:59], v[72:75], v[92:95]
	v_mfma_f32_16x16x32_bf16 v[88:91], v[64:67], v[72:75], v[88:91]
	v_mfma_f32_16x16x32_bf16 v[44:47], v[56:59], v[80:83], v[44:47]
	v_mfma_f32_16x16x32_bf16 v[40:43], v[64:67], v[80:83], v[40:43]
	v_mfma_f32_16x16x32_bf16 v[28:31], v[56:59], v[160:163], v[28:31]
	v_mfma_f32_16x16x32_bf16 v[24:27], v[64:67], v[160:163], v[24:27]
	v_mfma_f32_16x16x32_bf16 v[12:15], v[56:59], v[192:195], v[12:15]
	v_mfma_f32_16x16x32_bf16 v[8:11], v[64:67], v[192:195], v[8:11]
	v_mfma_f32_16x16x32_bf16 v[92:95], v[60:63], v[76:79], v[92:95]
	v_mfma_f32_16x16x32_bf16 v[88:91], v[68:71], v[76:79], v[88:91]
	v_mfma_f32_16x16x32_bf16 v[44:47], v[60:63], v[84:87], v[44:47]
	v_mfma_f32_16x16x32_bf16 v[40:43], v[68:71], v[84:87], v[40:43]
	v_mfma_f32_16x16x32_bf16 v[28:31], v[60:63], v[164:167], v[28:31]
	v_mfma_f32_16x16x32_bf16 v[24:27], v[68:71], v[164:167], v[24:27]
	v_mfma_f32_16x16x32_bf16 v[12:15], v[60:63], v[196:199], v[12:15]
	v_mfma_f32_16x16x32_bf16 v[8:11], v[68:71], v[196:199], v[8:11]
	s_setprio 0
	s_barrier
	s_add_u32 s2, s2, 0x40080
	s_addc_u32 s3, s3, 0
	s_add_i32 s28, s28, s40
	v_lshl_add_u64 v[56:57], s[2:3], 0, v[182:183]
	s_mov_b32 m0, s28
	s_nop 0
	global_load_lds_dwordx4 v[56:57], off
	v_lshl_add_u64 v[56:57], s[2:3], 0, v[186:187]
	s_add_i32 m0, s28, 0x2000
	s_nop 0
	global_load_lds_dwordx4 v[56:57], off
	s_waitcnt vmcnt(6)
	s_barrier
	s_setprio 1
	v_mfma_f32_16x16x32_bf16 v[48:51], v[212:215], v[72:75], v[48:51]
	v_mfma_f32_16x16x32_bf16 v[64:67], v[216:219], v[76:79], v[48:51]
	v_mfma_f32_16x16x32_bf16 v[48:51], v[220:223], v[72:75], v[52:55]
	v_mfma_f32_16x16x32_bf16 v[36:39], v[212:215], v[80:83], v[36:39]
	v_mfma_f32_16x16x32_bf16 v[32:35], v[220:223], v[80:83], v[32:35]
	v_mfma_f32_16x16x32_bf16 v[20:23], v[212:215], v[160:163], v[20:23]
	v_mfma_f32_16x16x32_bf16 v[16:19], v[220:223], v[160:163], v[16:19]
	v_mfma_f32_16x16x32_bf16 v[4:7], v[212:215], v[192:195], v[4:7]
	v_mfma_f32_16x16x32_bf16 v[0:3], v[220:223], v[192:195], v[0:3]
	v_mfma_f32_16x16x32_bf16 v[56:59], v[236:239], v[76:79], v[48:51]
	v_mfma_f32_16x16x32_bf16 v[36:39], v[216:219], v[84:87], v[36:39]
	v_mfma_f32_16x16x32_bf16 v[32:35], v[236:239], v[84:87], v[32:35]
	v_mfma_f32_16x16x32_bf16 v[20:23], v[216:219], v[164:167], v[20:23]
	v_mfma_f32_16x16x32_bf16 v[16:19], v[236:239], v[164:167], v[16:19]
	v_mfma_f32_16x16x32_bf16 v[4:7], v[216:219], v[196:199], v[4:7]
	v_mfma_f32_16x16x32_bf16 v[0:3], v[236:239], v[196:199], v[0:3]
	s_setprio 0
	s_add_i32 s58, s58, 2
	s_add_u32 s8, s8, 0x100
	s_addc_u32 s9, s9, 0
	s_add_u32 s56, s56, 0x100
	s_addc_u32 s57, s57, 0
	s_cmp_gt_u32 s58, 13
	s_barrier
	s_cbranch_scc0 .LBB0_678
	s_lshl_b32 s1, s0, 8
	s_add_i32 s2, s1, s51
	s_lshl_b32 s1, s6, 8
	v_mov_b32_e32 v160, v205
	v_mov_b32_e32 v208, v204
	s_or_b32 s1, s1, s52
	s_nop 0
	v_lshl_add_u32 v192, v208, 3, s1
	s_add_i32 s1, s0, -16
	s_lshr_b32 s1, s1, 3
	s_add_i32 s1, s1, 1
	s_cmp_gt_i32 s0, 15
	s_cselect_b32 s3, s1, 0
	s_mul_i32 s96, s3, 0x1800
	s_lshl_b64 s[0:1], s[96:97], 2
	s_add_u32 s0, s45, s0
	v_ashrrev_i32_e32 v193, 31, v192
	s_addc_u32 s1, s46, s1
	v_lshlrev_b64 v[196:197], 2, v[192:193]
	s_lshl_b32 s96, s3, 10
	v_lshl_add_u64 v[48:49], s[0:1], 0, v[196:197]
	s_lshl_b64 s[0:1], s[96:97], 2
	s_add_u32 s0, s49, s0
	s_addc_u32 s1, s50, s1
	v_lshl_add_u64 v[52:53], s[0:1], 0, v[196:197]
	global_load_dwordx4 v[80:83], v[48:49], off offset:16
	global_load_dwordx4 v[84:87], v[48:49], off
	global_load_dwordx4 v[72:75], v[52:53], off offset:16
	global_load_dwordx4 v[76:79], v[52:53], off
	global_load_dwordx4 v[60:63], v[48:49], off offset:528
	global_load_dwordx4 v[68:71], v[48:49], off offset:512
	s_nop 0
	global_load_dwordx4 v[48:51], v[52:53], off offset:528
	s_nop 0
	global_load_dwordx4 v[52:55], v[52:53], off offset:512
	v_add_u32_e32 v194, s2, v160
	v_ashrrev_i32_e32 v195, 31, v194
	v_lshlrev_b64 v[160:161], 10, v[194:195]
	v_lshl_add_u64 v[198:199], v[160:161], 0, v[192:193]
	v_cndmask_b32_e64 v160, 0, 1, s[74:75]
	v_cmp_gt_i32_e64 s[0:1], s71, v194
	v_cmp_ne_u32_e64 s[6:7], 1, v160
	s_andn2_b64 vcc, exec, s[74:75]
	s_mov_b64 s[2:3], -1
	s_cbranch_vccnz .LBB0_681
	v_lshl_add_u64 v[160:161], v[198:199], 1, s[14:15]
	v_mov_b32_e32 v222, v160
	v_mov_b32_e32 v223, v161
	global_load_dwordx4 v[210:213], v[222:223], off
	global_load_dwordx4 v[214:217], v[222:223], off offset:256
	s_mov_b64 s[80:81], 0x8000
	v_lshl_add_u64 v[222:223], v[222:223], 0, s[80:81]
	global_load_dwordx4 v[218:221], v[222:223], off
	global_load_dwordx4 v[236:239], v[222:223], off offset:256
	s_mov_b64 s[2:3], 0
	s_waitcnt vmcnt(3)
	v_lshlrev_b32_e32 v164, 16, v210
	v_and_b32_e32 v165, 0xffff0000, v210
	v_lshlrev_b32_e32 v166, 16, v211
	v_and_b32_e32 v167, 0xffff0000, v211
	v_lshlrev_b32_e32 v160, 16, v212
	v_and_b32_e32 v161, 0xffff0000, v212
	v_lshlrev_b32_e32 v162, 16, v213
	v_and_b32_e32 v163, 0xffff0000, v213
	s_mov_b64 s[80:81], 0x8000
	v_lshl_add_u64 v[222:223], v[222:223], 0, s[80:81]
	global_load_dwordx4 v[210:213], v[222:223], off
.LBB0_681:
	v_add_u32_e32 v168, 0xfffff000, v194
	v_lshlrev_b64 v[200:201], 12, v[194:195]
	v_lshlrev_b64 v[202:203], 12, v[168:169]
	v_lshl_add_u64 v[200:201], s[10:11], 0, v[200:201]
	v_lshl_add_u64 v[202:203], s[12:13], 0, v[202:203]
	v_cndmask_b32_e64 v201, v203, v201, s[0:1]
	v_cndmask_b32_e64 v200, v202, v200, s[0:1]
	s_andn2_b64 vcc, exec, s[2:3]
	v_lshl_add_u64 v[196:197], v[200:201], 0, v[196:197]
	s_cbranch_vccnz .LBB0_683
	v_mov_b32_e32 v222, v196
	v_mov_b32_e32 v223, v197
	global_load_dwordx4 v[214:217], v[222:223], off offset:16
	global_load_dwordx4 v[210:213], v[222:223], off
	global_load_dwordx4 v[236:239], v[222:223], off offset:528
	global_load_dwordx4 v[218:221], v[222:223], off offset:512
	s_waitcnt vmcnt(2)
	v_mov_b32_e32 v160, v214
	v_mov_b32_e32 v161, v215
	v_mov_b32_e32 v162, v216
	v_mov_b32_e32 v163, v217
	v_mov_b32_e32 v164, v210
	v_mov_b32_e32 v165, v211
	v_mov_b32_e32 v166, v212
	v_mov_b32_e32 v167, v213
	s_mov_b64 s[80:81], 0x10000
	v_lshl_add_u64 v[222:223], v[222:223], 0, s[80:81]
	global_load_dwordx4 v[214:217], v[222:223], off offset:16
	global_load_dwordx4 v[210:213], v[222:223], off
.LBB0_683:
	s_waitcnt vmcnt(63)
	v_pk_fma_f32 v[166:167], v[158:159], v[86:87], v[166:167]
	v_pk_fma_f32 v[200:201], v[156:157], v[84:85], v[164:165]
	v_pk_fma_f32 v[164:165], v[154:155], v[82:83], v[162:163]
	v_pk_fma_f32 v[202:203], v[152:153], v[80:81], v[160:161]
	v_lshlrev_b64 v[156:157], 1, v[198:199]
	v_cvt_pk_bf16_f32 v152, v200, v201
	v_cvt_pk_bf16_f32 v153, v166, v167
	v_cvt_pk_bf16_f32 v154, v202, v203
	v_cvt_pk_bf16_f32 v155, v164, v165
	v_lshl_add_u64 v[160:161], s[14:15], 0, v[156:157]
	global_store_dwordx4 v[160:161], v[152:155], off
	v_pk_mul_f32 v[158:159], v[74:75], v[164:165]
	v_pk_mul_f32 v[162:163], v[72:73], v[202:203]
	v_pk_mul_f32 v[154:155], v[78:79], v[166:167]
	v_pk_mul_f32 v[152:153], v[76:77], v[200:201]
	s_and_b64 vcc, exec, s[6:7]
	v_cvt_pk_bf16_f32 v152, v152, v153
	v_cvt_pk_bf16_f32 v153, v154, v155
	v_cvt_pk_bf16_f32 v154, v162, v163
	v_cvt_pk_bf16_f32 v155, v158, v159
	v_lshl_add_u64 v[162:163], s[16:17], 0, v[156:157]
	s_mov_b64 s[0:1], -1
	global_store_dwordx4 v[162:163], v[152:155], off
	s_cbranch_vccnz .LBB0_685
	s_mov_b64 s[0:1], 0
	s_waitcnt vmcnt(5)
	v_lshlrev_b32_e32 v156, 16, v214
	v_and_b32_e32 v157, 0xffff0000, v214
	v_lshlrev_b32_e32 v158, 16, v215
	v_and_b32_e32 v159, 0xffff0000, v215
	v_lshlrev_b32_e32 v152, 16, v216
	v_and_b32_e32 v153, 0xffff0000, v216
	v_lshlrev_b32_e32 v154, 16, v217
	v_and_b32_e32 v155, 0xffff0000, v217
	global_load_dwordx4 v[214:217], v[222:223], off offset:256
.LBB0_685:
	s_andn2_b64 vcc, exec, s[0:1]
	s_cbranch_vccnz .LBB0_687
	s_waitcnt vmcnt(4)
	v_mov_b32_e32 v152, v236
	v_mov_b32_e32 v153, v237
	v_mov_b32_e32 v154, v238
	v_mov_b32_e32 v155, v239
	v_mov_b32_e32 v156, v218
	v_mov_b32_e32 v157, v219
	v_mov_b32_e32 v158, v220
	v_mov_b32_e32 v159, v221
	global_load_dwordx4 v[236:239], v[222:223], off offset:528
	global_load_dwordx4 v[218:221], v[222:223], off offset:512
.LBB0_687:
	s_waitcnt vmcnt(63)
	v_pk_fma_f32 v[150:151], v[150:151], v[70:71], v[158:159]
	v_pk_fma_f32 v[148:149], v[148:149], v[68:69], v[156:157]
	v_pk_fma_f32 v[154:155], v[146:147], v[62:63], v[154:155]
	v_pk_fma_f32 v[152:153], v[144:145], v[60:61], v[152:153]
	v_cvt_pk_bf16_f32 v144, v148, v149
	v_cvt_pk_bf16_f32 v145, v150, v151
	v_cvt_pk_bf16_f32 v146, v152, v153
	v_cvt_pk_bf16_f32 v147, v154, v155
	global_store_dwordx4 v[160:161], v[144:147], off offset:256
	v_pk_mul_f32 v[156:157], v[50:51], v[154:155]
	v_pk_mul_f32 v[158:159], v[48:49], v[152:153]
	v_pk_mul_f32 v[146:147], v[54:55], v[150:151]
	v_pk_mul_f32 v[144:145], v[52:53], v[148:149]
	v_mul_f32_e32 v168, v201, v201
	v_cvt_pk_bf16_f32 v144, v144, v145
	v_cvt_pk_bf16_f32 v145, v146, v147
	v_cvt_pk_bf16_f32 v146, v158, v159
	v_cvt_pk_bf16_f32 v147, v156, v157
	v_mul_f32_e32 v167, v167, v167
	global_store_dwordx4 v[162:163], v[144:147], off offset:256
	v_fmac_f32_e32 v168, v200, v200
	v_fmac_f32_e32 v167, v166, v166
	v_mul_f32_e32 v145, v149, v149
	v_mul_f32_e32 v146, v151, v151
	v_fmac_f32_e32 v145, v148, v148
	v_fmac_f32_e32 v146, v150, v150
	v_add_f32_e32 v166, v168, v167
	v_mul_f32_e32 v167, v203, v203
	v_add_f32_e32 v145, v145, v146
	v_mul_f32_e32 v146, v153, v153
	v_fmac_f32_e32 v167, v202, v202
	v_mul_f32_e32 v165, v165, v165
	v_mul_f32_e32 v144, v155, v155
	v_fmac_f32_e32 v146, v152, v152
	v_add_f32_e32 v166, v166, v167
	v_fmac_f32_e32 v165, v164, v164
	v_fmac_f32_e32 v144, v154, v154
	v_add_f32_e32 v145, v145, v146
	v_add_f32_e32 v164, v165, v166
	v_add_f32_e32 v144, v144, v145
	v_add_f32_e32 v144, v164, v144
	v_mov_b32_e32 v145, v144
	s_nop 1
	v_permlane16_swap_b32_e32 v144, v145
	v_add_f32_e32 v144, v144, v145
	v_mov_b32_e32 v145, v144
	v_cmp_eq_u32_e64 s[8:9], 0, v208
	s_nop 0
	v_permlane32_swap_b32_e32 v144, v145
	v_lshl_add_u64 v[152:153], v[194:195], 2, s[18:19]
	s_and_saveexec_b64 s[0:1], s[8:9]
	s_cbranch_execz .LBB0_689
	v_add_f32_e32 v144, v144, v145
	global_atomic_add_f32 v[152:153], v144, off
.LBB0_689:
	s_or_b64 exec, exec, s[0:1]
	v_add_u32_e32 v154, 16, v194
	v_ashrrev_i32_e32 v155, 31, v154
	v_lshlrev_b64 v[144:145], 10, v[154:155]
	s_movk_i32 s0, 0xff0
	v_lshl_add_u64 v[156:157], v[144:145], 0, v[192:193]
	v_cmp_gt_i32_e64 s[0:1], s0, v194
	s_and_b64 vcc, exec, s[6:7]
	s_mov_b64 s[2:3], -1
	s_cbranch_vccnz .LBB0_691
	v_lshl_add_u64 v[144:145], v[156:157], 1, s[14:15]
	s_mov_b64 s[2:3], 0
	s_waitcnt vmcnt(7)
	v_lshlrev_b32_e32 v148, 16, v218
	v_and_b32_e32 v149, 0xffff0000, v218
	v_lshlrev_b32_e32 v150, 16, v219
	v_and_b32_e32 v151, 0xffff0000, v219
	v_lshlrev_b32_e32 v144, 16, v220
	v_and_b32_e32 v145, 0xffff0000, v220
	v_lshlrev_b32_e32 v146, 16, v221
	v_and_b32_e32 v147, 0xffff0000, v221
	s_mov_b64 s[80:81], 0x8000
	v_lshl_add_u64 v[222:223], v[222:223], 0, s[80:81]
	global_load_dwordx4 v[218:221], v[222:223], off
.LBB0_691:
	v_add_u32_e32 v168, 0xfffff010, v194
	v_lshlrev_b64 v[154:155], 12, v[154:155]
	v_lshlrev_b64 v[158:159], 12, v[168:169]
	v_lshl_add_u64 v[154:155], s[10:11], 0, v[154:155]
	v_lshl_add_u64 v[158:159], s[12:13], 0, v[158:159]
	v_cndmask_b32_e64 v155, v159, v155, s[0:1]
	v_cndmask_b32_e64 v154, v158, v154, s[0:1]
	s_andn2_b64 vcc, exec, s[2:3]
	v_lshl_add_u64 v[154:155], v[192:193], 2, v[154:155]
	s_cbranch_vccnz .LBB0_693
	s_waitcnt vmcnt(6)
	v_mov_b32_e32 v144, v214
	v_mov_b32_e32 v145, v215
	v_mov_b32_e32 v146, v216
	v_mov_b32_e32 v147, v217
	v_mov_b32_e32 v148, v210
	v_mov_b32_e32 v149, v211
	v_mov_b32_e32 v150, v212
	v_mov_b32_e32 v151, v213
	s_mov_b64 s[80:81], 0x10000
	v_lshl_add_u64 v[222:223], v[222:223], 0, s[80:81]
	global_load_dwordx4 v[214:217], v[222:223], off offset:16
	global_load_dwordx4 v[210:213], v[222:223], off
.LBB0_693:
	s_waitcnt vmcnt(63)
	v_pk_fma_f32 v[150:151], v[142:143], v[86:87], v[150:151]
	v_pk_fma_f32 v[158:159], v[140:141], v[84:85], v[148:149]
	v_pk_fma_f32 v[148:149], v[138:139], v[82:83], v[146:147]
	v_pk_fma_f32 v[160:161], v[136:137], v[80:81], v[144:145]
	v_lshlrev_b64 v[140:141], 1, v[156:157]
	v_cvt_pk_bf16_f32 v136, v158, v159
	v_cvt_pk_bf16_f32 v137, v150, v151
	v_cvt_pk_bf16_f32 v138, v160, v161
	v_cvt_pk_bf16_f32 v139, v148, v149
	v_lshl_add_u64 v[144:145], s[14:15], 0, v[140:141]
	global_store_dwordx4 v[144:145], v[136:139], off
	v_pk_mul_f32 v[142:143], v[74:75], v[148:149]
	v_pk_mul_f32 v[146:147], v[72:73], v[160:161]
	v_pk_mul_f32 v[138:139], v[78:79], v[150:151]
	v_pk_mul_f32 v[136:137], v[76:77], v[158:159]
	s_and_b64 vcc, exec, s[6:7]
	v_cvt_pk_bf16_f32 v136, v136, v137
	v_cvt_pk_bf16_f32 v137, v138, v139
	v_cvt_pk_bf16_f32 v138, v146, v147
	v_cvt_pk_bf16_f32 v139, v142, v143
	v_lshl_add_u64 v[146:147], s[16:17], 0, v[140:141]
	s_mov_b64 s[0:1], -1
	global_store_dwordx4 v[146:147], v[136:139], off
	s_cbranch_vccnz .LBB0_695
	s_mov_b64 s[0:1], 0
	s_waitcnt vmcnt(9)
	v_lshlrev_b32_e32 v140, 16, v236
	v_and_b32_e32 v141, 0xffff0000, v236
	v_lshlrev_b32_e32 v142, 16, v237
	v_and_b32_e32 v143, 0xffff0000, v237
	v_lshlrev_b32_e32 v136, 16, v238
	v_and_b32_e32 v137, 0xffff0000, v238
	v_lshlrev_b32_e32 v138, 16, v239
	v_and_b32_e32 v139, 0xffff0000, v239
	global_load_dwordx4 v[236:239], v[222:223], off offset:256
.LBB0_695:
	s_andn2_b64 vcc, exec, s[0:1]
	s_cbranch_vccnz .LBB0_697
	s_waitcnt vmcnt(6)
	v_mov_b32_e32 v136, v236
	v_mov_b32_e32 v137, v237
	v_mov_b32_e32 v138, v238
	v_mov_b32_e32 v139, v239
	v_mov_b32_e32 v140, v218
	v_mov_b32_e32 v141, v219
	v_mov_b32_e32 v142, v220
	v_mov_b32_e32 v143, v221
	global_load_dwordx4 v[236:239], v[222:223], off offset:528
	global_load_dwordx4 v[218:221], v[222:223], off offset:512
.LBB0_697:
	s_waitcnt vmcnt(63)
	v_pk_fma_f32 v[134:135], v[134:135], v[70:71], v[142:143]
	v_pk_fma_f32 v[132:133], v[132:133], v[68:69], v[140:141]
	v_pk_fma_f32 v[138:139], v[130:131], v[62:63], v[138:139]
	v_pk_fma_f32 v[136:137], v[128:129], v[60:61], v[136:137]
	v_cvt_pk_bf16_f32 v128, v132, v133
	v_cvt_pk_bf16_f32 v129, v134, v135
	v_cvt_pk_bf16_f32 v130, v136, v137
	v_cvt_pk_bf16_f32 v131, v138, v139
	global_store_dwordx4 v[144:145], v[128:131], off offset:256
	v_pk_mul_f32 v[140:141], v[50:51], v[138:139]
	v_pk_mul_f32 v[142:143], v[48:49], v[136:137]
	v_pk_mul_f32 v[130:131], v[54:55], v[134:135]
	v_pk_mul_f32 v[128:129], v[52:53], v[132:133]
	v_mul_f32_e32 v154, v159, v159
	v_cvt_pk_bf16_f32 v128, v128, v129
	v_cvt_pk_bf16_f32 v129, v130, v131
	v_cvt_pk_bf16_f32 v130, v142, v143
	v_cvt_pk_bf16_f32 v131, v140, v141
	v_mul_f32_e32 v151, v151, v151
	global_store_dwordx4 v[146:147], v[128:131], off offset:256
	v_fmac_f32_e32 v154, v158, v158
	v_fmac_f32_e32 v151, v150, v150
	v_mul_f32_e32 v129, v133, v133
	v_mul_f32_e32 v130, v135, v135
	v_fmac_f32_e32 v129, v132, v132
	v_fmac_f32_e32 v130, v134, v134
	v_add_f32_e32 v150, v154, v151
	v_mul_f32_e32 v151, v161, v161
	v_add_f32_e32 v129, v129, v130
	v_mul_f32_e32 v130, v137, v137
	v_fmac_f32_e32 v151, v160, v160
	v_mul_f32_e32 v149, v149, v149
	v_mul_f32_e32 v128, v139, v139
	v_fmac_f32_e32 v130, v136, v136
	v_add_f32_e32 v150, v150, v151
	v_fmac_f32_e32 v149, v148, v148
	v_fmac_f32_e32 v128, v138, v138
	v_add_f32_e32 v129, v129, v130
	v_add_f32_e32 v148, v149, v150
	v_add_f32_e32 v128, v128, v129
	v_add_f32_e32 v128, v148, v128
	v_mov_b32_e32 v129, v128
	s_nop 1
	v_permlane16_swap_b32_e32 v128, v129
	v_add_f32_e32 v128, v128, v129
	v_mov_b32_e32 v129, v128
	s_nop 1
	v_permlane32_swap_b32_e32 v128, v129
	s_and_saveexec_b64 s[0:1], s[8:9]
	s_cbranch_execz .LBB0_699
	v_add_f32_e32 v128, v128, v129
	global_atomic_add_f32 v[152:153], v128, off offset:64
.LBB0_699:
	s_or_b64 exec, exec, s[0:1]
	v_add_u32_e32 v136, 32, v194
	v_ashrrev_i32_e32 v137, 31, v136
	v_lshlrev_b64 v[128:129], 10, v[136:137]
	s_movk_i32 s0, 0xfe0
	v_lshl_add_u64 v[138:139], v[128:129], 0, v[192:193]
	v_cmp_gt_i32_e64 s[0:1], s0, v194
	s_and_b64 vcc, exec, s[6:7]
	s_mov_b64 s[2:3], -1
	s_cbranch_vccnz .LBB0_701
	v_lshl_add_u64 v[128:129], v[138:139], 1, s[14:15]
	s_mov_b64 s[2:3], 0
	s_waitcnt vmcnt(11)
	v_lshlrev_b32_e32 v132, 16, v210
	v_and_b32_e32 v133, 0xffff0000, v210
	v_lshlrev_b32_e32 v134, 16, v211
	v_and_b32_e32 v135, 0xffff0000, v211
	v_lshlrev_b32_e32 v128, 16, v212
	v_and_b32_e32 v129, 0xffff0000, v212
	v_lshlrev_b32_e32 v130, 16, v213
	v_and_b32_e32 v131, 0xffff0000, v213
	s_mov_b64 s[80:81], 0x28000
	v_lshl_add_u64 v[222:223], v[222:223], 0, s[80:81]
	global_load_dwordx4 v[210:213], v[222:223], off
.LBB0_701:
	v_add_u32_e32 v168, 0xfffff020, v194
	v_lshlrev_b64 v[136:137], 12, v[136:137]
	v_lshlrev_b64 v[140:141], 12, v[168:169]
	v_lshl_add_u64 v[136:137], s[10:11], 0, v[136:137]
	v_lshl_add_u64 v[140:141], s[12:13], 0, v[140:141]
	v_cndmask_b32_e64 v137, v141, v137, s[0:1]
	v_cndmask_b32_e64 v136, v140, v136, s[0:1]
	s_andn2_b64 vcc, exec, s[2:3]
	v_lshl_add_u64 v[136:137], v[192:193], 2, v[136:137]
	s_cbranch_vccnz .LBB0_703
	s_waitcnt vmcnt(6)
	v_mov_b32_e32 v128, v214
	v_mov_b32_e32 v129, v215
	v_mov_b32_e32 v130, v216
	v_mov_b32_e32 v131, v217
	v_mov_b32_e32 v132, v210
	v_mov_b32_e32 v133, v211
	v_mov_b32_e32 v134, v212
	v_mov_b32_e32 v135, v213
	s_mov_b64 s[80:81], 0x10000
	v_lshl_add_u64 v[222:223], v[222:223], 0, s[80:81]
	global_load_dwordx4 v[214:217], v[222:223], off offset:16
	global_load_dwordx4 v[210:213], v[222:223], off
.LBB0_703:
	s_waitcnt vmcnt(63)
	v_pk_fma_f32 v[134:135], v[126:127], v[86:87], v[134:135]
	v_pk_fma_f32 v[140:141], v[124:125], v[84:85], v[132:133]
	v_pk_fma_f32 v[132:133], v[122:123], v[82:83], v[130:131]
	v_pk_fma_f32 v[142:143], v[120:121], v[80:81], v[128:129]
	v_lshlrev_b64 v[124:125], 1, v[138:139]
	v_cvt_pk_bf16_f32 v120, v140, v141
	v_cvt_pk_bf16_f32 v121, v134, v135
	v_cvt_pk_bf16_f32 v122, v142, v143
	v_cvt_pk_bf16_f32 v123, v132, v133
	v_lshl_add_u64 v[128:129], s[14:15], 0, v[124:125]
	global_store_dwordx4 v[128:129], v[120:123], off
	v_pk_mul_f32 v[126:127], v[74:75], v[132:133]
	v_pk_mul_f32 v[130:131], v[72:73], v[142:143]
	v_pk_mul_f32 v[122:123], v[78:79], v[134:135]
	v_pk_mul_f32 v[120:121], v[76:77], v[140:141]
	s_and_b64 vcc, exec, s[6:7]
	v_cvt_pk_bf16_f32 v120, v120, v121
	v_cvt_pk_bf16_f32 v121, v122, v123
	v_cvt_pk_bf16_f32 v122, v130, v131
	v_cvt_pk_bf16_f32 v123, v126, v127
	v_lshl_add_u64 v[130:131], s[16:17], 0, v[124:125]
	s_mov_b64 s[0:1], -1
	global_store_dwordx4 v[130:131], v[120:123], off
	s_cbranch_vccnz .LBB0_705
	s_mov_b64 s[0:1], 0
	s_waitcnt vmcnt(11)
	v_lshlrev_b32_e32 v124, 16, v214
	v_and_b32_e32 v125, 0xffff0000, v214
	v_lshlrev_b32_e32 v126, 16, v215
	v_and_b32_e32 v127, 0xffff0000, v215
	v_lshlrev_b32_e32 v120, 16, v216
	v_and_b32_e32 v121, 0xffff0000, v216
	v_lshlrev_b32_e32 v122, 16, v217
	v_and_b32_e32 v123, 0xffff0000, v217
	global_load_dwordx4 v[214:217], v[222:223], off offset:256
.LBB0_705:
	s_andn2_b64 vcc, exec, s[0:1]
	s_cbranch_vccnz .LBB0_707
	s_waitcnt vmcnt(6)
	v_mov_b32_e32 v120, v236
	v_mov_b32_e32 v121, v237
	v_mov_b32_e32 v122, v238
	v_mov_b32_e32 v123, v239
	v_mov_b32_e32 v124, v218
	v_mov_b32_e32 v125, v219
	v_mov_b32_e32 v126, v220
	v_mov_b32_e32 v127, v221
	global_load_dwordx4 v[236:239], v[222:223], off offset:528
	global_load_dwordx4 v[218:221], v[222:223], off offset:512
.LBB0_707:
	s_waitcnt vmcnt(63)
	v_pk_fma_f32 v[118:119], v[118:119], v[70:71], v[126:127]
	v_pk_fma_f32 v[116:117], v[116:117], v[68:69], v[124:125]
	v_pk_fma_f32 v[122:123], v[114:115], v[62:63], v[122:123]
	v_pk_fma_f32 v[120:121], v[112:113], v[60:61], v[120:121]
	v_cvt_pk_bf16_f32 v112, v116, v117
	v_cvt_pk_bf16_f32 v113, v118, v119
	v_cvt_pk_bf16_f32 v114, v120, v121
	v_cvt_pk_bf16_f32 v115, v122, v123
	global_store_dwordx4 v[128:129], v[112:115], off offset:256
	v_pk_mul_f32 v[124:125], v[50:51], v[122:123]
	v_pk_mul_f32 v[126:127], v[48:49], v[120:121]
	v_pk_mul_f32 v[114:115], v[54:55], v[118:119]
	v_pk_mul_f32 v[112:113], v[52:53], v[116:117]
	v_mul_f32_e32 v136, v141, v141
	v_cvt_pk_bf16_f32 v112, v112, v113
	v_cvt_pk_bf16_f32 v113, v114, v115
	v_cvt_pk_bf16_f32 v114, v126, v127
	v_cvt_pk_bf16_f32 v115, v124, v125
	v_mul_f32_e32 v135, v135, v135
	global_store_dwordx4 v[130:131], v[112:115], off offset:256
	v_fmac_f32_e32 v136, v140, v140
	v_fmac_f32_e32 v135, v134, v134
	v_mul_f32_e32 v113, v117, v117
	v_mul_f32_e32 v114, v119, v119
	v_fmac_f32_e32 v113, v116, v116
	v_fmac_f32_e32 v114, v118, v118
	v_add_f32_e32 v134, v136, v135
	v_mul_f32_e32 v135, v143, v143
	v_add_f32_e32 v113, v113, v114
	v_mul_f32_e32 v114, v121, v121
	v_fmac_f32_e32 v135, v142, v142
	v_mul_f32_e32 v133, v133, v133
	v_mul_f32_e32 v112, v123, v123
	v_fmac_f32_e32 v114, v120, v120
	v_add_f32_e32 v134, v134, v135
	v_fmac_f32_e32 v133, v132, v132
	v_fmac_f32_e32 v112, v122, v122
	v_add_f32_e32 v113, v113, v114
	v_add_f32_e32 v132, v133, v134
	v_add_f32_e32 v112, v112, v113
	v_add_f32_e32 v112, v132, v112
	v_mov_b32_e32 v113, v112
	s_nop 1
	v_permlane16_swap_b32_e32 v112, v113
	v_add_f32_e32 v112, v112, v113
	v_mov_b32_e32 v113, v112
	s_nop 1
	v_permlane32_swap_b32_e32 v112, v113
	s_and_saveexec_b64 s[0:1], s[8:9]
	s_cbranch_execz .LBB0_709
	v_add_f32_e32 v112, v112, v113
	global_atomic_add_f32 v[152:153], v112, off offset:128
.LBB0_709:
	s_or_b64 exec, exec, s[0:1]
	v_add_u32_e32 v120, 48, v194
	v_ashrrev_i32_e32 v121, 31, v120
	v_lshlrev_b64 v[112:113], 10, v[120:121]
	s_movk_i32 s0, 0xfd0
	v_lshl_add_u64 v[122:123], v[112:113], 0, v[192:193]
	v_cmp_gt_i32_e64 s[0:1], s0, v194
	s_and_b64 vcc, exec, s[6:7]
	s_mov_b64 s[2:3], -1
	s_cbranch_vccnz .LBB0_711
	v_lshl_add_u64 v[112:113], v[122:123], 1, s[14:15]
	s_mov_b64 s[2:3], 0
	s_waitcnt vmcnt(11)
	v_lshlrev_b32_e32 v116, 16, v218
	v_and_b32_e32 v117, 0xffff0000, v218
	v_lshlrev_b32_e32 v118, 16, v219
	v_and_b32_e32 v119, 0xffff0000, v219
	v_lshlrev_b32_e32 v112, 16, v220
	v_and_b32_e32 v113, 0xffff0000, v220
	v_lshlrev_b32_e32 v114, 16, v221
	v_and_b32_e32 v115, 0xffff0000, v221
	s_mov_b64 s[80:81], 0x8000
	v_lshl_add_u64 v[222:223], v[222:223], 0, s[80:81]
	global_load_dwordx4 v[218:221], v[222:223], off
.LBB0_711:
	v_add_u32_e32 v168, 0xfffff030, v194
	v_lshlrev_b64 v[120:121], 12, v[120:121]
	v_lshlrev_b64 v[124:125], 12, v[168:169]
	v_lshl_add_u64 v[120:121], s[10:11], 0, v[120:121]
	v_lshl_add_u64 v[124:125], s[12:13], 0, v[124:125]
	v_cndmask_b32_e64 v121, v125, v121, s[0:1]
	v_cndmask_b32_e64 v120, v124, v120, s[0:1]
	s_andn2_b64 vcc, exec, s[2:3]
	v_lshl_add_u64 v[120:121], v[192:193], 2, v[120:121]
	s_cbranch_vccnz .LBB0_713
	s_waitcnt vmcnt(6)
	v_mov_b32_e32 v112, v214
	v_mov_b32_e32 v113, v215
	v_mov_b32_e32 v114, v216
	v_mov_b32_e32 v115, v217
	v_mov_b32_e32 v116, v210
	v_mov_b32_e32 v117, v211
	v_mov_b32_e32 v118, v212
	v_mov_b32_e32 v119, v213
	s_mov_b64 s[80:81], 0x50000
	v_lshl_add_u64 v[222:223], v[222:223], 0, s[80:81]
	global_load_dwordx4 v[214:217], v[222:223], off offset:16
	global_load_dwordx4 v[210:213], v[222:223], off
.LBB0_713:
	s_waitcnt vmcnt(63)
	v_pk_fma_f32 v[118:119], v[110:111], v[86:87], v[118:119]
	v_pk_fma_f32 v[124:125], v[108:109], v[84:85], v[116:117]
	v_pk_fma_f32 v[116:117], v[106:107], v[82:83], v[114:115]
	v_pk_fma_f32 v[126:127], v[104:105], v[80:81], v[112:113]
	v_lshlrev_b64 v[108:109], 1, v[122:123]
	v_cvt_pk_bf16_f32 v104, v124, v125
	v_cvt_pk_bf16_f32 v105, v118, v119
	v_cvt_pk_bf16_f32 v106, v126, v127
	v_cvt_pk_bf16_f32 v107, v116, v117
	v_lshl_add_u64 v[112:113], s[14:15], 0, v[108:109]
	global_store_dwordx4 v[112:113], v[104:107], off
	v_pk_mul_f32 v[110:111], v[74:75], v[116:117]
	v_pk_mul_f32 v[114:115], v[72:73], v[126:127]
	v_pk_mul_f32 v[106:107], v[78:79], v[118:119]
	v_pk_mul_f32 v[104:105], v[76:77], v[124:125]
	s_and_b64 vcc, exec, s[6:7]
	v_cvt_pk_bf16_f32 v104, v104, v105
	v_cvt_pk_bf16_f32 v105, v106, v107
	v_cvt_pk_bf16_f32 v106, v114, v115
	v_cvt_pk_bf16_f32 v107, v110, v111
	v_lshl_add_u64 v[114:115], s[16:17], 0, v[108:109]
	s_mov_b64 s[0:1], -1
	global_store_dwordx4 v[114:115], v[104:107], off
	s_cbranch_vccnz .LBB0_715
	s_mov_b64 s[0:1], 0
	s_waitcnt vmcnt(11)
	v_lshlrev_b32_e32 v108, 16, v236
	v_and_b32_e32 v109, 0xffff0000, v236
	v_lshlrev_b32_e32 v110, 16, v237
	v_and_b32_e32 v111, 0xffff0000, v237
	v_lshlrev_b32_e32 v104, 16, v238
	v_and_b32_e32 v105, 0xffff0000, v238
	v_lshlrev_b32_e32 v106, 16, v239
	v_and_b32_e32 v107, 0xffff0000, v239
	global_load_dwordx4 v[236:239], v[222:223], off offset:256
.LBB0_715:
	s_andn2_b64 vcc, exec, s[0:1]
	s_cbranch_vccnz .LBB0_717
	s_waitcnt vmcnt(6)
	v_mov_b32_e32 v104, v236
	v_mov_b32_e32 v105, v237
	v_mov_b32_e32 v106, v238
	v_mov_b32_e32 v107, v239
	v_mov_b32_e32 v108, v218
	v_mov_b32_e32 v109, v219
	v_mov_b32_e32 v110, v220
	v_mov_b32_e32 v111, v221
	global_load_dwordx4 v[236:239], v[222:223], off offset:528
	global_load_dwordx4 v[218:221], v[222:223], off offset:512
.LBB0_717:
	s_waitcnt vmcnt(63)
	v_pk_fma_f32 v[102:103], v[102:103], v[70:71], v[110:111]
	v_pk_fma_f32 v[100:101], v[100:101], v[68:69], v[108:109]
	v_pk_fma_f32 v[106:107], v[98:99], v[62:63], v[106:107]
	v_pk_fma_f32 v[104:105], v[96:97], v[60:61], v[104:105]
	v_cvt_pk_bf16_f32 v96, v100, v101
	v_cvt_pk_bf16_f32 v97, v102, v103
	v_cvt_pk_bf16_f32 v98, v104, v105
	v_cvt_pk_bf16_f32 v99, v106, v107
	global_store_dwordx4 v[112:113], v[96:99], off offset:256
	v_pk_mul_f32 v[108:109], v[50:51], v[106:107]
	v_pk_mul_f32 v[110:111], v[48:49], v[104:105]
	v_pk_mul_f32 v[98:99], v[54:55], v[102:103]
	v_pk_mul_f32 v[96:97], v[52:53], v[100:101]
	v_mul_f32_e32 v120, v125, v125
	v_cvt_pk_bf16_f32 v96, v96, v97
	v_cvt_pk_bf16_f32 v97, v98, v99
	v_cvt_pk_bf16_f32 v98, v110, v111
	v_cvt_pk_bf16_f32 v99, v108, v109
	v_mul_f32_e32 v119, v119, v119
	global_store_dwordx4 v[114:115], v[96:99], off offset:256
	v_fmac_f32_e32 v120, v124, v124
	v_fmac_f32_e32 v119, v118, v118
	v_mul_f32_e32 v97, v101, v101
	v_mul_f32_e32 v98, v103, v103
	v_fmac_f32_e32 v97, v100, v100
	v_fmac_f32_e32 v98, v102, v102
	v_add_f32_e32 v118, v120, v119
	v_mul_f32_e32 v119, v127, v127
	v_add_f32_e32 v97, v97, v98
	v_mul_f32_e32 v98, v105, v105
	v_fmac_f32_e32 v119, v126, v126
	v_mul_f32_e32 v117, v117, v117
	v_mul_f32_e32 v96, v107, v107
	v_fmac_f32_e32 v98, v104, v104
	v_add_f32_e32 v118, v118, v119
	v_fmac_f32_e32 v117, v116, v116
	v_fmac_f32_e32 v96, v106, v106
	v_add_f32_e32 v97, v97, v98
	v_add_f32_e32 v116, v117, v118
	v_add_f32_e32 v96, v96, v97
	v_add_f32_e32 v96, v116, v96
	v_mov_b32_e32 v97, v96
	s_nop 1
	v_permlane16_swap_b32_e32 v96, v97
	v_add_f32_e32 v96, v96, v97
	v_mov_b32_e32 v97, v96
	s_nop 1
	v_permlane32_swap_b32_e32 v96, v97
	s_and_saveexec_b64 s[0:1], s[8:9]
	s_cbranch_execz .LBB0_719
	v_add_f32_e32 v96, v96, v97
	global_atomic_add_f32 v[152:153], v96, off offset:192
.LBB0_719:
	s_or_b64 exec, exec, s[0:1]
	v_add_u32_e32 v104, 0x80, v194
	v_ashrrev_i32_e32 v105, 31, v104
	v_lshlrev_b64 v[96:97], 10, v[104:105]
	s_movk_i32 s0, 0xf80
	v_lshl_add_u64 v[106:107], v[96:97], 0, v[192:193]
	v_cmp_gt_i32_e64 s[0:1], s0, v194
	s_and_b64 vcc, exec, s[6:7]
	s_mov_b64 s[2:3], -1
	s_cbranch_vccnz .LBB0_721
	v_lshl_add_u64 v[96:97], v[106:107], 1, s[14:15]
	s_mov_b64 s[2:3], 0
	s_waitcnt vmcnt(11)
	v_lshlrev_b32_e32 v100, 16, v210
	v_and_b32_e32 v101, 0xffff0000, v210
	v_lshlrev_b32_e32 v102, 16, v211
	v_and_b32_e32 v103, 0xffff0000, v211
	v_lshlrev_b32_e32 v96, 16, v212
	v_and_b32_e32 v97, 0xffff0000, v212
	v_lshlrev_b32_e32 v98, 16, v213
	v_and_b32_e32 v99, 0xffff0000, v213
	s_mov_b64 s[80:81], 0x8000
	v_lshl_add_u64 v[222:223], v[222:223], 0, s[80:81]
	global_load_dwordx4 v[210:213], v[222:223], off
.LBB0_721:
	v_add_u32_e32 v168, 0xfffff080, v194
	v_lshlrev_b64 v[104:105], 12, v[104:105]
	v_lshlrev_b64 v[108:109], 12, v[168:169]
	v_lshl_add_u64 v[104:105], s[10:11], 0, v[104:105]
	v_lshl_add_u64 v[108:109], s[12:13], 0, v[108:109]
	v_cndmask_b32_e64 v105, v109, v105, s[0:1]
	v_cndmask_b32_e64 v104, v108, v104, s[0:1]
	s_andn2_b64 vcc, exec, s[2:3]
	v_lshl_add_u64 v[104:105], v[192:193], 2, v[104:105]
	s_cbranch_vccnz .LBB0_723
	s_waitcnt vmcnt(6)
	v_mov_b32_e32 v96, v214
	v_mov_b32_e32 v97, v215
	v_mov_b32_e32 v98, v216
	v_mov_b32_e32 v99, v217
	v_mov_b32_e32 v100, v210
	v_mov_b32_e32 v101, v211
	v_mov_b32_e32 v102, v212
	v_mov_b32_e32 v103, v213
	s_mov_b64 s[80:81], 0x10000
	v_lshl_add_u64 v[222:223], v[222:223], 0, s[80:81]
	global_load_dwordx4 v[214:217], v[222:223], off offset:16
	global_load_dwordx4 v[210:213], v[222:223], off
.LBB0_723:
	s_waitcnt vmcnt(63)
	v_pk_fma_f32 v[102:103], v[94:95], v[86:87], v[102:103]
	v_pk_fma_f32 v[108:109], v[92:93], v[84:85], v[100:101]
	v_pk_fma_f32 v[100:101], v[90:91], v[82:83], v[98:99]
	v_pk_fma_f32 v[110:111], v[88:89], v[80:81], v[96:97]
	v_lshlrev_b64 v[92:93], 1, v[106:107]
	v_cvt_pk_bf16_f32 v88, v108, v109
	v_cvt_pk_bf16_f32 v89, v102, v103
	v_cvt_pk_bf16_f32 v90, v110, v111
	v_cvt_pk_bf16_f32 v91, v100, v101
	v_lshl_add_u64 v[96:97], s[14:15], 0, v[92:93]
	global_store_dwordx4 v[96:97], v[88:91], off
	v_pk_mul_f32 v[94:95], v[74:75], v[100:101]
	v_pk_mul_f32 v[98:99], v[72:73], v[110:111]
	v_pk_mul_f32 v[90:91], v[78:79], v[102:103]
	v_pk_mul_f32 v[88:89], v[76:77], v[108:109]
	s_and_b64 vcc, exec, s[6:7]
	v_cvt_pk_bf16_f32 v88, v88, v89
	v_cvt_pk_bf16_f32 v89, v90, v91
	v_cvt_pk_bf16_f32 v90, v98, v99
	v_cvt_pk_bf16_f32 v91, v94, v95
	v_lshl_add_u64 v[98:99], s[16:17], 0, v[92:93]
	s_mov_b64 s[0:1], -1
	global_store_dwordx4 v[98:99], v[88:91], off
	s_cbranch_vccnz .LBB0_725
	s_mov_b64 s[0:1], 0
	s_waitcnt vmcnt(11)
	v_lshlrev_b32_e32 v92, 16, v214
	v_and_b32_e32 v93, 0xffff0000, v214
	v_lshlrev_b32_e32 v94, 16, v215
	v_and_b32_e32 v95, 0xffff0000, v215
	v_lshlrev_b32_e32 v88, 16, v216
	v_and_b32_e32 v89, 0xffff0000, v216
	v_lshlrev_b32_e32 v90, 16, v217
	v_and_b32_e32 v91, 0xffff0000, v217
	global_load_dwordx4 v[214:217], v[222:223], off offset:256
.LBB0_725:
	s_andn2_b64 vcc, exec, s[0:1]
	s_cbranch_vccnz .LBB0_727
	s_waitcnt vmcnt(6)
	v_mov_b32_e32 v88, v236
	v_mov_b32_e32 v89, v237
	v_mov_b32_e32 v90, v238
	v_mov_b32_e32 v91, v239
	v_mov_b32_e32 v92, v218
	v_mov_b32_e32 v93, v219
	v_mov_b32_e32 v94, v220
	v_mov_b32_e32 v95, v221
	global_load_dwordx4 v[236:239], v[222:223], off offset:528
	global_load_dwordx4 v[218:221], v[222:223], off offset:512
.LBB0_727:
	s_waitcnt vmcnt(63)
	v_pk_fma_f32 v[66:67], v[66:67], v[70:71], v[94:95]
	v_pk_fma_f32 v[64:65], v[64:65], v[68:69], v[92:93]
	v_pk_fma_f32 v[90:91], v[58:59], v[62:63], v[90:91]
	v_pk_fma_f32 v[88:89], v[56:57], v[60:61], v[88:89]
	v_cvt_pk_bf16_f32 v56, v64, v65
	v_cvt_pk_bf16_f32 v57, v66, v67
	v_cvt_pk_bf16_f32 v58, v88, v89
	v_cvt_pk_bf16_f32 v59, v90, v91
	global_store_dwordx4 v[96:97], v[56:59], off offset:256
	v_pk_mul_f32 v[92:93], v[50:51], v[90:91]
	v_pk_mul_f32 v[94:95], v[48:49], v[88:89]
	v_pk_mul_f32 v[58:59], v[54:55], v[66:67]
	v_pk_mul_f32 v[56:57], v[52:53], v[64:65]
	v_mul_f32_e32 v104, v109, v109
	v_cvt_pk_bf16_f32 v56, v56, v57
	v_cvt_pk_bf16_f32 v57, v58, v59
	v_cvt_pk_bf16_f32 v58, v94, v95
	v_cvt_pk_bf16_f32 v59, v92, v93
	v_mul_f32_e32 v103, v103, v103
	global_store_dwordx4 v[98:99], v[56:59], off offset:256
	v_fmac_f32_e32 v104, v108, v108
	v_fmac_f32_e32 v103, v102, v102
	v_mul_f32_e32 v57, v65, v65
	v_mul_f32_e32 v58, v67, v67
	v_fmac_f32_e32 v57, v64, v64
	v_fmac_f32_e32 v58, v66, v66
	v_add_f32_e32 v102, v104, v103
	v_mul_f32_e32 v103, v111, v111
	v_add_f32_e32 v57, v57, v58
	v_mul_f32_e32 v58, v89, v89
	v_fmac_f32_e32 v103, v110, v110
	v_mul_f32_e32 v101, v101, v101
	v_mul_f32_e32 v56, v91, v91
	v_fmac_f32_e32 v58, v88, v88
	v_add_f32_e32 v102, v102, v103
	v_fmac_f32_e32 v101, v100, v100
	v_fmac_f32_e32 v56, v90, v90
	v_add_f32_e32 v57, v57, v58
	v_add_f32_e32 v100, v101, v102
	v_add_f32_e32 v56, v56, v57
	v_add_f32_e32 v56, v100, v56
	v_mov_b32_e32 v57, v56
	s_nop 1
	v_permlane16_swap_b32_e32 v56, v57
	v_add_f32_e32 v56, v56, v57
	v_mov_b32_e32 v57, v56
	s_nop 1
	v_permlane32_swap_b32_e32 v56, v57
	s_and_saveexec_b64 s[0:1], s[8:9]
	s_cbranch_execz .LBB0_729
	v_add_f32_e32 v56, v56, v57
	global_atomic_add_f32 v[152:153], v56, off offset:512
.LBB0_729:
	s_or_b64 exec, exec, s[0:1]
	v_add_u32_e32 v88, 0x90, v194
	v_ashrrev_i32_e32 v89, 31, v88
	v_lshlrev_b64 v[56:57], 10, v[88:89]
	s_movk_i32 s0, 0xf70
	v_lshl_add_u64 v[90:91], v[56:57], 0, v[192:193]
	v_cmp_gt_i32_e64 s[0:1], s0, v194
	s_and_b64 vcc, exec, s[6:7]
	s_mov_b64 s[2:3], -1
	s_cbranch_vccnz .LBB0_731
	v_lshl_add_u64 v[56:57], v[90:91], 1, s[14:15]
	s_mov_b64 s[2:3], 0
	s_waitcnt vmcnt(11)
	v_lshlrev_b32_e32 v64, 16, v218
	v_and_b32_e32 v65, 0xffff0000, v218
	v_lshlrev_b32_e32 v66, 16, v219
	v_and_b32_e32 v67, 0xffff0000, v219
	v_lshlrev_b32_e32 v56, 16, v220
	v_and_b32_e32 v57, 0xffff0000, v220
	v_lshlrev_b32_e32 v58, 16, v221
	v_and_b32_e32 v59, 0xffff0000, v221
	s_mov_b64 s[80:81], 0x8000
	v_lshl_add_u64 v[222:223], v[222:223], 0, s[80:81]
	global_load_dwordx4 v[218:221], v[222:223], off
.LBB0_731:
	v_add_u32_e32 v168, 0xfffff090, v194
	v_lshlrev_b64 v[88:89], 12, v[88:89]
	v_lshlrev_b64 v[92:93], 12, v[168:169]
	v_lshl_add_u64 v[88:89], s[10:11], 0, v[88:89]
	v_lshl_add_u64 v[92:93], s[12:13], 0, v[92:93]
	v_cndmask_b32_e64 v89, v93, v89, s[0:1]
	v_cndmask_b32_e64 v88, v92, v88, s[0:1]
	s_andn2_b64 vcc, exec, s[2:3]
	v_lshl_add_u64 v[88:89], v[192:193], 2, v[88:89]
	s_cbranch_vccnz .LBB0_733
	s_waitcnt vmcnt(6)
	v_mov_b32_e32 v56, v214
	v_mov_b32_e32 v57, v215
	v_mov_b32_e32 v58, v216
	v_mov_b32_e32 v59, v217
	v_mov_b32_e32 v64, v210
	v_mov_b32_e32 v65, v211
	v_mov_b32_e32 v66, v212
	v_mov_b32_e32 v67, v213
	s_mov_b64 s[80:81], 0x10000
	v_lshl_add_u64 v[222:223], v[222:223], 0, s[80:81]
	global_load_dwordx4 v[214:217], v[222:223], off offset:16
	global_load_dwordx4 v[210:213], v[222:223], off
.LBB0_733:
	s_waitcnt vmcnt(63)
	v_pk_fma_f32 v[66:67], v[46:47], v[86:87], v[66:67]
	v_pk_fma_f32 v[92:93], v[44:45], v[84:85], v[64:65]
	v_pk_fma_f32 v[64:65], v[42:43], v[82:83], v[58:59]
	v_pk_fma_f32 v[94:95], v[40:41], v[80:81], v[56:57]
	v_lshlrev_b64 v[44:45], 1, v[90:91]
	v_cvt_pk_bf16_f32 v40, v92, v93
	v_cvt_pk_bf16_f32 v41, v66, v67
	v_cvt_pk_bf16_f32 v42, v94, v95
	v_cvt_pk_bf16_f32 v43, v64, v65
	v_lshl_add_u64 v[56:57], s[14:15], 0, v[44:45]
	global_store_dwordx4 v[56:57], v[40:43], off
	v_pk_mul_f32 v[46:47], v[74:75], v[64:65]
	v_pk_mul_f32 v[58:59], v[72:73], v[94:95]
	v_pk_mul_f32 v[42:43], v[78:79], v[66:67]
	v_pk_mul_f32 v[40:41], v[76:77], v[92:93]
	s_and_b64 vcc, exec, s[6:7]
	v_cvt_pk_bf16_f32 v40, v40, v41
	v_cvt_pk_bf16_f32 v41, v42, v43
	v_cvt_pk_bf16_f32 v42, v58, v59
	v_cvt_pk_bf16_f32 v43, v46, v47
	v_lshl_add_u64 v[58:59], s[16:17], 0, v[44:45]
	s_mov_b64 s[0:1], -1
	global_store_dwordx4 v[58:59], v[40:43], off
	s_cbranch_vccnz .LBB0_735
	s_mov_b64 s[0:1], 0
	s_waitcnt vmcnt(11)
	v_lshlrev_b32_e32 v44, 16, v236
	v_and_b32_e32 v45, 0xffff0000, v236
	v_lshlrev_b32_e32 v46, 16, v237
	v_and_b32_e32 v47, 0xffff0000, v237
	v_lshlrev_b32_e32 v40, 16, v238
	v_and_b32_e32 v41, 0xffff0000, v238
	v_lshlrev_b32_e32 v42, 16, v239
	v_and_b32_e32 v43, 0xffff0000, v239
	global_load_dwordx4 v[236:239], v[222:223], off offset:256
.LBB0_735:
	s_andn2_b64 vcc, exec, s[0:1]
	s_cbranch_vccnz .LBB0_737
	s_waitcnt vmcnt(6)
	v_mov_b32_e32 v40, v236
	v_mov_b32_e32 v41, v237
	v_mov_b32_e32 v42, v238
	v_mov_b32_e32 v43, v239
	v_mov_b32_e32 v44, v218
	v_mov_b32_e32 v45, v219
	v_mov_b32_e32 v46, v220
	v_mov_b32_e32 v47, v221
	global_load_dwordx4 v[236:239], v[222:223], off offset:528
	global_load_dwordx4 v[218:221], v[222:223], off offset:512
.LBB0_737:
	s_waitcnt vmcnt(63)
	v_pk_fma_f32 v[38:39], v[38:39], v[70:71], v[46:47]
	v_pk_fma_f32 v[36:37], v[36:37], v[68:69], v[44:45]
	v_pk_fma_f32 v[42:43], v[34:35], v[62:63], v[42:43]
	v_pk_fma_f32 v[40:41], v[32:33], v[60:61], v[40:41]
	v_cvt_pk_bf16_f32 v32, v36, v37
	v_cvt_pk_bf16_f32 v33, v38, v39
	v_cvt_pk_bf16_f32 v34, v40, v41
	v_cvt_pk_bf16_f32 v35, v42, v43
	global_store_dwordx4 v[56:57], v[32:35], off offset:256
	v_pk_mul_f32 v[44:45], v[50:51], v[42:43]
	v_pk_mul_f32 v[46:47], v[48:49], v[40:41]
	v_pk_mul_f32 v[34:35], v[54:55], v[38:39]
	v_pk_mul_f32 v[32:33], v[52:53], v[36:37]
	v_mul_f32_e32 v88, v93, v93
	v_cvt_pk_bf16_f32 v32, v32, v33
	v_cvt_pk_bf16_f32 v33, v34, v35
	v_cvt_pk_bf16_f32 v34, v46, v47
	v_cvt_pk_bf16_f32 v35, v44, v45
	v_mul_f32_e32 v67, v67, v67
	global_store_dwordx4 v[58:59], v[32:35], off offset:256
	v_fmac_f32_e32 v88, v92, v92
	v_fmac_f32_e32 v67, v66, v66
	v_mul_f32_e32 v33, v37, v37
	v_mul_f32_e32 v34, v39, v39
	v_fmac_f32_e32 v33, v36, v36
	v_fmac_f32_e32 v34, v38, v38
	v_add_f32_e32 v66, v88, v67
	v_mul_f32_e32 v67, v95, v95
	v_add_f32_e32 v33, v33, v34
	v_mul_f32_e32 v34, v41, v41
	v_fmac_f32_e32 v67, v94, v94
	v_mul_f32_e32 v65, v65, v65
	v_mul_f32_e32 v32, v43, v43
	v_fmac_f32_e32 v34, v40, v40
	v_add_f32_e32 v66, v66, v67
	v_fmac_f32_e32 v65, v64, v64
	v_fmac_f32_e32 v32, v42, v42
	v_add_f32_e32 v33, v33, v34
	v_add_f32_e32 v64, v65, v66
	v_add_f32_e32 v32, v32, v33
	v_add_f32_e32 v32, v64, v32
	v_mov_b32_e32 v33, v32
	s_nop 1
	v_permlane16_swap_b32_e32 v32, v33
	v_add_f32_e32 v32, v32, v33
	v_mov_b32_e32 v33, v32
	s_nop 1
	v_permlane32_swap_b32_e32 v32, v33
	s_and_saveexec_b64 s[0:1], s[8:9]
	s_cbranch_execz .LBB0_739
	v_add_f32_e32 v32, v32, v33
	global_atomic_add_f32 v[152:153], v32, off offset:576
.LBB0_739:
	s_or_b64 exec, exec, s[0:1]
	v_add_u32_e32 v40, 0xa0, v194
	v_ashrrev_i32_e32 v41, 31, v40
	v_lshlrev_b64 v[32:33], 10, v[40:41]
	s_movk_i32 s0, 0xf60
	v_lshl_add_u64 v[42:43], v[32:33], 0, v[192:193]
	v_cmp_gt_i32_e64 s[0:1], s0, v194
	s_and_b64 vcc, exec, s[6:7]
	s_mov_b64 s[2:3], -1
	s_cbranch_vccnz .LBB0_741
	v_lshl_add_u64 v[32:33], v[42:43], 1, s[14:15]
	s_mov_b64 s[2:3], 0
	s_waitcnt vmcnt(11)
	v_lshlrev_b32_e32 v36, 16, v210
	v_and_b32_e32 v37, 0xffff0000, v210
	v_lshlrev_b32_e32 v38, 16, v211
	v_and_b32_e32 v39, 0xffff0000, v211
	v_lshlrev_b32_e32 v32, 16, v212
	v_and_b32_e32 v33, 0xffff0000, v212
	v_lshlrev_b32_e32 v34, 16, v213
	v_and_b32_e32 v35, 0xffff0000, v213
.LBB0_741:
	v_add_u32_e32 v168, 0xfffff0a0, v194
	v_lshlrev_b64 v[40:41], 12, v[40:41]
	v_lshlrev_b64 v[44:45], 12, v[168:169]
	v_lshl_add_u64 v[40:41], s[10:11], 0, v[40:41]
	v_lshl_add_u64 v[44:45], s[12:13], 0, v[44:45]
	v_cndmask_b32_e64 v41, v45, v41, s[0:1]
	v_cndmask_b32_e64 v40, v44, v40, s[0:1]
	s_andn2_b64 vcc, exec, s[2:3]
	v_lshl_add_u64 v[40:41], v[192:193], 2, v[40:41]
	s_cbranch_vccnz .LBB0_743
	s_waitcnt vmcnt(6)
	v_mov_b32_e32 v32, v214
	v_mov_b32_e32 v33, v215
	v_mov_b32_e32 v34, v216
	v_mov_b32_e32 v35, v217
	v_mov_b32_e32 v36, v210
	v_mov_b32_e32 v37, v211
	v_mov_b32_e32 v38, v212
	v_mov_b32_e32 v39, v213
	s_mov_b64 s[80:81], 0x10000
	v_lshl_add_u64 v[222:223], v[222:223], 0, s[80:81]
	global_load_dwordx4 v[214:217], v[222:223], off offset:16
	global_load_dwordx4 v[210:213], v[222:223], off
.LBB0_743:
	s_waitcnt vmcnt(63)
	v_pk_fma_f32 v[38:39], v[30:31], v[86:87], v[38:39]
	v_pk_fma_f32 v[44:45], v[28:29], v[84:85], v[36:37]
	v_pk_fma_f32 v[36:37], v[26:27], v[82:83], v[34:35]
	v_pk_fma_f32 v[46:47], v[24:25], v[80:81], v[32:33]
	v_lshlrev_b64 v[28:29], 1, v[42:43]
	v_cvt_pk_bf16_f32 v24, v44, v45
	v_cvt_pk_bf16_f32 v25, v38, v39
	v_cvt_pk_bf16_f32 v26, v46, v47
	v_cvt_pk_bf16_f32 v27, v36, v37
	v_lshl_add_u64 v[32:33], s[14:15], 0, v[28:29]
	global_store_dwordx4 v[32:33], v[24:27], off
	v_pk_mul_f32 v[30:31], v[74:75], v[36:37]
	v_pk_mul_f32 v[34:35], v[72:73], v[46:47]
	v_pk_mul_f32 v[26:27], v[78:79], v[38:39]
	v_pk_mul_f32 v[24:25], v[76:77], v[44:45]
	s_and_b64 vcc, exec, s[6:7]
	v_cvt_pk_bf16_f32 v24, v24, v25
	v_cvt_pk_bf16_f32 v25, v26, v27
	v_cvt_pk_bf16_f32 v26, v34, v35
	v_cvt_pk_bf16_f32 v27, v30, v31
	v_lshl_add_u64 v[34:35], s[16:17], 0, v[28:29]
	s_mov_b64 s[0:1], -1
	global_store_dwordx4 v[34:35], v[24:27], off
	s_cbranch_vccnz .LBB0_745
	s_mov_b64 s[0:1], 0
	s_waitcnt vmcnt(10)
	v_lshlrev_b32_e32 v28, 16, v214
	v_and_b32_e32 v29, 0xffff0000, v214
	v_lshlrev_b32_e32 v30, 16, v215
	v_and_b32_e32 v31, 0xffff0000, v215
	v_lshlrev_b32_e32 v24, 16, v216
	v_and_b32_e32 v25, 0xffff0000, v216
	v_lshlrev_b32_e32 v26, 16, v217
	v_and_b32_e32 v27, 0xffff0000, v217
.LBB0_745:
	s_andn2_b64 vcc, exec, s[0:1]
	s_cbranch_vccnz .LBB0_747
	s_waitcnt vmcnt(6)
	v_mov_b32_e32 v24, v236
	v_mov_b32_e32 v25, v237
	v_mov_b32_e32 v26, v238
	v_mov_b32_e32 v27, v239
	v_mov_b32_e32 v28, v218
	v_mov_b32_e32 v29, v219
	v_mov_b32_e32 v30, v220
	v_mov_b32_e32 v31, v221
	global_load_dwordx4 v[236:239], v[222:223], off offset:528
	global_load_dwordx4 v[218:221], v[222:223], off offset:512
.LBB0_747:
	s_waitcnt vmcnt(63)
	v_pk_fma_f32 v[22:23], v[22:23], v[70:71], v[30:31]
	v_pk_fma_f32 v[20:21], v[20:21], v[68:69], v[28:29]
	v_pk_fma_f32 v[26:27], v[18:19], v[62:63], v[26:27]
	v_pk_fma_f32 v[24:25], v[16:17], v[60:61], v[24:25]
	v_cvt_pk_bf16_f32 v16, v20, v21
	v_cvt_pk_bf16_f32 v17, v22, v23
	v_cvt_pk_bf16_f32 v18, v24, v25
	v_cvt_pk_bf16_f32 v19, v26, v27
	global_store_dwordx4 v[32:33], v[16:19], off offset:256
	v_pk_mul_f32 v[28:29], v[50:51], v[26:27]
	v_pk_mul_f32 v[30:31], v[48:49], v[24:25]
	v_pk_mul_f32 v[18:19], v[54:55], v[22:23]
	v_pk_mul_f32 v[16:17], v[52:53], v[20:21]
	v_mul_f32_e32 v40, v45, v45
	v_cvt_pk_bf16_f32 v16, v16, v17
	v_cvt_pk_bf16_f32 v17, v18, v19
	v_cvt_pk_bf16_f32 v18, v30, v31
	v_cvt_pk_bf16_f32 v19, v28, v29
	v_mul_f32_e32 v39, v39, v39
	global_store_dwordx4 v[34:35], v[16:19], off offset:256
	v_fmac_f32_e32 v40, v44, v44
	v_fmac_f32_e32 v39, v38, v38
	v_mul_f32_e32 v17, v21, v21
	v_mul_f32_e32 v18, v23, v23
	v_fmac_f32_e32 v17, v20, v20
	v_fmac_f32_e32 v18, v22, v22
	v_add_f32_e32 v38, v40, v39
	v_mul_f32_e32 v39, v47, v47
	v_add_f32_e32 v17, v17, v18
	v_mul_f32_e32 v18, v25, v25
	v_fmac_f32_e32 v39, v46, v46
	v_mul_f32_e32 v37, v37, v37
	v_mul_f32_e32 v16, v27, v27
	v_fmac_f32_e32 v18, v24, v24
	v_add_f32_e32 v38, v38, v39
	v_fmac_f32_e32 v37, v36, v36
	v_fmac_f32_e32 v16, v26, v26
	v_add_f32_e32 v17, v17, v18
	v_add_f32_e32 v36, v37, v38
	v_add_f32_e32 v16, v16, v17
	v_add_f32_e32 v16, v36, v16
	v_mov_b32_e32 v17, v16
	s_nop 1
	v_permlane16_swap_b32_e32 v16, v17
	v_add_f32_e32 v16, v16, v17
	v_mov_b32_e32 v17, v16
	s_nop 1
	v_permlane32_swap_b32_e32 v16, v17
	s_and_saveexec_b64 s[0:1], s[8:9]
	s_cbranch_execz .LBB0_749
	v_add_f32_e32 v16, v16, v17
	global_atomic_add_f32 v[152:153], v16, off offset:640
.LBB0_749:
	s_or_b64 exec, exec, s[0:1]
	v_add_u32_e32 v24, 0xb0, v194
	v_ashrrev_i32_e32 v25, 31, v24
	v_lshlrev_b64 v[16:17], 10, v[24:25]
	s_movk_i32 s0, 0xf50
	v_lshl_add_u64 v[26:27], v[16:17], 0, v[192:193]
	v_cmp_gt_i32_e64 s[0:1], s0, v194
	s_and_b64 vcc, exec, s[6:7]
	s_mov_b64 s[2:3], -1
	s_cbranch_vccnz .LBB0_751
	v_lshl_add_u64 v[16:17], v[26:27], 1, s[14:15]
	s_mov_b64 s[2:3], 0
	s_waitcnt vmcnt(9)
	v_lshlrev_b32_e32 v20, 16, v218
	v_and_b32_e32 v21, 0xffff0000, v218
	v_lshlrev_b32_e32 v22, 16, v219
	v_and_b32_e32 v23, 0xffff0000, v219
	v_lshlrev_b32_e32 v16, 16, v220
	v_and_b32_e32 v17, 0xffff0000, v220
	v_lshlrev_b32_e32 v18, 16, v221
	v_and_b32_e32 v19, 0xffff0000, v221
.LBB0_751:
	v_add_u32_e32 v168, 0xfffff0b0, v194
	v_lshlrev_b64 v[24:25], 12, v[24:25]
	v_lshlrev_b64 v[28:29], 12, v[168:169]
	v_lshl_add_u64 v[24:25], s[10:11], 0, v[24:25]
	v_lshl_add_u64 v[28:29], s[12:13], 0, v[28:29]
	v_cndmask_b32_e64 v25, v29, v25, s[0:1]
	v_cndmask_b32_e64 v24, v28, v24, s[0:1]
	s_andn2_b64 vcc, exec, s[2:3]
	v_lshl_add_u64 v[24:25], v[192:193], 2, v[24:25]
	s_cbranch_vccnz .LBB0_753
	s_waitcnt vmcnt(6)
	v_mov_b32_e32 v16, v214
	v_mov_b32_e32 v17, v215
	v_mov_b32_e32 v18, v216
	v_mov_b32_e32 v19, v217
	v_mov_b32_e32 v20, v210
	v_mov_b32_e32 v21, v211
	v_mov_b32_e32 v22, v212
	v_mov_b32_e32 v23, v213
.LBB0_753:
	s_waitcnt vmcnt(63)
	v_pk_fma_f32 v[22:23], v[14:15], v[86:87], v[22:23]
	v_pk_fma_f32 v[28:29], v[12:13], v[84:85], v[20:21]
	v_pk_fma_f32 v[20:21], v[10:11], v[82:83], v[18:19]
	v_pk_fma_f32 v[30:31], v[8:9], v[80:81], v[16:17]
	v_lshlrev_b64 v[12:13], 1, v[26:27]
	v_cvt_pk_bf16_f32 v8, v28, v29
	v_cvt_pk_bf16_f32 v9, v22, v23
	v_cvt_pk_bf16_f32 v10, v30, v31
	v_cvt_pk_bf16_f32 v11, v20, v21
	v_lshl_add_u64 v[16:17], s[14:15], 0, v[12:13]
	global_store_dwordx4 v[16:17], v[8:11], off
	v_pk_mul_f32 v[14:15], v[74:75], v[20:21]
	v_pk_mul_f32 v[18:19], v[72:73], v[30:31]
	v_pk_mul_f32 v[10:11], v[78:79], v[22:23]
	v_pk_mul_f32 v[8:9], v[76:77], v[28:29]
	s_and_b64 vcc, exec, s[6:7]
	v_cvt_pk_bf16_f32 v8, v8, v9
	v_cvt_pk_bf16_f32 v9, v10, v11
	v_cvt_pk_bf16_f32 v10, v18, v19
	v_cvt_pk_bf16_f32 v11, v14, v15
	v_lshl_add_u64 v[18:19], s[16:17], 0, v[12:13]
	s_mov_b64 s[0:1], -1
	global_store_dwordx4 v[18:19], v[8:11], off
	s_cbranch_vccnz .LBB0_755
	s_mov_b64 s[0:1], 0
	s_waitcnt vmcnt(8)
	v_lshlrev_b32_e32 v12, 16, v236
	v_and_b32_e32 v13, 0xffff0000, v236
	v_lshlrev_b32_e32 v14, 16, v237
	v_and_b32_e32 v15, 0xffff0000, v237
	v_lshlrev_b32_e32 v8, 16, v238
	v_and_b32_e32 v9, 0xffff0000, v238
	v_lshlrev_b32_e32 v10, 16, v239
	v_and_b32_e32 v11, 0xffff0000, v239
.LBB0_755:
	s_andn2_b64 vcc, exec, s[0:1]
	s_cbranch_vccnz .LBB0_757
	s_waitcnt vmcnt(4)
	v_mov_b32_e32 v8, v236
	v_mov_b32_e32 v9, v237
	v_mov_b32_e32 v10, v238
	v_mov_b32_e32 v11, v239
	v_mov_b32_e32 v12, v218
	v_mov_b32_e32 v13, v219
	v_mov_b32_e32 v14, v220
	v_mov_b32_e32 v15, v221
.LBB0_757:
	s_waitcnt vmcnt(63)
	v_pk_fma_f32 v[6:7], v[6:7], v[70:71], v[14:15]
	v_pk_fma_f32 v[4:5], v[4:5], v[68:69], v[12:13]
	v_pk_fma_f32 v[10:11], v[2:3], v[62:63], v[10:11]
	v_pk_fma_f32 v[8:9], v[0:1], v[60:61], v[8:9]
	v_cvt_pk_bf16_f32 v0, v4, v5
	v_cvt_pk_bf16_f32 v1, v6, v7
	v_cvt_pk_bf16_f32 v2, v8, v9
	v_cvt_pk_bf16_f32 v3, v10, v11
	global_store_dwordx4 v[16:17], v[0:3], off offset:256
	v_pk_mul_f32 v[12:13], v[50:51], v[10:11]
	v_pk_mul_f32 v[14:15], v[48:49], v[8:9]
	v_pk_mul_f32 v[2:3], v[54:55], v[6:7]
	v_pk_mul_f32 v[0:1], v[52:53], v[4:5]
	v_mul_f32_e32 v24, v29, v29
	v_cvt_pk_bf16_f32 v0, v0, v1
	v_cvt_pk_bf16_f32 v1, v2, v3
	v_cvt_pk_bf16_f32 v2, v14, v15
	v_cvt_pk_bf16_f32 v3, v12, v13
	v_mul_f32_e32 v23, v23, v23
	global_store_dwordx4 v[18:19], v[0:3], off offset:256
	v_fmac_f32_e32 v24, v28, v28
	v_fmac_f32_e32 v23, v22, v22
	v_mul_f32_e32 v1, v5, v5
	v_mul_f32_e32 v2, v7, v7
	v_fmac_f32_e32 v1, v4, v4
	v_fmac_f32_e32 v2, v6, v6
	v_add_f32_e32 v22, v24, v23
	v_mul_f32_e32 v23, v31, v31
	v_add_f32_e32 v1, v1, v2
	v_mul_f32_e32 v2, v9, v9
	v_fmac_f32_e32 v23, v30, v30
	v_mul_f32_e32 v21, v21, v21
	v_mul_f32_e32 v0, v11, v11
	v_fmac_f32_e32 v2, v8, v8
	v_add_f32_e32 v22, v22, v23
	v_fmac_f32_e32 v21, v20, v20
	v_fmac_f32_e32 v0, v10, v10
	v_add_f32_e32 v1, v1, v2
	v_add_f32_e32 v20, v21, v22
	v_add_f32_e32 v0, v0, v1
	v_add_f32_e32 v0, v20, v0
	v_mov_b32_e32 v1, v0
	s_nop 1
	v_permlane16_swap_b32_e32 v0, v1
	v_add_f32_e32 v0, v0, v1
	v_mov_b32_e32 v1, v0
	s_nop 1
	v_permlane32_swap_b32_e32 v0, v1
	s_and_saveexec_b64 s[0:1], s[8:9]
	s_cbranch_execz .LBB0_674
	v_add_f32_e32 v0, v0, v1
	global_atomic_add_f32 v[152:153], v0, off offset:704
	s_branch .LBB0_674

.LBB0_796:
	v_readlane_b32 s2, v254, 26
	s_addk_i32 s24, 0xc0
	v_mov_b32_e32 v91, v169
	v_mov_b32_e32 v0, s2
	ds_read_b64 v[0:1], v0
	s_mul_hi_i32 s2, s24, 0x2aaaaaab
	s_lshr_b32 s3, s2, 31
	s_ashr_i32 s2, s2, 5
	s_add_i32 s14, s2, s3
	s_mul_i32 s2, s14, 0xc0
	s_sub_i32 s16, s24, s2
	v_readlane_b32 s2, v254, 49
	s_waitcnt lgkmcnt(0)
	v_readfirstlane_b32 s12, v0
	v_readfirstlane_b32 s13, v1
	v_mov_b32_e32 v0, s2
	ds_read_b64 v[0:1], v0
	s_ashr_i32 s15, s14, 31
	s_lshl_b32 s16, s16, 5
	s_ashr_i32 s17, s16, 31
	s_waitcnt lgkmcnt(0)
	v_readfirstlane_b32 s2, v1
	v_readfirstlane_b32 s3, v0
	s_nop 0
	v_mov_b32_e32 v1, s2
	v_mov_b32_e32 v0, s3
	s_lshl_b64 s[2:3], s[14:15], 10
	v_lshl_add_u64 v[2:3], s[2:3], 0, v[82:83]
	s_movk_i32 s15, 0x6000
	v_mad_u64_u32 v[0:1], s[2:3], v2, s15, v[0:1]
	v_mad_i32_i24 v1, v3, s15, v1
	v_lshl_add_u64 v[0:1], s[16:17], 2, v[0:1]
	v_lshl_add_u64 v[28:29], v[0:1], 0, v[90:91]
	v_mov_b32_e32 v244, v28
	v_mov_b32_e32 v245, v29
	s_mov_b64 s[80:81], 0x6000
	global_load_dwordx4 v[132:135], v[244:245], off nt
	v_lshl_add_u64 v[244:245], v[244:245], 0, s[80:81]
	global_load_dwordx4 v[136:139], v[244:245], off nt
	v_lshl_add_u64 v[244:245], v[244:245], 0, s[80:81]
	global_load_dwordx4 v[140:143], v[244:245], off nt
	v_lshl_add_u64 v[244:245], v[244:245], 0, s[80:81]
	global_load_dwordx4 v[144:147], v[244:245], off nt
	v_lshl_add_u64 v[244:245], v[244:245], 0, s[80:81]
	global_load_dwordx4 v[148:151], v[244:245], off nt
	v_lshl_add_u64 v[244:245], v[244:245], 0, s[80:81]
	global_load_dwordx4 v[156:159], v[244:245], off nt
	v_lshl_add_u64 v[244:245], v[244:245], 0, s[80:81]
	global_load_dwordx4 v[160:163], v[244:245], off nt
	v_lshl_add_u64 v[244:245], v[244:245], 0, s[80:81]
	global_load_dwordx4 v[164:167], v[244:245], off nt
	v_lshl_add_u64 v[244:245], v[244:245], 0, s[80:81]
	global_load_dwordx4 v[180:183], v[244:245], off nt
	v_lshl_add_u64 v[244:245], v[244:245], 0, s[80:81]
	global_load_dwordx4 v[184:187], v[244:245], off nt
	v_lshl_add_u64 v[244:245], v[244:245], 0, s[80:81]
	global_load_dwordx4 v[188:191], v[244:245], off nt
	v_lshl_add_u64 v[244:245], v[244:245], 0, s[80:81]
	global_load_dwordx4 v[192:195], v[244:245], off nt
	v_lshl_add_u64 v[244:245], v[244:245], 0, s[80:81]
	global_load_dwordx4 v[196:199], v[244:245], off nt
	v_lshl_add_u64 v[244:245], v[244:245], 0, s[80:81]
	global_load_dwordx4 v[200:203], v[244:245], off nt
	v_lshl_add_u64 v[244:245], v[244:245], 0, s[80:81]
	global_load_dwordx4 v[204:207], v[244:245], off nt
	v_lshl_add_u64 v[244:245], v[244:245], 0, s[80:81]
	global_load_dwordx4 v[240:243], v[244:245], off nt
	s_waitcnt vmcnt(15)
	v_mov_b32_e32 v12, v132
	v_mov_b32_e32 v13, v133
	v_mov_b32_e32 v14, v134
	v_mov_b32_e32 v15, v135
	ds_read_b128 v[16:19], v108
	ds_read_b128 v[8:11], v108 offset:16
	ds_read_b128 v[4:7], v108 offset:32
	ds_read_b128 v[0:3], v108 offset:48
	ds_read_b128 v[20:23], v108 offset:4096
	ds_read_b128 v[24:27], v108 offset:8192
	ds_read_b128 v[30:33], v108 offset:12288
	ds_read_b128 v[34:37], v108 offset:16384
	s_mov_b32 s2, 0xc000
	s_waitcnt lgkmcnt(7)
	v_pk_fma_f32 v[40:41], v[12:13], v[16:17], 0 op_sel_hi:[1,0,0]
	s_waitcnt lgkmcnt(3)
	v_pk_fma_f32 v[44:45], v[12:13], v[20:21], 0 op_sel_hi:[1,0,0]
	s_waitcnt lgkmcnt(2)
	v_pk_fma_f32 v[48:49], v[12:13], v[24:25], 0 op_sel_hi:[1,0,0]
	s_waitcnt lgkmcnt(1)
	v_pk_fma_f32 v[52:53], v[12:13], v[30:31], 0 op_sel_hi:[1,0,0]
	s_waitcnt lgkmcnt(0)
	v_pk_fma_f32 v[56:57], v[12:13], v[34:35], 0 op_sel_hi:[1,0,0]
	v_add_co_u32_e32 v12, vcc, s15, v28
	v_pk_fma_f32 v[38:39], v[14:15], v[16:17], 0 op_sel_hi:[1,0,0]
	s_nop 0
	v_addc_co_u32_e32 v13, vcc, 0, v29, vcc
	v_pk_fma_f32 v[42:43], v[14:15], v[20:21], 0 op_sel_hi:[1,0,0]
	v_pk_fma_f32 v[46:47], v[14:15], v[24:25], 0 op_sel_hi:[1,0,0]
	v_pk_fma_f32 v[50:51], v[14:15], v[30:31], 0 op_sel_hi:[1,0,0]
	v_pk_fma_f32 v[54:55], v[14:15], v[34:35], 0 op_sel_hi:[1,0,0]
	s_waitcnt vmcnt(14)
	v_mov_b32_e32 v12, v136
	v_mov_b32_e32 v13, v137
	v_mov_b32_e32 v14, v138
	v_mov_b32_e32 v15, v139
	s_nop 0
	v_pk_fma_f32 v[38:39], v[14:15], v[16:17], v[38:39] op_sel:[0,1,0]
	v_pk_fma_f32 v[16:17], v[12:13], v[16:17], v[40:41] op_sel:[0,1,0]
	v_pk_fma_f32 v[40:41], v[14:15], v[20:21], v[42:43] op_sel:[0,1,0]
	v_pk_fma_f32 v[20:21], v[12:13], v[20:21], v[44:45] op_sel:[0,1,0]
	v_pk_fma_f32 v[42:43], v[14:15], v[24:25], v[46:47] op_sel:[0,1,0]
	v_pk_fma_f32 v[24:25], v[12:13], v[24:25], v[48:49] op_sel:[0,1,0]
	v_pk_fma_f32 v[44:45], v[14:15], v[30:31], v[50:51] op_sel:[0,1,0]
	v_pk_fma_f32 v[30:31], v[12:13], v[30:31], v[52:53] op_sel:[0,1,0]
	v_pk_fma_f32 v[46:47], v[14:15], v[34:35], v[54:55] op_sel:[0,1,0]
	v_pk_fma_f32 v[34:35], v[12:13], v[34:35], v[56:57] op_sel:[0,1,0]
	v_add_co_u32_e32 v12, vcc, s2, v28
	s_mov_b32 s2, 0x12000
	s_nop 0
	v_addc_co_u32_e32 v13, vcc, 0, v29, vcc
	s_waitcnt vmcnt(13)
	v_mov_b32_e32 v12, v140
	v_mov_b32_e32 v13, v141
	v_mov_b32_e32 v14, v142
	v_mov_b32_e32 v15, v143
	s_nop 0
	v_pk_fma_f32 v[16:17], v[12:13], v[18:19], v[16:17] op_sel_hi:[1,0,1]
	v_pk_fma_f32 v[20:21], v[12:13], v[22:23], v[20:21] op_sel_hi:[1,0,1]
	v_pk_fma_f32 v[24:25], v[12:13], v[26:27], v[24:25] op_sel_hi:[1,0,1]
	v_pk_fma_f32 v[30:31], v[12:13], v[32:33], v[30:31] op_sel_hi:[1,0,1]
	v_pk_fma_f32 v[34:35], v[12:13], v[36:37], v[34:35] op_sel_hi:[1,0,1]
	v_add_co_u32_e32 v12, vcc, s2, v28
	v_pk_fma_f32 v[38:39], v[14:15], v[18:19], v[38:39] op_sel_hi:[1,0,1]
	s_nop 0
	v_addc_co_u32_e32 v13, vcc, 0, v29, vcc
	v_pk_fma_f32 v[40:41], v[14:15], v[22:23], v[40:41] op_sel_hi:[1,0,1]
	v_pk_fma_f32 v[42:43], v[14:15], v[26:27], v[42:43] op_sel_hi:[1,0,1]
	v_pk_fma_f32 v[44:45], v[14:15], v[32:33], v[44:45] op_sel_hi:[1,0,1]
	v_pk_fma_f32 v[46:47], v[14:15], v[36:37], v[46:47] op_sel_hi:[1,0,1]
	s_waitcnt vmcnt(12)
	v_mov_b32_e32 v12, v144
	v_mov_b32_e32 v13, v145
	v_mov_b32_e32 v14, v146
	v_mov_b32_e32 v15, v147
	v_mov_b32_e32 v18, v19
	s_mov_b32 s2, 0x18000
	s_nop 0
	v_pk_fma_f32 v[38:39], v[14:15], v[18:19], v[38:39] op_sel_hi:[1,0,1]
	v_pk_fma_f32 v[16:17], v[12:13], v[18:19], v[16:17] op_sel_hi:[1,0,1]
	v_mov_b32_e32 v18, v23
	v_pk_fma_f32 v[22:23], v[14:15], v[18:19], v[40:41] op_sel_hi:[1,0,1]
	v_pk_fma_f32 v[18:19], v[12:13], v[18:19], v[20:21] op_sel_hi:[1,0,1]
	v_mov_b32_e32 v20, v27
	v_pk_fma_f32 v[26:27], v[14:15], v[20:21], v[42:43] op_sel_hi:[1,0,1]
	v_pk_fma_f32 v[20:21], v[12:13], v[20:21], v[24:25] op_sel_hi:[1,0,1]
	v_mov_b32_e32 v24, v33
	v_pk_fma_f32 v[40:41], v[14:15], v[24:25], v[44:45] op_sel_hi:[1,0,1]
	v_pk_fma_f32 v[24:25], v[12:13], v[24:25], v[30:31] op_sel_hi:[1,0,1]
	v_mov_b32_e32 v30, v37
	v_pk_fma_f32 v[34:35], v[12:13], v[30:31], v[34:35] op_sel_hi:[1,0,1]
	v_add_co_u32_e32 v12, vcc, s2, v28
	v_pk_fma_f32 v[36:37], v[14:15], v[30:31], v[46:47] op_sel_hi:[1,0,1]
	s_nop 0
	v_addc_co_u32_e32 v13, vcc, 0, v29, vcc
	s_waitcnt vmcnt(11)
	v_mov_b32_e32 v30, v148
	v_mov_b32_e32 v31, v149
	v_mov_b32_e32 v32, v150
	v_mov_b32_e32 v33, v151
	ds_read_b128 v[12:15], v108 offset:4112
	s_mov_b32 s2, 0x1e000
	s_nop 0
	v_pk_fma_f32 v[42:43], v[30:31], v[8:9], v[16:17] op_sel_hi:[1,0,1]
	s_waitcnt lgkmcnt(0)
	v_pk_fma_f32 v[46:47], v[30:31], v[12:13], v[18:19] op_sel_hi:[1,0,1]
	ds_read_b128 v[16:19], v108 offset:8208
	v_pk_fma_f32 v[44:45], v[32:33], v[12:13], v[22:23] op_sel_hi:[1,0,1]
	v_pk_fma_f32 v[38:39], v[32:33], v[8:9], v[38:39] op_sel_hi:[1,0,1]
	s_waitcnt lgkmcnt(0)
	v_pk_fma_f32 v[50:51], v[30:31], v[16:17], v[20:21] op_sel_hi:[1,0,1]
	ds_read_b128 v[20:23], v108 offset:12304
	v_pk_fma_f32 v[48:49], v[32:33], v[16:17], v[26:27] op_sel_hi:[1,0,1]
	s_waitcnt lgkmcnt(0)
	v_pk_fma_f32 v[52:53], v[30:31], v[20:21], v[24:25] op_sel_hi:[1,0,1]
	ds_read_b128 v[24:27], v108 offset:16400
	v_pk_fma_f32 v[40:41], v[32:33], v[20:21], v[40:41] op_sel_hi:[1,0,1]
	s_waitcnt lgkmcnt(0)
	v_pk_fma_f32 v[34:35], v[30:31], v[24:25], v[34:35] op_sel_hi:[1,0,1]
	v_add_co_u32_e32 v30, vcc, s2, v28
	v_pk_fma_f32 v[36:37], v[32:33], v[24:25], v[36:37] op_sel_hi:[1,0,1]
	s_nop 0
	v_addc_co_u32_e32 v31, vcc, 0, v29, vcc
	s_waitcnt vmcnt(10)
	v_mov_b32_e32 v30, v156
	v_mov_b32_e32 v31, v157
	v_mov_b32_e32 v32, v158
	v_mov_b32_e32 v33, v159
	s_mov_b32 s2, 0x24000
	s_nop 0
	v_pk_fma_f32 v[38:39], v[32:33], v[8:9], v[38:39] op_sel:[0,1,0]
	v_pk_fma_f32 v[8:9], v[30:31], v[8:9], v[42:43] op_sel:[0,1,0]
	v_pk_fma_f32 v[42:43], v[32:33], v[12:13], v[44:45] op_sel:[0,1,0]
	v_pk_fma_f32 v[12:13], v[30:31], v[12:13], v[46:47] op_sel:[0,1,0]
	v_pk_fma_f32 v[44:45], v[32:33], v[16:17], v[48:49] op_sel:[0,1,0]
	v_pk_fma_f32 v[16:17], v[30:31], v[16:17], v[50:51] op_sel:[0,1,0]
	v_pk_fma_f32 v[40:41], v[32:33], v[20:21], v[40:41] op_sel:[0,1,0]
	v_pk_fma_f32 v[20:21], v[30:31], v[20:21], v[52:53] op_sel:[0,1,0]
	v_pk_fma_f32 v[36:37], v[32:33], v[24:25], v[36:37] op_sel:[0,1,0]
	v_pk_fma_f32 v[24:25], v[30:31], v[24:25], v[34:35] op_sel:[0,1,0]
	v_add_co_u32_e32 v30, vcc, s2, v28
	s_mov_b32 s2, 0x2a000
	s_nop 0
	v_addc_co_u32_e32 v31, vcc, 0, v29, vcc
	s_waitcnt vmcnt(9)
	v_mov_b32_e32 v30, v160
	v_mov_b32_e32 v31, v161
	v_mov_b32_e32 v32, v162
	v_mov_b32_e32 v33, v163
	s_nop 0
	v_pk_fma_f32 v[8:9], v[30:31], v[10:11], v[8:9] op_sel_hi:[1,0,1]
	v_pk_fma_f32 v[12:13], v[30:31], v[14:15], v[12:13] op_sel_hi:[1,0,1]
	v_pk_fma_f32 v[16:17], v[30:31], v[18:19], v[16:17] op_sel_hi:[1,0,1]
	v_pk_fma_f32 v[20:21], v[30:31], v[22:23], v[20:21] op_sel_hi:[1,0,1]
	v_pk_fma_f32 v[24:25], v[30:31], v[26:27], v[24:25] op_sel_hi:[1,0,1]
	v_add_co_u32_e32 v30, vcc, s2, v28
	v_pk_fma_f32 v[34:35], v[32:33], v[10:11], v[38:39] op_sel_hi:[1,0,1]
	s_nop 0
	v_addc_co_u32_e32 v31, vcc, 0, v29, vcc
	v_pk_fma_f32 v[38:39], v[32:33], v[14:15], v[42:43] op_sel_hi:[1,0,1]
	v_pk_fma_f32 v[42:43], v[32:33], v[18:19], v[44:45] op_sel_hi:[1,0,1]
	v_pk_fma_f32 v[40:41], v[32:33], v[22:23], v[40:41] op_sel_hi:[1,0,1]
	v_pk_fma_f32 v[36:37], v[32:33], v[26:27], v[36:37] op_sel_hi:[1,0,1]
	s_waitcnt vmcnt(8)
	v_mov_b32_e32 v30, v164
	v_mov_b32_e32 v31, v165
	v_mov_b32_e32 v32, v166
	v_mov_b32_e32 v33, v167
	v_mov_b32_e32 v10, v11
	s_mov_b32 s2, 0x30000
	s_nop 0
	v_pk_fma_f32 v[34:35], v[32:33], v[10:11], v[34:35] op_sel_hi:[1,0,1]
	v_pk_fma_f32 v[8:9], v[30:31], v[10:11], v[8:9] op_sel_hi:[1,0,1]
	v_mov_b32_e32 v10, v15
	v_pk_fma_f32 v[14:15], v[32:33], v[10:11], v[38:39] op_sel_hi:[1,0,1]
	v_pk_fma_f32 v[12:13], v[30:31], v[10:11], v[12:13] op_sel_hi:[1,0,1]
	v_mov_b32_e32 v10, v19
	v_pk_fma_f32 v[18:19], v[32:33], v[10:11], v[42:43] op_sel_hi:[1,0,1]
	v_pk_fma_f32 v[16:17], v[30:31], v[10:11], v[16:17] op_sel_hi:[1,0,1]
	v_mov_b32_e32 v10, v23
	v_pk_fma_f32 v[22:23], v[32:33], v[10:11], v[40:41] op_sel_hi:[1,0,1]
	v_pk_fma_f32 v[20:21], v[30:31], v[10:11], v[20:21] op_sel_hi:[1,0,1]
	v_mov_b32_e32 v10, v27
	v_pk_fma_f32 v[32:33], v[32:33], v[10:11], v[36:37] op_sel_hi:[1,0,1]
	v_pk_fma_f32 v[30:31], v[30:31], v[10:11], v[24:25] op_sel_hi:[1,0,1]
	v_add_co_u32_e32 v10, vcc, s2, v28
	s_mov_b32 s2, 0x36000
	s_nop 0
	v_addc_co_u32_e32 v11, vcc, 0, v29, vcc
	s_waitcnt vmcnt(7)
	v_mov_b32_e32 v24, v180
	v_mov_b32_e32 v25, v181
	v_mov_b32_e32 v26, v182
	v_mov_b32_e32 v27, v183
	s_nop 0
	v_pk_fma_f32 v[36:37], v[24:25], v[4:5], v[8:9] op_sel_hi:[1,0,1]
	ds_read_b128 v[8:11], v108 offset:4128
	v_pk_fma_f32 v[34:35], v[26:27], v[4:5], v[34:35] op_sel_hi:[1,0,1]
	s_waitcnt lgkmcnt(0)
	v_pk_fma_f32 v[38:39], v[26:27], v[8:9], v[14:15] op_sel_hi:[1,0,1]
	v_pk_fma_f32 v[40:41], v[24:25], v[8:9], v[12:13] op_sel_hi:[1,0,1]
	ds_read_b128 v[12:15], v108 offset:8224
	s_waitcnt lgkmcnt(0)
	v_pk_fma_f32 v[42:43], v[26:27], v[12:13], v[18:19] op_sel_hi:[1,0,1]
	v_pk_fma_f32 v[44:45], v[24:25], v[12:13], v[16:17] op_sel_hi:[1,0,1]
	ds_read_b128 v[16:19], v108 offset:12320
	s_waitcnt lgkmcnt(0)
	v_pk_fma_f32 v[46:47], v[26:27], v[16:17], v[22:23] op_sel_hi:[1,0,1]
	v_pk_fma_f32 v[48:49], v[24:25], v[16:17], v[20:21] op_sel_hi:[1,0,1]
	ds_read_b128 v[20:23], v108 offset:16416
	s_waitcnt lgkmcnt(0)
	v_pk_fma_f32 v[30:31], v[24:25], v[20:21], v[30:31] op_sel_hi:[1,0,1]
	v_add_co_u32_e32 v24, vcc, s2, v28
	v_pk_fma_f32 v[32:33], v[26:27], v[20:21], v[32:33] op_sel_hi:[1,0,1]
	s_nop 0
	v_addc_co_u32_e32 v25, vcc, 0, v29, vcc
	s_waitcnt vmcnt(6)
	v_mov_b32_e32 v24, v184
	v_mov_b32_e32 v25, v185
	v_mov_b32_e32 v26, v186
	v_mov_b32_e32 v27, v187
	s_mov_b32 s2, 0x3c000
	s_nop 0
	v_pk_fma_f32 v[34:35], v[26:27], v[4:5], v[34:35] op_sel:[0,1,0]
	v_pk_fma_f32 v[4:5], v[24:25], v[4:5], v[36:37] op_sel:[0,1,0]
	v_pk_fma_f32 v[36:37], v[26:27], v[8:9], v[38:39] op_sel:[0,1,0]
	v_pk_fma_f32 v[8:9], v[24:25], v[8:9], v[40:41] op_sel:[0,1,0]
	v_pk_fma_f32 v[38:39], v[26:27], v[12:13], v[42:43] op_sel:[0,1,0]
	v_pk_fma_f32 v[12:13], v[24:25], v[12:13], v[44:45] op_sel:[0,1,0]
	v_pk_fma_f32 v[40:41], v[26:27], v[16:17], v[46:47] op_sel:[0,1,0]
	v_pk_fma_f32 v[16:17], v[24:25], v[16:17], v[48:49] op_sel:[0,1,0]
	v_pk_fma_f32 v[32:33], v[26:27], v[20:21], v[32:33] op_sel:[0,1,0]
	v_pk_fma_f32 v[20:21], v[24:25], v[20:21], v[30:31] op_sel:[0,1,0]
	v_add_co_u32_e32 v24, vcc, s2, v28
	s_mov_b32 s2, 0x42000
	s_nop 0
	v_addc_co_u32_e32 v25, vcc, 0, v29, vcc
	s_waitcnt vmcnt(5)
	v_mov_b32_e32 v24, v188
	v_mov_b32_e32 v25, v189
	v_mov_b32_e32 v26, v190
	v_mov_b32_e32 v27, v191
	s_nop 0
	v_pk_fma_f32 v[4:5], v[24:25], v[6:7], v[4:5] op_sel_hi:[1,0,1]
	v_pk_fma_f32 v[8:9], v[24:25], v[10:11], v[8:9] op_sel_hi:[1,0,1]
	v_pk_fma_f32 v[12:13], v[24:25], v[14:15], v[12:13] op_sel_hi:[1,0,1]
	v_pk_fma_f32 v[16:17], v[24:25], v[18:19], v[16:17] op_sel_hi:[1,0,1]
	v_pk_fma_f32 v[20:21], v[24:25], v[22:23], v[20:21] op_sel_hi:[1,0,1]
	v_add_co_u32_e32 v24, vcc, s2, v28
	v_pk_fma_f32 v[30:31], v[26:27], v[6:7], v[34:35] op_sel_hi:[1,0,1]
	s_nop 0
	v_addc_co_u32_e32 v25, vcc, 0, v29, vcc
	v_pk_fma_f32 v[34:35], v[26:27], v[10:11], v[36:37] op_sel_hi:[1,0,1]
	v_pk_fma_f32 v[36:37], v[26:27], v[14:15], v[38:39] op_sel_hi:[1,0,1]
	v_pk_fma_f32 v[38:39], v[26:27], v[18:19], v[40:41] op_sel_hi:[1,0,1]
	v_pk_fma_f32 v[32:33], v[26:27], v[22:23], v[32:33] op_sel_hi:[1,0,1]
	s_waitcnt vmcnt(4)
	v_mov_b32_e32 v24, v192
	v_mov_b32_e32 v25, v193
	v_mov_b32_e32 v26, v194
	v_mov_b32_e32 v27, v195
	v_mov_b32_e32 v6, v7
	s_mov_b32 s2, 0x48000
	s_nop 0
	v_pk_fma_f32 v[30:31], v[26:27], v[6:7], v[30:31] op_sel_hi:[1,0,1]
	v_pk_fma_f32 v[4:5], v[24:25], v[6:7], v[4:5] op_sel_hi:[1,0,1]
	v_mov_b32_e32 v6, v11
	v_pk_fma_f32 v[10:11], v[26:27], v[6:7], v[34:35] op_sel_hi:[1,0,1]
	v_pk_fma_f32 v[6:7], v[24:25], v[6:7], v[8:9] op_sel_hi:[1,0,1]
	v_mov_b32_e32 v8, v15
	v_pk_fma_f32 v[34:35], v[26:27], v[8:9], v[36:37] op_sel_hi:[1,0,1]
	v_pk_fma_f32 v[8:9], v[24:25], v[8:9], v[12:13] op_sel_hi:[1,0,1]
	v_mov_b32_e32 v12, v19
	v_pk_fma_f32 v[36:37], v[26:27], v[12:13], v[38:39] op_sel_hi:[1,0,1]
	v_pk_fma_f32 v[38:39], v[24:25], v[12:13], v[16:17] op_sel_hi:[1,0,1]
	v_mov_b32_e32 v12, v23
	v_pk_fma_f32 v[26:27], v[26:27], v[12:13], v[32:33] op_sel_hi:[1,0,1]
	v_pk_fma_f32 v[24:25], v[24:25], v[12:13], v[20:21] op_sel_hi:[1,0,1]
	v_add_co_u32_e32 v12, vcc, s2, v28
	ds_read_b128 v[16:19], v108 offset:4144
	s_nop 0
	v_addc_co_u32_e32 v13, vcc, 0, v29, vcc
	s_waitcnt vmcnt(3)
	v_mov_b32_e32 v20, v196
	v_mov_b32_e32 v21, v197
	v_mov_b32_e32 v22, v198
	v_mov_b32_e32 v23, v199
	ds_read_b128 v[12:15], v108 offset:8240
	s_mov_b32 s2, 0x4e000
	s_nop 0
	v_pk_fma_f32 v[32:33], v[20:21], v[0:1], v[4:5] op_sel_hi:[1,0,1]
	s_waitcnt lgkmcnt(1)
	v_pk_fma_f32 v[40:41], v[22:23], v[16:17], v[10:11] op_sel_hi:[1,0,1]
	v_pk_fma_f32 v[42:43], v[20:21], v[16:17], v[6:7] op_sel_hi:[1,0,1]
	s_waitcnt lgkmcnt(0)
	v_pk_fma_f32 v[44:45], v[20:21], v[12:13], v[8:9] op_sel_hi:[1,0,1]
	ds_read_b128 v[8:11], v108 offset:12336
	ds_read_b128 v[4:7], v108 offset:16432
	v_pk_fma_f32 v[30:31], v[22:23], v[0:1], v[30:31] op_sel_hi:[1,0,1]
	v_pk_fma_f32 v[34:35], v[22:23], v[12:13], v[34:35] op_sel_hi:[1,0,1]
	s_waitcnt lgkmcnt(1)
	v_pk_fma_f32 v[38:39], v[20:21], v[8:9], v[38:39] op_sel_hi:[1,0,1]
	s_waitcnt lgkmcnt(0)
	v_pk_fma_f32 v[24:25], v[20:21], v[4:5], v[24:25] op_sel_hi:[1,0,1]
	v_add_co_u32_e32 v20, vcc, s2, v28
	v_pk_fma_f32 v[36:37], v[22:23], v[8:9], v[36:37] op_sel_hi:[1,0,1]
	s_nop 0
	v_addc_co_u32_e32 v21, vcc, 0, v29, vcc
	v_pk_fma_f32 v[26:27], v[22:23], v[4:5], v[26:27] op_sel_hi:[1,0,1]
	s_waitcnt vmcnt(2)
	v_mov_b32_e32 v20, v200
	v_mov_b32_e32 v21, v201
	v_mov_b32_e32 v22, v202
	v_mov_b32_e32 v23, v203
	s_mov_b32 s2, 0x54000
	s_nop 0
	v_pk_fma_f32 v[36:37], v[22:23], v[8:9], v[36:37] op_sel:[0,1,0]
	v_pk_fma_f32 v[38:39], v[20:21], v[8:9], v[38:39] op_sel:[0,1,0]
	v_add_co_u32_e32 v8, vcc, s2, v28
	v_pk_fma_f32 v[30:31], v[22:23], v[0:1], v[30:31] op_sel:[0,1,0]
	s_nop 0
	v_addc_co_u32_e32 v9, vcc, 0, v29, vcc
	v_pk_fma_f32 v[0:1], v[20:21], v[0:1], v[32:33] op_sel:[0,1,0]
	v_pk_fma_f32 v[40:41], v[22:23], v[16:17], v[40:41] op_sel:[0,1,0]
	v_pk_fma_f32 v[16:17], v[20:21], v[16:17], v[42:43] op_sel:[0,1,0]
	v_pk_fma_f32 v[42:43], v[22:23], v[12:13], v[34:35] op_sel:[0,1,0]
	v_pk_fma_f32 v[12:13], v[20:21], v[12:13], v[44:45] op_sel:[0,1,0]
	v_pk_fma_f32 v[44:45], v[22:23], v[4:5], v[26:27] op_sel:[0,1,0]
	v_pk_fma_f32 v[4:5], v[20:21], v[4:5], v[24:25] op_sel:[0,1,0]
	s_waitcnt vmcnt(1)
	v_mov_b32_e32 v20, v204
	v_mov_b32_e32 v21, v205
	v_mov_b32_e32 v22, v206
	v_mov_b32_e32 v23, v207
	s_mov_b32 s2, 0x5a000
	s_nop 0
	v_pk_fma_f32 v[32:33], v[22:23], v[2:3], v[30:31] op_sel_hi:[1,0,1]
	v_pk_fma_f32 v[34:35], v[20:21], v[2:3], v[0:1] op_sel_hi:[1,0,1]
	v_pk_fma_f32 v[30:31], v[20:21], v[18:19], v[16:17] op_sel_hi:[1,0,1]
	v_pk_fma_f32 v[24:25], v[20:21], v[14:15], v[12:13] op_sel_hi:[1,0,1]
	v_pk_fma_f32 v[12:13], v[20:21], v[10:11], v[38:39] op_sel_hi:[1,0,1]
	v_pk_fma_f32 v[4:5], v[20:21], v[6:7], v[4:5] op_sel_hi:[1,0,1]
	v_add_co_u32_e32 v20, vcc, s2, v28
	v_pk_fma_f32 v[26:27], v[22:23], v[18:19], v[40:41] op_sel_hi:[1,0,1]
	s_nop 0
	v_addc_co_u32_e32 v21, vcc, 0, v29, vcc
	v_pk_fma_f32 v[16:17], v[22:23], v[14:15], v[42:43] op_sel_hi:[1,0,1]
	v_pk_fma_f32 v[8:9], v[22:23], v[10:11], v[36:37] op_sel_hi:[1,0,1]
	v_pk_fma_f32 v[0:1], v[22:23], v[6:7], v[44:45] op_sel_hi:[1,0,1]
	s_waitcnt vmcnt(0)
	v_mov_b32_e32 v20, v240
	v_mov_b32_e32 v21, v241
	v_mov_b32_e32 v22, v242
	v_mov_b32_e32 v23, v243
	v_mov_b32_e32 v2, v3
	v_mov_b32_e32 v6, v7
	s_nop 0
	v_pk_fma_f32 v[36:37], v[22:23], v[2:3], v[32:33] op_sel_hi:[1,0,1]
	v_pk_fma_f32 v[34:35], v[20:21], v[2:3], v[34:35] op_sel_hi:[1,0,1]
	v_mov_b32_e32 v2, v19
	v_pk_fma_f32 v[28:29], v[22:23], v[2:3], v[26:27] op_sel_hi:[1,0,1]
	v_pk_fma_f32 v[26:27], v[20:21], v[2:3], v[30:31] op_sel_hi:[1,0,1]
	v_mov_b32_e32 v2, v15
	v_pk_fma_f32 v[16:17], v[22:23], v[2:3], v[16:17] op_sel_hi:[1,0,1]
	v_pk_fma_f32 v[14:15], v[20:21], v[2:3], v[24:25] op_sel_hi:[1,0,1]
	v_mov_b32_e32 v2, v11
	v_pk_fma_f32 v[10:11], v[22:23], v[2:3], v[8:9] op_sel_hi:[1,0,1]
	v_pk_fma_f32 v[8:9], v[20:21], v[2:3], v[12:13] op_sel_hi:[1,0,1]
	v_pk_fma_f32 v[2:3], v[22:23], v[6:7], v[0:1] op_sel_hi:[1,0,1]
	v_pk_fma_f32 v[0:1], v[20:21], v[6:7], v[4:5] op_sel_hi:[1,0,1]
	ds_write_b128 v111, v[34:37]
	ds_write_b128 v111, v[26:29] offset:16
	ds_write_b128 v111, v[14:17] offset:32
	ds_write_b128 v111, v[8:11] offset:48
	ds_write_b128 v111, v[0:3] offset:64
	s_waitcnt lgkmcnt(0)
	s_barrier
	s_and_saveexec_b64 s[18:19], s[10:11]
	s_cbranch_execz .LBB0_764
	ds_read2_b32 v[0:1], v109 offset1:160
	v_readlane_b32 s2, v254, 50
	v_lshlrev_b32_e32 v168, 2, v80
	s_waitcnt lgkmcnt(0)
	v_add_f32_e32 v0, 0, v0
	v_add_f32_e32 v2, v0, v1
	v_add_u32_e32 v0, 0x400, v109
	ds_read2_b32 v[0:1], v0 offset0:64 offset1:224
	s_waitcnt lgkmcnt(0)
	v_add_f32_e32 v0, v2, v0
	v_add_f32_e32 v2, v0, v1
	v_add_u32_e32 v0, 0xa00, v109
	ds_read2_b32 v[0:1], v0 offset1:160
	s_waitcnt lgkmcnt(0)
	v_add_f32_e32 v0, v2, v0
	v_add_f32_e32 v2, v0, v1
	v_add_u32_e32 v0, 0xe00, v109
	ds_read2_b32 v[0:1], v0 offset0:64 offset1:224
	s_waitcnt lgkmcnt(0)
	v_add_f32_e32 v0, v2, v0
	v_add_f32_e32 v2, v0, v1
	v_add_u32_e32 v0, 0x1400, v109
	ds_read2_b32 v[0:1], v0 offset1:160
	s_waitcnt lgkmcnt(0)
	v_add_f32_e32 v0, v2, v0
	v_add_f32_e32 v2, v0, v1
	v_add_u32_e32 v0, 0x1800, v109
	ds_read2_b32 v[0:1], v0 offset0:64 offset1:224
	s_waitcnt lgkmcnt(0)
	v_add_f32_e32 v0, v2, v0
	v_add_f32_e32 v2, v0, v1
	v_add_u32_e32 v0, 0x1e00, v109
	ds_read2_b32 v[0:1], v0 offset1:160
	s_waitcnt lgkmcnt(0)
	v_add_f32_e32 v0, v2, v0
	v_add_f32_e32 v2, v0, v1
	v_add_u32_e32 v0, 0x2200, v109
	ds_read2_b32 v[0:1], v0 offset0:64 offset1:224
	s_waitcnt lgkmcnt(0)
	v_add_f32_e32 v0, v2, v0
	v_add_f32_e32 v2, v0, v1
	v_add_u32_e32 v0, 0x2800, v109
	ds_read2_b32 v[0:1], v0 offset1:160
	s_waitcnt lgkmcnt(0)
	v_add_f32_e32 v0, v2, v0
	v_add_f32_e32 v2, v0, v1
	v_add_u32_e32 v0, 0x2c00, v109
	ds_read2_b32 v[0:1], v0 offset0:64 offset1:224
	s_waitcnt lgkmcnt(0)
	v_add_f32_e32 v0, v2, v0
	v_add_f32_e32 v2, v0, v1
	v_add_u32_e32 v0, 0x3200, v109
	ds_read2_b32 v[0:1], v0 offset1:160
	s_waitcnt lgkmcnt(0)
	v_add_f32_e32 v0, v2, v0
	v_add_f32_e32 v2, v0, v1
	v_add_u32_e32 v0, 0x3600, v109
	ds_read2_b32 v[0:1], v0 offset0:64 offset1:224
	s_waitcnt lgkmcnt(0)
	v_add_f32_e32 v0, v2, v0
	v_add_f32_e32 v2, v0, v1
	v_add_u32_e32 v0, 0x3c00, v109
	ds_read2_b32 v[0:1], v0 offset1:160
	s_waitcnt lgkmcnt(0)
	v_add_f32_e32 v0, v2, v0
	v_add_f32_e32 v2, v0, v1
	v_add_u32_e32 v0, 0x4000, v109
	ds_read2_b32 v[0:1], v0 offset0:64 offset1:224
	s_waitcnt lgkmcnt(0)
	v_add_f32_e32 v0, v2, v0
	v_add_f32_e32 v2, v0, v1
	v_add_u32_e32 v0, 0x4600, v109
	ds_read2_b32 v[0:1], v0 offset1:160
	s_waitcnt lgkmcnt(0)
	v_add_f32_e32 v0, v2, v0
	v_add_f32_e32 v2, v0, v1
	v_add_u32_e32 v0, 0x4a00, v109
	ds_read2_b32 v[0:1], v0 offset0:64 offset1:224
	s_waitcnt lgkmcnt(0)
	v_add_f32_e32 v0, v2, v0
	v_add_f32_e32 v2, v0, v1
	v_add_u32_e32 v0, 0x5000, v109
	ds_read2_b32 v[0:1], v0 offset1:160
	s_waitcnt lgkmcnt(0)
	v_add_f32_e32 v0, v2, v0
	v_add_f32_e32 v2, v0, v1
	v_add_u32_e32 v0, 0x5400, v109
	ds_read2_b32 v[0:1], v0 offset0:64 offset1:224
	s_waitcnt lgkmcnt(0)
	v_add_f32_e32 v0, v2, v0
	v_add_f32_e32 v2, v0, v1
	v_add_u32_e32 v0, 0x5a00, v109
	ds_read2_b32 v[0:1], v0 offset1:160
	s_waitcnt lgkmcnt(0)
	v_add_f32_e32 v0, v2, v0
	v_add_f32_e32 v2, v0, v1
	v_add_u32_e32 v0, 0x5e00, v109
	ds_read2_b32 v[0:1], v0 offset0:64 offset1:224
	s_waitcnt lgkmcnt(0)
	v_add_f32_e32 v0, v2, v0
	v_add_f32_e32 v2, v0, v1
	v_add_u32_e32 v0, 0x6400, v109
	ds_read2_b32 v[0:1], v0 offset1:160
	s_waitcnt lgkmcnt(0)
	v_add_f32_e32 v0, v2, v0
	v_add_f32_e32 v2, v0, v1
	v_add_u32_e32 v0, 0x6800, v109
	ds_read2_b32 v[0:1], v0 offset0:64 offset1:224
	s_waitcnt lgkmcnt(0)
	v_add_f32_e32 v0, v2, v0
	v_add_f32_e32 v2, v0, v1
	v_add_u32_e32 v0, 0x6e00, v109
	ds_read2_b32 v[0:1], v0 offset1:160
	s_waitcnt lgkmcnt(0)
	v_add_f32_e32 v0, v2, v0
	v_add_f32_e32 v2, v0, v1
	v_add_u32_e32 v0, 0x7200, v109
	ds_read2_b32 v[0:1], v0 offset0:64 offset1:224
	s_waitcnt lgkmcnt(0)
	v_add_f32_e32 v0, v2, v0
	v_add_f32_e32 v2, v0, v1
	v_add_u32_e32 v0, 0x7800, v109
	ds_read2_b32 v[0:1], v0 offset1:160
	s_waitcnt lgkmcnt(0)
	v_add_f32_e32 v0, v2, v0
	v_add_f32_e32 v2, v0, v1
	v_add_u32_e32 v0, 0x7c00, v109
	ds_read2_b32 v[0:1], v0 offset0:64 offset1:224
	s_waitcnt lgkmcnt(0)
	v_add_f32_e32 v0, v2, v0
	v_add_f32_e32 v2, v0, v1
	v_add_u32_e32 v0, 0x8200, v109
	ds_read2_b32 v[0:1], v0 offset1:160
	s_waitcnt lgkmcnt(0)
	v_add_f32_e32 v0, v2, v0
	v_add_f32_e32 v2, v0, v1
	v_add_u32_e32 v0, 0x8600, v109
	ds_read2_b32 v[0:1], v0 offset0:64 offset1:224
	s_waitcnt lgkmcnt(0)
	v_add_f32_e32 v0, v2, v0
	v_add_f32_e32 v2, v0, v1
	v_add_u32_e32 v0, 0x8c00, v109
	ds_read2_b32 v[0:1], v0 offset1:160
	s_waitcnt lgkmcnt(0)
	v_add_f32_e32 v0, v2, v0
	v_add_f32_e32 v2, v0, v1
	v_add_u32_e32 v0, 0x9000, v109
	ds_read2_b32 v[0:1], v0 offset0:64 offset1:224
	s_waitcnt lgkmcnt(0)
	v_add_f32_e32 v0, v2, v0
	v_add_f32_e32 v2, v0, v1
	v_add_u32_e32 v0, 0x9600, v109
	ds_read2_b32 v[0:1], v0 offset1:160
	s_waitcnt lgkmcnt(0)
	v_add_f32_e32 v0, v2, v0
	v_add_f32_e32 v2, v0, v1
	v_add_u32_e32 v0, 0x9a00, v109
	ds_read2_b32 v[0:1], v0 offset0:64 offset1:224
	s_waitcnt lgkmcnt(0)
	v_add_f32_e32 v0, v2, v0
	v_add_f32_e32 v0, v0, v1
	v_mov_b32_e32 v1, s2
	ds_read_b64 v[2:3], v1
	s_waitcnt lgkmcnt(0)
	v_readfirstlane_b32 s2, v3
	s_nop 1
	v_mov_b32_e32 v3, s2
	s_mul_i32 s2, s14, 0x1800
	s_add_i32 s2, s2, s16
	v_readfirstlane_b32 s3, v2
	v_or_b32_e32 v4, s2, v80
	v_ashrrev_i32_e32 v5, 31, v4
	v_mov_b32_e32 v2, s3
	v_lshl_add_u64 v[2:3], v[4:5], 2, v[2:3]
	global_load_dword v1, v[2:3], off
	v_mov_b64_e32 v[2:3], s[12:13]
	s_waitcnt vmcnt(0)
	v_add_f32_e32 v4, v0, v1
	v_mad_u64_u32 v[0:1], s[2:3], s14, 5, v[84:85]
	s_movk_i32 s2, 0x6000
	s_nop 0
	v_mad_i64_i32 v[0:1], s[2:3], v0, s2, v[2:3]
	v_lshl_add_u64 v[0:1], s[16:17], 2, v[0:1]
	v_lshl_add_u64 v[0:1], v[0:1], 0, v[168:169]
	v_add_co_u32_e32 v0, vcc, 0x2ec2000, v0
	s_nop 1
	v_addc_co_u32_e32 v1, vcc, 0, v1, vcc
	global_store_dword v[0:1], v4, off
	s_branch .LBB0_764
